# F: v28 + DSA indexer K-chunk loads made unconditional with exact counted vmcnt waits (true 2-chunks-ahead prefetch)
# speedup vs baseline: 1.0150x; 1.0042x over previous
; #define GAS __attribute__((address_space(1)))
; #define MFMA16(a, b, c) __builtin_amdgcn_mfma_f32_16x16x32_bf16((a), (b), (c), 0, 0, 0)
; __device__ __forceinline__ void dsa_token(Frame& F, int b, int t, const bf16* QI, const bf16* KI, const float* WI, const bf16* CKVN, const bf16* QLAT, bf16* OLAT) {
;     ...
;         float sc[64];
;         const bf16x8 qa = *(const GAS bf16x8*)(QI + row * 512 + fr * 32 + 8 * fq);
;         const f32x4 w4 = *(const GAS f32x4*)(WI + row * 16 + 4 * fq);
;         const GAS bf16* kp = (const GAS bf16*)(KI + ((size_t)b * SEQ + fr) * 32 + 8 * fq);
;         bf16x8 kbuf[3][4];
;         float vmax = -INFINITY, vmin = INFINITY;
;     ...
;         const int cmax4 = cmax | 3;
;         DSA_KLOAD(0, 0); DSA_KLOAD(1, 1);
; #pragma unroll
;         for (int c = 0; c < 64; ++c) sc[c] = -INFINITY;
; #pragma unroll
;         for (int g4 = 0; g4 < 16; ++g4) {
;             if (4 * g4 <= cmax) {
; #pragma unroll
;                 for (int c = 4 * g4; c < 4 * g4 + 4; ++c) {
;                     asm volatile("" : "+v"(kp));
;                     if (c + 2 < 64) { if (c + 2 <= cmax4) DSA_KLOAD(c + 2, 2); }
;                     float v[4];
; #pragma unroll
;                     for (int tau = 0; tau < 4; ++tau) {
;                         const f32x4 d = MFMA16(qa, kbuf[c % 3][tau], ((f32x4){0.f, 0.f, 0.f, 0.f}));
;                         typedef int i32x4_ __attribute__((ext_vector_type(4)));
;                         const f32x4 rl = __builtin_bit_cast(f32x4, __builtin_elementwise_max(__builtin_bit_cast(i32x4_, d), ((i32x4_){0, 0, 0, 0})));
;                         v[tau] = fmaf(w4.w, rl[3], fmaf(w4.z, rl[2], fmaf(w4.y, rl[1], w4.x * rl[0])));
;                     }
;                     const SwapPair r0 = swap32p(v[0], v[2]), r1 = swap32p(v[1], v[3]);
;                     const float a0 = __builtin_bit_cast(float, r0.a) + __builtin_bit_cast(float, r0.b), a1 = __builtin_bit_cast(float, r1.a) + __builtin_bit_cast(float, r1.b);
;                     const SwapPair r2 = swap16p(a0, a1);
;                     const float keep = __builtin_bit_cast(float, r2.a) + __builtin_bit_cast(float, r2.b);
;                     const bool cand = 64 * c + lane <= t;
;                     sc[c] = cand ? keep : -INFINITY; vmax = fmaxf(vmax, sc[c]); vmin = fminf(vmin, cand ? keep : INFINITY);
;                     kp += 64 * 32;
.LBB0_945:
	s_sub_i32 s2, 7, s22
	s_and_b64 s[0:1], s[20:21], exec
	s_cselect_b32 s0, s22, s2
	s_lshl_b32 s1, s0, 9
	s_bitcmp0_b32 s0, 0
	s_cselect_b32 s2, s19, s38
	s_add_i32 s2, s2, s1
	s_ashr_i32 s0, s2, 31
	v_readlane_b32 s6, v253, 23
	v_readlane_b32 s7, v253, 24
	s_add_u32 s78, s6, s2
	s_addc_u32 s79, s7, s0
	s_lshl_b64 s[0:1], s[78:79], 10
	v_lshl_add_u64 v[2:3], v[180:181], 0, s[0:1]
	s_lshl_b64 s[0:1], s[78:79], 6
	v_lshl_add_u64 v[4:5], v[182:183], 0, s[0:1]
	global_load_dwordx4 v[6:9], v[2:3], off
	s_nop 0
	global_load_dwordx4 v[2:5], v[4:5], off
	s_nop 0
	global_load_dwordx4 v[22:25], v[184:185], off
	global_load_dwordx4 v[18:21], v[184:185], off offset:1024
	global_load_dwordx4 v[14:17], v[184:185], off offset:2048
	global_load_dwordx4 v[10:13], v[184:185], off offset:3072
	global_load_dwordx4 v[42:45], v[186:187], off
	global_load_dwordx4 v[46:49], v[188:189], off
	global_load_dwordx4 v[50:53], v[190:191], off
	global_load_dwordx4 v[54:57], v[192:193], off
	s_ashr_i32 s18, s2, 6
	s_or_b32 s16, s18, 3
	s_cmp_gt_i32 s18, -1
	s_cselect_b64 s[80:81], -1, 0
	s_and_b64 vcc, exec, s[80:81]
	s_cbranch_vccz .LBB0_951
	s_waitcnt vmcnt(7)
	v_mfma_f32_16x16x32_bf16 v[22:25], v[6:9], v[22:25], 0
	v_mov_b64_e32 v[62:63], v[184:185]
	s_movk_i32 s0, 0x2000
	s_waitcnt vmcnt(6)
	v_mfma_f32_16x16x32_bf16 v[18:21], v[6:9], v[18:21], 0
	v_add_co_u32_e32 v38, vcc, 0x2000, v62
	s_nop 2
	v_max_i32_e32 v22, 0, v22
	s_waitcnt vmcnt(5)
	v_mfma_f32_16x16x32_bf16 v[14:17], v[6:9], v[14:17], 0
	v_max_i32_e32 v23, 0, v23
	v_mul_f32_e32 v22, v2, v22
	v_max_i32_e32 v18, 0, v18
	s_waitcnt vmcnt(4)
	v_mfma_f32_16x16x32_bf16 v[10:13], v[6:9], v[10:13], 0
	v_max_i32_e32 v24, 0, v24
	v_fmac_f32_e32 v22, v3, v23
	v_max_i32_e32 v19, 0, v19
	v_mul_f32_e32 v18, v2, v18
	v_max_i32_e32 v14, 0, v14
	v_max_i32_e32 v0, 0, v25
	v_fmac_f32_e32 v22, v4, v24
	v_max_i32_e32 v20, 0, v20
	v_fmac_f32_e32 v18, v3, v19
	v_max_i32_e32 v15, 0, v15
	v_mul_f32_e32 v14, v2, v14
	v_max_i32_e32 v10, 0, v10
	v_fmac_f32_e32 v22, v5, v0
	v_max_i32_e32 v0, 0, v21
	v_fmac_f32_e32 v18, v4, v20
	v_max_i32_e32 v16, 0, v16
	v_fmac_f32_e32 v14, v3, v15
	v_max_i32_e32 v11, 0, v11
	v_mul_f32_e32 v10, v2, v10
	v_fmac_f32_e32 v18, v5, v0
	v_max_i32_e32 v0, 0, v17
	v_fmac_f32_e32 v14, v4, v16
	v_max_i32_e32 v12, 0, v12
	v_fmac_f32_e32 v10, v3, v11
	v_fmac_f32_e32 v14, v5, v0
	v_max_i32_e32 v0, 0, v13
	v_fmac_f32_e32 v10, v4, v12
	v_addc_co_u32_e32 v39, vcc, 0, v63, vcc
	v_fmac_f32_e32 v10, v5, v0
	global_load_dwordx4 v[26:29], v[38:39], off
	global_load_dwordx4 v[30:33], v[38:39], off offset:1024
	global_load_dwordx4 v[34:37], v[38:39], off offset:2048
	s_nop 0
	global_load_dwordx4 v[38:41], v[38:39], off offset:3072
	v_lshl_add_u64 v[66:67], v[62:63], 0, s[28:29]
	v_permlane32_swap_b32_e32 v22, v14
	v_permlane32_swap_b32_e32 v18, v10
	v_add_f32_e32 v58, v22, v14
	v_add_f32_e32 v60, v18, v10
	s_waitcnt vmcnt(7)
	v_mfma_f32_16x16x32_bf16 v[62:65], v[6:9], v[42:45], 0
	v_add_co_u32_e32 v10, vcc, s0, v66
	v_permlane16_swap_b32_e32 v58, v60
	s_nop 0
	v_addc_co_u32_e32 v11, vcc, 0, v67, vcc
	global_load_dwordx4 v[22:25], v[10:11], off
	global_load_dwordx4 v[18:21], v[10:11], off offset:1024
	global_load_dwordx4 v[14:17], v[10:11], off offset:2048
	s_nop 0
	global_load_dwordx4 v[10:13], v[10:11], off offset:3072
	v_max_i32_e32 v62, 0, v62
	v_max_i32_e32 v0, 0, v65
	v_max_i32_e32 v59, 0, v64
	v_max_i32_e32 v61, 0, v63
	v_mul_f32_e32 v68, v2, v62
	s_waitcnt vmcnt(10)
	v_mfma_f32_16x16x32_bf16 v[62:65], v[6:9], v[46:49], 0
	v_fmac_f32_e32 v68, v3, v61
	v_fmac_f32_e32 v68, v4, v59
	v_fmac_f32_e32 v68, v5, v0
	s_cmp_lt_i32 s16, 4
	s_nop 3
	v_max_i32_e32 v62, 0, v62
	v_max_i32_e32 v0, 0, v65
	v_max_i32_e32 v59, 0, v64
	v_max_i32_e32 v61, 0, v63
	v_mul_f32_e32 v69, v2, v62
	s_waitcnt vmcnt(9)
	v_mfma_f32_16x16x32_bf16 v[62:65], v[6:9], v[50:53], 0
	v_fmac_f32_e32 v69, v3, v61
	v_fmac_f32_e32 v69, v4, v59
	v_fmac_f32_e32 v69, v5, v0
	s_nop 4
	v_max_i32_e32 v62, 0, v62
	v_max_i32_e32 v0, 0, v65
	v_max_i32_e32 v59, 0, v64
	v_max_i32_e32 v61, 0, v63
	v_mul_f32_e32 v70, v2, v62
	s_waitcnt vmcnt(8)
	v_mfma_f32_16x16x32_bf16 v[62:65], v[6:9], v[54:57], 0
	v_fmac_f32_e32 v70, v3, v61
	v_fmac_f32_e32 v70, v4, v59
	v_fmac_f32_e32 v70, v5, v0
	s_nop 1
	v_permlane32_swap_b32_e32 v68, v70
	s_nop 1
	v_max_i32_e32 v62, 0, v62
	v_max_i32_e32 v61, 0, v63
	v_mul_f32_e32 v62, v2, v62
	v_max_i32_e32 v59, 0, v64
	v_fmac_f32_e32 v62, v3, v61
	v_max_i32_e32 v0, 0, v65
	v_fmac_f32_e32 v62, v4, v59
	v_fmac_f32_e32 v62, v5, v0
	v_add_f32_e32 v59, v68, v70
	s_nop 0
	v_permlane32_swap_b32_e32 v69, v62
	v_add_f32_e32 v61, v69, v62
	v_lshl_add_u64 v[62:63], v[66:67], 0, s[28:29]
	s_nop 0
	v_permlane16_swap_b32_e32 v59, v61
	s_nop 0
	v_add_co_u32_e32 v54, vcc, 0x2000, v62
	s_nop 1
	v_addc_co_u32_e32 v55, vcc, 0, v63, vcc
	global_load_dwordx4 v[42:45], v[54:55], off
	global_load_dwordx4 v[46:49], v[54:55], off offset:1024
	global_load_dwordx4 v[50:53], v[54:55], off offset:2048
	s_nop 0
	global_load_dwordx4 v[54:57], v[54:55], off offset:3072
; #define GAS __attribute__((address_space(1)))
; #define MFMA16(a, b, c) __builtin_amdgcn_mfma_f32_16x16x32_bf16((a), (b), (c), 0, 0, 0)
; __device__ __forceinline__ void dsa_token(Frame& F, int b, int t, const bf16* QI, const bf16* KI, const float* WI, const bf16* CKVN, const bf16* QLAT, bf16* OLAT) {
;     ...
;         float sc[64];
;         const bf16x8 qa = *(const GAS bf16x8*)(QI + row * 512 + fr * 32 + 8 * fq);
;         const f32x4 w4 = *(const GAS f32x4*)(WI + row * 16 + 4 * fq);
;         const GAS bf16* kp = (const GAS bf16*)(KI + ((size_t)b * SEQ + fr) * 32 + 8 * fq);
;         bf16x8 kbuf[3][4];
;         float vmax = -INFINITY, vmin = INFINITY;
;     ...
;         const int cmax4 = cmax | 3;
;         DSA_KLOAD(0, 0); DSA_KLOAD(1, 1);
; #pragma unroll
;         for (int c = 0; c < 64; ++c) sc[c] = -INFINITY;
; #pragma unroll
;         for (int g4 = 0; g4 < 16; ++g4) {
;             if (4 * g4 <= cmax) {
; #pragma unroll
;                 for (int c = 4 * g4; c < 4 * g4 + 4; ++c) {
;                     asm volatile("" : "+v"(kp));
;                     if (c + 2 < 64) { if (c + 2 <= cmax4) DSA_KLOAD(c + 2, 2); }
;                     float v[4];
; #pragma unroll
;                     for (int tau = 0; tau < 4; ++tau) {
;                         const f32x4 d = MFMA16(qa, kbuf[c % 3][tau], ((f32x4){0.f, 0.f, 0.f, 0.f}));
;                         typedef int i32x4_ __attribute__((ext_vector_type(4)));
;                         const f32x4 rl = __builtin_bit_cast(f32x4, __builtin_elementwise_max(__builtin_bit_cast(i32x4_, d), ((i32x4_){0, 0, 0, 0})));
;                         v[tau] = fmaf(w4.w, rl[3], fmaf(w4.z, rl[2], fmaf(w4.y, rl[1], w4.x * rl[0])));
;                     }
;                     const SwapPair r0 = swap32p(v[0], v[2]), r1 = swap32p(v[1], v[3]);
;                     const float a0 = __builtin_bit_cast(float, r0.a) + __builtin_bit_cast(float, r0.b), a1 = __builtin_bit_cast(float, r1.a) + __builtin_bit_cast(float, r1.b);
;                     const SwapPair r2 = swap16p(a0, a1);
;                     const float keep = __builtin_bit_cast(float, r2.a) + __builtin_bit_cast(float, r2.b);
;                     const bool cand = 64 * c + lane <= t;
;                     sc[c] = cand ? keep : -INFINITY; vmax = fmaxf(vmax, sc[c]); vmin = fminf(vmin, cand ? keep : INFINITY);
;                     kp += 64 * 32;
.LBB0_948:
	s_waitcnt vmcnt(11)
	v_mfma_f32_16x16x32_bf16 v[64:67], v[6:9], v[26:29], 0
	v_lshl_add_u64 v[62:63], v[62:63], 0, s[28:29]
	s_cmp_lt_i32 s16, 5
	s_nop 5
	v_max_i32_e32 v64, 0, v64
	v_max_i32_e32 v65, 0, v65
	v_mul_f32_e32 v68, v2, v64
	v_max_i32_e32 v66, 0, v66
	v_fmac_f32_e32 v68, v3, v65
	v_max_i32_e32 v0, 0, v67
	v_fmac_f32_e32 v68, v4, v66
	s_waitcnt vmcnt(10)
	v_mfma_f32_16x16x32_bf16 v[64:67], v[6:9], v[30:33], 0
	v_fmac_f32_e32 v68, v5, v0
	s_nop 6
	v_max_i32_e32 v64, 0, v64
	v_max_i32_e32 v65, 0, v65
	v_mul_f32_e32 v69, v2, v64
	v_max_i32_e32 v66, 0, v66
	v_fmac_f32_e32 v69, v3, v65
	v_max_i32_e32 v0, 0, v67
	v_fmac_f32_e32 v69, v4, v66
	s_waitcnt vmcnt(9)
	v_mfma_f32_16x16x32_bf16 v[64:67], v[6:9], v[34:37], 0
	v_fmac_f32_e32 v69, v5, v0
	s_nop 6
	v_max_i32_e32 v64, 0, v64
	v_max_i32_e32 v65, 0, v65
	v_mul_f32_e32 v70, v2, v64
	v_max_i32_e32 v66, 0, v66
	v_fmac_f32_e32 v70, v3, v65
	v_max_i32_e32 v0, 0, v67
	v_fmac_f32_e32 v70, v4, v66
	s_waitcnt vmcnt(8)
	v_mfma_f32_16x16x32_bf16 v[64:67], v[6:9], v[38:41], 0
	v_fmac_f32_e32 v70, v5, v0
	s_nop 1
	v_permlane32_swap_b32_e32 v68, v70
	s_nop 3
	v_max_i32_e32 v64, 0, v64
	v_max_i32_e32 v65, 0, v65
	v_mul_f32_e32 v64, v2, v64
	v_max_i32_e32 v66, 0, v66
	v_fmac_f32_e32 v64, v3, v65
	v_max_i32_e32 v0, 0, v67
	v_fmac_f32_e32 v64, v4, v66
	v_fmac_f32_e32 v64, v5, v0
	v_add_f32_e32 v0, v68, v70
	s_nop 0
	v_permlane32_swap_b32_e32 v69, v64
	v_add_f32_e32 v64, v69, v64
	s_nop 1
	v_permlane16_swap_b32_e32 v0, v64
	s_nop 0
	v_add_co_u32_e32 v38, vcc, 0x2000, v62
	s_nop 1
	v_addc_co_u32_e32 v39, vcc, 0, v63, vcc
	global_load_dwordx4 v[26:29], v[38:39], off
	global_load_dwordx4 v[30:33], v[38:39], off offset:1024
	global_load_dwordx4 v[34:37], v[38:39], off offset:2048
	s_nop 0
	global_load_dwordx4 v[38:41], v[38:39], off offset:3072
.LBB0_950:
	v_pk_add_f32 v[58:59], v[58:59], v[60:61]
	v_cmp_lt_i32_e32 vcc, s2, v176
	v_cmp_lt_i32_e64 s[44:45], s2, v177
	v_add_f32_e32 v0, v0, v64
	v_cndmask_b32_e32 v74, v58, v206, vcc
	v_min_f32_e32 v58, 0x7f800000, v58
	v_cndmask_b32_e64 v72, v59, v206, s[44:45]
	v_cndmask_b32_e32 v58, v58, v207, vcc
	v_cndmask_b32_e64 v59, v59, v207, s[44:45]
	v_min_f32_e32 v66, v58, v59
	s_waitcnt vmcnt(11)
	v_mfma_f32_16x16x32_bf16 v[58:61], v[6:9], v[22:25], 0
	v_cmp_lt_i32_e32 vcc, s2, v209
	s_mov_b32 s0, 0xff800000
	v_max3_f32 v65, v74, s0, v72
	v_cndmask_b32_e32 v71, v0, v206, vcc
	v_cndmask_b32_e32 v0, v0, v207, vcc
	s_nop 2
	v_max_i32_e32 v58, 0, v58
	v_max_i32_e32 v59, 0, v59
	v_mul_f32_e32 v64, v2, v58
	v_max_i32_e32 v60, 0, v60
	v_fmac_f32_e32 v64, v3, v59
	v_max_i32_e32 v61, 0, v61
	v_fmac_f32_e32 v64, v4, v60
	v_fmac_f32_e32 v64, v5, v61
	s_waitcnt vmcnt(10)
	v_mfma_f32_16x16x32_bf16 v[58:61], v[6:9], v[18:21], 0
	v_cmp_lt_i32_e32 vcc, s2, v210
	s_nop 6
	v_max_i32_e32 v58, 0, v58
	v_max_i32_e32 v59, 0, v59
	v_mul_f32_e32 v67, v2, v58
	v_max_i32_e32 v60, 0, v60
	v_fmac_f32_e32 v67, v3, v59
	v_max_i32_e32 v61, 0, v61
	v_fmac_f32_e32 v67, v4, v60
	v_fmac_f32_e32 v67, v5, v61
	s_waitcnt vmcnt(9)
	v_mfma_f32_16x16x32_bf16 v[58:61], v[6:9], v[14:17], 0
	s_nop 7
	v_max_i32_e32 v58, 0, v58
	v_max_i32_e32 v59, 0, v59
	v_mul_f32_e32 v68, v2, v58
	v_max_i32_e32 v60, 0, v60
	v_fmac_f32_e32 v68, v3, v59
	v_max_i32_e32 v61, 0, v61
	v_fmac_f32_e32 v68, v4, v60
	v_fmac_f32_e32 v68, v5, v61
	s_waitcnt vmcnt(8)
	v_mfma_f32_16x16x32_bf16 v[58:61], v[6:9], v[10:13], 0
	s_nop 0
	v_permlane32_swap_b32_e32 v64, v68
	s_nop 5
	v_max_i32_e32 v58, 0, v58
	v_max_i32_e32 v59, 0, v59
	v_mul_f32_e32 v58, v2, v58
	v_max_i32_e32 v60, 0, v60
	v_fmac_f32_e32 v58, v3, v59
	v_max_i32_e32 v61, 0, v61
	v_fmac_f32_e32 v58, v4, v60
	v_fmac_f32_e32 v58, v5, v61
	v_add_f32_e32 v59, v64, v68
	s_nop 0
	v_permlane32_swap_b32_e32 v67, v58
	v_add_f32_e32 v58, v67, v58
	s_nop 1
	v_permlane16_swap_b32_e32 v59, v58
	v_add_f32_e32 v58, v59, v58
	v_cndmask_b32_e32 v73, v58, v206, vcc
	v_cndmask_b32_e32 v58, v58, v207, vcc
	v_max3_f32 v107, v65, v71, v73
	v_min3_f32 v108, v66, v0, v58
	v_lshl_add_u64 v[58:59], v[62:63], 0, s[28:29]
	s_branch .LBB0_952
.LBB0_951:
	s_nop 0
	v_mov_b32_e32 v108, 0x7f800000
	v_mov_b32_e32 v72, 0xff800000
	v_mov_b32_e32 v74, 0xff800000
	v_mov_b64_e32 v[58:59], v[184:185]
	v_mov_b32_e32 v107, 0xff800000
	v_mov_b32_e32 v71, 0xff800000
	v_mov_b32_e32 v73, 0xff800000
.LBB0_952:
	s_cmp_gt_i32 s18, 3
	s_cselect_b64 s[8:9], -1, 0
	s_cmp_lt_i32 s18, 4
	v_mov_b32_e32 v82, 0xff800000
	s_cbranch_scc1 .LBB0_962
	s_cmp_lt_i32 s16, 6
	s_nop 0
	s_nop 0
	v_add_co_u32_e32 v10, vcc, 0x2000, v58
	s_nop 1
	v_addc_co_u32_e32 v11, vcc, 0, v59, vcc
	global_load_dwordx4 v[22:25], v[10:11], off
	global_load_dwordx4 v[18:21], v[10:11], off offset:1024
	global_load_dwordx4 v[14:17], v[10:11], off offset:2048
	s_nop 0
	global_load_dwordx4 v[10:13], v[10:11], off offset:3072
; __device__ __forceinline__ SwapPair swap32p(float x, float y) { unsigned a = __builtin_bit_cast(unsigned, x), b = __builtin_bit_cast(unsigned, y); asm volatile("" : "+v"(a), "+v"(b)); auto r = __builtin_amdgcn_permlane32_swap(a, b, false, false); return SwapPair{r[0], r[1]}; }
; __device__ __forceinline__ SwapPair swap16p(float x, float y) { unsigned a = __builtin_bit_cast(unsigned, x), b = __builtin_bit_cast(unsigned, y); asm volatile("" : "+v"(a), "+v"(b)); auto r = __builtin_amdgcn_permlane16_swap(a, b, false, false); return SwapPair{r[0], r[1]}; }
; #define MFMA16(a, b, c) __builtin_amdgcn_mfma_f32_16x16x32_bf16((a), (b), (c), 0, 0, 0)
; __device__ __forceinline__ void dsa_token(Frame& F, int b, int t, const bf16* QI, const bf16* KI, const float* WI, const bf16* CKVN, const bf16* QLAT, bf16* OLAT) {
;     ...
;         for (int g4 = 0; g4 < 16; ++g4) {
;             if (4 * g4 <= cmax) {
; #pragma unroll
;                 for (int c = 4 * g4; c < 4 * g4 + 4; ++c) {
;                     asm volatile("" : "+v"(kp));
;                     if (c + 2 < 64) { if (c + 2 <= cmax4) DSA_KLOAD(c + 2, 2); }
;                     float v[4];
; #pragma unroll
;                     for (int tau = 0; tau < 4; ++tau) {
;                         const f32x4 d = MFMA16(qa, kbuf[c % 3][tau], ((f32x4){0.f, 0.f, 0.f, 0.f}));
;                         typedef int i32x4_ __attribute__((ext_vector_type(4)));
;                         const f32x4 rl = __builtin_bit_cast(f32x4, __builtin_elementwise_max(__builtin_bit_cast(i32x4_, d), ((i32x4_){0, 0, 0, 0})));
;                         v[tau] = fmaf(w4.w, rl[3], fmaf(w4.z, rl[2], fmaf(w4.y, rl[1], w4.x * rl[0])));
;                     }
;                     const SwapPair r0 = swap32p(v[0], v[2]), r1 = swap32p(v[1], v[3]);
;                     const float a0 = __builtin_bit_cast(float, r0.a) + __builtin_bit_cast(float, r0.b), a1 = __builtin_bit_cast(float, r1.a) + __builtin_bit_cast(float, r1.b);
;                     const SwapPair r2 = swap16p(a0, a1);
;                     const float keep = __builtin_bit_cast(float, r2.a) + __builtin_bit_cast(float, r2.b);
;                     const bool cand = 64 * c + lane <= t;
;                     sc[c] = cand ? keep : -INFINITY; vmax = fmaxf(vmax, sc[c]); vmin = fminf(vmin, cand ? keep : INFINITY);
;                     kp += 64 * 32;
.LBB0_955:
	s_waitcnt vmcnt(11)
	v_mfma_f32_16x16x32_bf16 v[60:63], v[6:9], v[42:45], 0
	v_lshl_add_u64 v[58:59], v[58:59], 0, s[28:29]
	s_cmp_lt_i32 s16, 7
	s_nop 5
	v_max_i32_e32 v60, 0, v60
	v_max_i32_e32 v61, 0, v61
	v_mul_f32_e32 v64, v2, v60
	v_max_i32_e32 v62, 0, v62
	v_fmac_f32_e32 v64, v3, v61
	v_max_i32_e32 v0, 0, v63
	v_fmac_f32_e32 v64, v4, v62
	s_waitcnt vmcnt(10)
	v_mfma_f32_16x16x32_bf16 v[60:63], v[6:9], v[46:49], 0
	v_fmac_f32_e32 v64, v5, v0
	s_nop 6
	v_max_i32_e32 v60, 0, v60
	v_max_i32_e32 v61, 0, v61
	v_mul_f32_e32 v65, v2, v60
	v_max_i32_e32 v62, 0, v62
	v_fmac_f32_e32 v65, v3, v61
	v_max_i32_e32 v0, 0, v63
	v_fmac_f32_e32 v65, v4, v62
	s_waitcnt vmcnt(9)
	v_mfma_f32_16x16x32_bf16 v[60:63], v[6:9], v[50:53], 0
	v_fmac_f32_e32 v65, v5, v0
	s_nop 6
	v_max_i32_e32 v60, 0, v60
	v_max_i32_e32 v61, 0, v61
	v_mul_f32_e32 v66, v2, v60
	v_max_i32_e32 v62, 0, v62
	v_fmac_f32_e32 v66, v3, v61
	v_max_i32_e32 v0, 0, v63
	v_fmac_f32_e32 v66, v4, v62
	s_waitcnt vmcnt(8)
	v_mfma_f32_16x16x32_bf16 v[60:63], v[6:9], v[54:57], 0
	v_fmac_f32_e32 v66, v5, v0
	s_nop 1
	v_permlane32_swap_b32_e32 v64, v66
	s_nop 3
	v_max_i32_e32 v60, 0, v60
	v_max_i32_e32 v61, 0, v61
	v_mul_f32_e32 v60, v2, v60
	v_max_i32_e32 v62, 0, v62
	v_fmac_f32_e32 v60, v3, v61
	v_max_i32_e32 v0, 0, v63
	v_fmac_f32_e32 v60, v4, v62
	v_fmac_f32_e32 v60, v5, v0
	v_add_f32_e32 v0, v64, v66
	s_nop 0
	v_permlane32_swap_b32_e32 v65, v60
	v_add_f32_e32 v60, v65, v60
	s_nop 1
	v_permlane16_swap_b32_e32 v0, v60
	s_nop 0
	v_add_co_u32_e32 v54, vcc, 0x2000, v58
	s_nop 1
	v_addc_co_u32_e32 v55, vcc, 0, v59, vcc
	global_load_dwordx4 v[42:45], v[54:55], off
	global_load_dwordx4 v[46:49], v[54:55], off offset:1024
	global_load_dwordx4 v[50:53], v[54:55], off offset:2048
	s_nop 0
	global_load_dwordx4 v[54:57], v[54:55], off offset:3072
.LBB0_957:
	s_waitcnt vmcnt(11)
	v_mfma_f32_16x16x32_bf16 v[62:65], v[6:9], v[26:29], 0
	v_lshl_add_u64 v[58:59], v[58:59], 0, s[28:29]
	s_cmp_lt_i32 s16, 8
	s_nop 5
	v_max_i32_e32 v62, 0, v62
	v_max_i32_e32 v63, 0, v63
	v_mul_f32_e32 v66, v2, v62
	v_max_i32_e32 v64, 0, v64
	v_fmac_f32_e32 v66, v3, v63
	v_max_i32_e32 v61, 0, v65
	v_fmac_f32_e32 v66, v4, v64
	s_waitcnt vmcnt(10)
	v_mfma_f32_16x16x32_bf16 v[62:65], v[6:9], v[30:33], 0
	v_fmac_f32_e32 v66, v5, v61
	s_nop 6
	v_max_i32_e32 v62, 0, v62
	v_max_i32_e32 v63, 0, v63
	v_mul_f32_e32 v67, v2, v62
	v_max_i32_e32 v64, 0, v64
	v_fmac_f32_e32 v67, v3, v63
	v_max_i32_e32 v61, 0, v65
	v_fmac_f32_e32 v67, v4, v64
	s_waitcnt vmcnt(9)
	v_mfma_f32_16x16x32_bf16 v[62:65], v[6:9], v[34:37], 0
	v_fmac_f32_e32 v67, v5, v61
	s_nop 6
	v_max_i32_e32 v62, 0, v62
	v_max_i32_e32 v63, 0, v63
	v_mul_f32_e32 v68, v2, v62
	v_max_i32_e32 v64, 0, v64
	v_fmac_f32_e32 v68, v3, v63
	v_max_i32_e32 v61, 0, v65
	v_fmac_f32_e32 v68, v4, v64
	s_waitcnt vmcnt(8)
	v_mfma_f32_16x16x32_bf16 v[62:65], v[6:9], v[38:41], 0
	v_fmac_f32_e32 v68, v5, v61
	s_nop 1
	v_permlane32_swap_b32_e32 v66, v68
	s_nop 3
	v_max_i32_e32 v62, 0, v62
	v_max_i32_e32 v63, 0, v63
	v_mul_f32_e32 v62, v2, v62
	v_max_i32_e32 v64, 0, v64
	v_fmac_f32_e32 v62, v3, v63
	v_max_i32_e32 v61, 0, v65
	v_fmac_f32_e32 v62, v4, v64
	v_fmac_f32_e32 v62, v5, v61
	v_add_f32_e32 v61, v66, v68
	s_nop 0
	v_permlane32_swap_b32_e32 v67, v62
	v_add_f32_e32 v62, v67, v62
	s_nop 1
	v_permlane16_swap_b32_e32 v61, v62
	s_nop 0
	v_add_co_u32_e32 v38, vcc, 0x2000, v58
	s_nop 1
	v_addc_co_u32_e32 v39, vcc, 0, v59, vcc
	global_load_dwordx4 v[26:29], v[38:39], off
	global_load_dwordx4 v[30:33], v[38:39], off offset:1024
	global_load_dwordx4 v[34:37], v[38:39], off offset:2048
	s_nop 0
	global_load_dwordx4 v[38:41], v[38:39], off offset:3072
; __device__ __forceinline__ SwapPair swap32p(float x, float y) { unsigned a = __builtin_bit_cast(unsigned, x), b = __builtin_bit_cast(unsigned, y); asm volatile("" : "+v"(a), "+v"(b)); auto r = __builtin_amdgcn_permlane32_swap(a, b, false, false); return SwapPair{r[0], r[1]}; }
; __device__ __forceinline__ SwapPair swap16p(float x, float y) { unsigned a = __builtin_bit_cast(unsigned, x), b = __builtin_bit_cast(unsigned, y); asm volatile("" : "+v"(a), "+v"(b)); auto r = __builtin_amdgcn_permlane16_swap(a, b, false, false); return SwapPair{r[0], r[1]}; }
; #define MFMA16(a, b, c) __builtin_amdgcn_mfma_f32_16x16x32_bf16((a), (b), (c), 0, 0, 0)
; __device__ __forceinline__ void dsa_token(Frame& F, int b, int t, const bf16* QI, const bf16* KI, const float* WI, const bf16* CKVN, const bf16* QLAT, bf16* OLAT) {
;     ...
;         for (int g4 = 0; g4 < 16; ++g4) {
;             if (4 * g4 <= cmax) {
; #pragma unroll
;                 for (int c = 4 * g4; c < 4 * g4 + 4; ++c) {
;                     asm volatile("" : "+v"(kp));
;                     if (c + 2 < 64) { if (c + 2 <= cmax4) DSA_KLOAD(c + 2, 2); }
;                     float v[4];
; #pragma unroll
;                     for (int tau = 0; tau < 4; ++tau) {
;                         const f32x4 d = MFMA16(qa, kbuf[c % 3][tau], ((f32x4){0.f, 0.f, 0.f, 0.f}));
;                         typedef int i32x4_ __attribute__((ext_vector_type(4)));
;                         const f32x4 rl = __builtin_bit_cast(f32x4, __builtin_elementwise_max(__builtin_bit_cast(i32x4_, d), ((i32x4_){0, 0, 0, 0})));
;                         v[tau] = fmaf(w4.w, rl[3], fmaf(w4.z, rl[2], fmaf(w4.y, rl[1], w4.x * rl[0])));
;                     }
;                     const SwapPair r0 = swap32p(v[0], v[2]), r1 = swap32p(v[1], v[3]);
;                     const float a0 = __builtin_bit_cast(float, r0.a) + __builtin_bit_cast(float, r0.b), a1 = __builtin_bit_cast(float, r1.a) + __builtin_bit_cast(float, r1.b);
;                     const SwapPair r2 = swap16p(a0, a1);
;                     const float keep = __builtin_bit_cast(float, r2.a) + __builtin_bit_cast(float, r2.b);
;                     const bool cand = 64 * c + lane <= t;
;                     sc[c] = cand ? keep : -INFINITY; vmax = fmaxf(vmax, sc[c]); vmin = fminf(vmin, cand ? keep : INFINITY);
;                     kp += 64 * 32;
.LBB0_959:
	s_waitcnt vmcnt(11)
	v_mfma_f32_16x16x32_bf16 v[64:67], v[6:9], v[22:25], 0
	v_lshl_add_u64 v[58:59], v[58:59], 0, s[28:29]
	s_cmp_lt_i32 s16, 9
	s_nop 5
	v_max_i32_e32 v64, 0, v64
	v_max_i32_e32 v65, 0, v65
	v_mul_f32_e32 v68, v2, v64
	v_max_i32_e32 v66, 0, v66
	v_fmac_f32_e32 v68, v3, v65
	v_max_i32_e32 v63, 0, v67
	v_fmac_f32_e32 v68, v4, v66
	s_waitcnt vmcnt(10)
	v_mfma_f32_16x16x32_bf16 v[64:67], v[6:9], v[18:21], 0
	v_fmac_f32_e32 v68, v5, v63
	s_nop 6
	v_max_i32_e32 v64, 0, v64
	v_max_i32_e32 v65, 0, v65
	v_mul_f32_e32 v69, v2, v64
	v_max_i32_e32 v66, 0, v66
	v_fmac_f32_e32 v69, v3, v65
	v_max_i32_e32 v63, 0, v67
	v_fmac_f32_e32 v69, v4, v66
	s_waitcnt vmcnt(9)
	v_mfma_f32_16x16x32_bf16 v[64:67], v[6:9], v[14:17], 0
	v_fmac_f32_e32 v69, v5, v63
	s_nop 6
	v_max_i32_e32 v64, 0, v64
	v_max_i32_e32 v65, 0, v65
	v_mul_f32_e32 v70, v2, v64
	v_max_i32_e32 v66, 0, v66
	v_fmac_f32_e32 v70, v3, v65
	v_max_i32_e32 v63, 0, v67
	v_fmac_f32_e32 v70, v4, v66
	s_waitcnt vmcnt(8)
	v_mfma_f32_16x16x32_bf16 v[64:67], v[6:9], v[10:13], 0
	v_fmac_f32_e32 v70, v5, v63
	s_nop 1
	v_permlane32_swap_b32_e32 v68, v70
	s_nop 3
	v_max_i32_e32 v64, 0, v64
	v_max_i32_e32 v65, 0, v65
	v_mul_f32_e32 v64, v2, v64
	v_max_i32_e32 v66, 0, v66
	v_fmac_f32_e32 v64, v3, v65
	v_max_i32_e32 v63, 0, v67
	v_fmac_f32_e32 v64, v4, v66
	v_fmac_f32_e32 v64, v5, v63
	v_add_f32_e32 v63, v68, v70
	s_nop 0
	v_permlane32_swap_b32_e32 v69, v64
	v_add_f32_e32 v64, v69, v64
	s_nop 1
	v_permlane16_swap_b32_e32 v63, v64
	s_nop 0
	v_add_co_u32_e32 v10, vcc, 0x2000, v58
	s_nop 1
	v_addc_co_u32_e32 v11, vcc, 0, v59, vcc
	global_load_dwordx4 v[22:25], v[10:11], off
	global_load_dwordx4 v[18:21], v[10:11], off offset:1024
	global_load_dwordx4 v[14:17], v[10:11], off offset:2048
	s_nop 0
	global_load_dwordx4 v[10:13], v[10:11], off offset:3072
.LBB0_961:
	v_add_f32_e32 v0, v0, v60
	v_or_b32_e32 v60, 0x100, v176
	v_cmp_lt_i32_e32 vcc, s2, v60
	v_add_f32_e32 v60, v61, v62
	v_or_b32_e32 v61, 0x140, v176
	v_cndmask_b32_e32 v82, v0, v206, vcc
	v_cndmask_b32_e32 v0, v0, v207, vcc
	v_cmp_lt_i32_e32 vcc, s2, v61
	v_or_b32_e32 v61, 0x180, v176
	v_lshl_add_u64 v[58:59], v[58:59], 0, s[28:29]
	v_cndmask_b32_e32 v80, v60, v206, vcc
	v_cndmask_b32_e32 v60, v60, v207, vcc
	v_min3_f32 v0, v108, v0, v60
	v_add_f32_e32 v60, v63, v64
	v_cmp_lt_i32_e32 vcc, s2, v61
	v_max3_f32 v65, v107, v82, v80
	s_nop 0
	v_cndmask_b32_e32 v78, v60, v206, vcc
	v_cndmask_b32_e32 v64, v60, v207, vcc
	s_waitcnt vmcnt(11)
	v_mfma_f32_16x16x32_bf16 v[60:63], v[6:9], v[42:45], 0
	s_nop 7
	v_max_i32_e32 v60, 0, v60
	v_max_i32_e32 v61, 0, v61
	v_mul_f32_e32 v66, v2, v60
	v_max_i32_e32 v62, 0, v62
	v_fmac_f32_e32 v66, v3, v61
	v_max_i32_e32 v63, 0, v63
	v_fmac_f32_e32 v66, v4, v62
	v_fmac_f32_e32 v66, v5, v63
	s_waitcnt vmcnt(10)
	v_mfma_f32_16x16x32_bf16 v[60:63], v[6:9], v[46:49], 0
	s_nop 7
	v_max_i32_e32 v60, 0, v60
	v_max_i32_e32 v61, 0, v61
	v_mul_f32_e32 v67, v2, v60
	v_max_i32_e32 v62, 0, v62
	v_fmac_f32_e32 v67, v3, v61
	v_max_i32_e32 v63, 0, v63
	v_fmac_f32_e32 v67, v4, v62
	v_fmac_f32_e32 v67, v5, v63
	s_waitcnt vmcnt(9)
	v_mfma_f32_16x16x32_bf16 v[60:63], v[6:9], v[50:53], 0
	s_nop 7
	v_max_i32_e32 v60, 0, v60
	v_max_i32_e32 v61, 0, v61
	v_mul_f32_e32 v68, v2, v60
	v_max_i32_e32 v62, 0, v62
	v_fmac_f32_e32 v68, v3, v61
	v_max_i32_e32 v63, 0, v63
	v_fmac_f32_e32 v68, v4, v62
	v_fmac_f32_e32 v68, v5, v63
	s_waitcnt vmcnt(8)
	v_mfma_f32_16x16x32_bf16 v[60:63], v[6:9], v[54:57], 0
	s_nop 0
	v_permlane32_swap_b32_e32 v66, v68
	s_nop 5
	v_max_i32_e32 v60, 0, v60
	v_max_i32_e32 v61, 0, v61
	v_mul_f32_e32 v60, v2, v60
	v_max_i32_e32 v62, 0, v62
	v_fmac_f32_e32 v60, v3, v61
	v_max_i32_e32 v63, 0, v63
	v_fmac_f32_e32 v60, v4, v62
	v_fmac_f32_e32 v60, v5, v63
	v_add_f32_e32 v61, v66, v68
	s_nop 0
	v_permlane32_swap_b32_e32 v67, v60
	v_add_f32_e32 v60, v67, v60
	s_nop 1
	v_permlane16_swap_b32_e32 v61, v60
	v_add_f32_e32 v60, v61, v60
	v_or_b32_e32 v61, 0x1c0, v176
	v_cmp_lt_i32_e32 vcc, s2, v61
	s_nop 1
	v_cndmask_b32_e32 v81, v60, v206, vcc
	v_cndmask_b32_e32 v60, v60, v207, vcc
	v_max3_f32 v107, v65, v78, v81
	v_min3_f32 v108, v0, v64, v60
	s_branch .LBB0_963

; __device__ __forceinline__ SwapPair swap32p(float x, float y) { unsigned a = __builtin_bit_cast(unsigned, x), b = __builtin_bit_cast(unsigned, y); asm volatile("" : "+v"(a), "+v"(b)); auto r = __builtin_amdgcn_permlane32_swap(a, b, false, false); return SwapPair{r[0], r[1]}; }
; __device__ __forceinline__ SwapPair swap16p(float x, float y) { unsigned a = __builtin_bit_cast(unsigned, x), b = __builtin_bit_cast(unsigned, y); asm volatile("" : "+v"(a), "+v"(b)); auto r = __builtin_amdgcn_permlane16_swap(a, b, false, false); return SwapPair{r[0], r[1]}; }
; #define MFMA16(a, b, c) __builtin_amdgcn_mfma_f32_16x16x32_bf16((a), (b), (c), 0, 0, 0)
; __device__ __forceinline__ void dsa_token(Frame& F, int b, int t, const bf16* QI, const bf16* KI, const float* WI, const bf16* CKVN, const bf16* QLAT, bf16* OLAT) {
;     ...
;         for (int g4 = 0; g4 < 16; ++g4) {
;             if (4 * g4 <= cmax) {
; #pragma unroll
;                 for (int c = 4 * g4; c < 4 * g4 + 4; ++c) {
;                     asm volatile("" : "+v"(kp));
;                     if (c + 2 < 64) { if (c + 2 <= cmax4) DSA_KLOAD(c + 2, 2); }
;                     float v[4];
; #pragma unroll
;                     for (int tau = 0; tau < 4; ++tau) {
;                         const f32x4 d = MFMA16(qa, kbuf[c % 3][tau], ((f32x4){0.f, 0.f, 0.f, 0.f}));
;                         typedef int i32x4_ __attribute__((ext_vector_type(4)));
;                         const f32x4 rl = __builtin_bit_cast(f32x4, __builtin_elementwise_max(__builtin_bit_cast(i32x4_, d), ((i32x4_){0, 0, 0, 0})));
;                         v[tau] = fmaf(w4.w, rl[3], fmaf(w4.z, rl[2], fmaf(w4.y, rl[1], w4.x * rl[0])));
;                     }
;                     const SwapPair r0 = swap32p(v[0], v[2]), r1 = swap32p(v[1], v[3]);
;                     const float a0 = __builtin_bit_cast(float, r0.a) + __builtin_bit_cast(float, r0.b), a1 = __builtin_bit_cast(float, r1.a) + __builtin_bit_cast(float, r1.b);
;                     const SwapPair r2 = swap16p(a0, a1);
;                     const float keep = __builtin_bit_cast(float, r2.a) + __builtin_bit_cast(float, r2.b);
;                     const bool cand = 64 * c + lane <= t;
;                     sc[c] = cand ? keep : -INFINITY; vmax = fmaxf(vmax, sc[c]); vmin = fminf(vmin, cand ? keep : INFINITY);
;                     kp += 64 * 32;
.LBB0_963:
	s_cmp_gt_i32 s18, 7
	s_cselect_b64 s[14:15], -1, 0
	s_cmp_lt_i32 s18, 8
	v_mov_b32_e32 v86, 0xff800000
	s_cbranch_scc1 .LBB0_973
	s_cmp_lt_i32 s16, 10
	s_nop 0
	s_nop 0
	v_add_co_u32_e32 v54, vcc, 0x2000, v58
	s_nop 1
	v_addc_co_u32_e32 v55, vcc, 0, v59, vcc
	global_load_dwordx4 v[42:45], v[54:55], off
	global_load_dwordx4 v[46:49], v[54:55], off offset:1024
	global_load_dwordx4 v[50:53], v[54:55], off offset:2048
	s_nop 0
	global_load_dwordx4 v[54:57], v[54:55], off offset:3072
.LBB0_966:
	s_waitcnt vmcnt(11)
	v_mfma_f32_16x16x32_bf16 v[60:63], v[6:9], v[26:29], 0
	v_lshl_add_u64 v[58:59], v[58:59], 0, s[28:29]
	s_cmp_lt_i32 s16, 11
	s_nop 5
	v_max_i32_e32 v60, 0, v60
	v_max_i32_e32 v61, 0, v61
	s_nop 0
	v_mul_f32_e32 v64, v2, v60
	v_max_i32_e32 v62, 0, v62
	v_fmac_f32_e32 v64, v3, v61
	v_max_i32_e32 v0, 0, v63
	v_fmac_f32_e32 v64, v4, v62
	s_waitcnt vmcnt(10)
	v_mfma_f32_16x16x32_bf16 v[60:63], v[6:9], v[30:33], 0
	v_fmac_f32_e32 v64, v5, v0
	s_nop 6
	v_max_i32_e32 v60, 0, v60
	v_max_i32_e32 v61, 0, v61
	v_mul_f32_e32 v65, v2, v60
	v_max_i32_e32 v62, 0, v62
	v_fmac_f32_e32 v65, v3, v61
	v_max_i32_e32 v0, 0, v63
	v_fmac_f32_e32 v65, v4, v62
	s_waitcnt vmcnt(9)
	v_mfma_f32_16x16x32_bf16 v[60:63], v[6:9], v[34:37], 0
	v_fmac_f32_e32 v65, v5, v0
	s_nop 6
	v_max_i32_e32 v60, 0, v60
	v_max_i32_e32 v61, 0, v61
	v_mul_f32_e32 v66, v2, v60
	v_max_i32_e32 v62, 0, v62
	v_fmac_f32_e32 v66, v3, v61
	v_max_i32_e32 v0, 0, v63
	v_fmac_f32_e32 v66, v4, v62
	s_waitcnt vmcnt(8)
	v_mfma_f32_16x16x32_bf16 v[60:63], v[6:9], v[38:41], 0
	v_fmac_f32_e32 v66, v5, v0
	s_nop 1
	v_permlane32_swap_b32_e32 v64, v66
	s_nop 3
	v_max_i32_e32 v60, 0, v60
	v_max_i32_e32 v61, 0, v61
	v_mul_f32_e32 v60, v2, v60
	v_max_i32_e32 v62, 0, v62
	v_fmac_f32_e32 v60, v3, v61
	v_max_i32_e32 v0, 0, v63
	v_fmac_f32_e32 v60, v4, v62
	v_fmac_f32_e32 v60, v5, v0
	v_add_f32_e32 v0, v64, v66
	s_nop 0
	v_permlane32_swap_b32_e32 v65, v60
	v_add_f32_e32 v60, v65, v60
	s_nop 1
	v_permlane16_swap_b32_e32 v0, v60
	s_nop 0
	v_add_co_u32_e32 v38, vcc, 0x2000, v58
	s_nop 1
	v_addc_co_u32_e32 v39, vcc, 0, v59, vcc
	global_load_dwordx4 v[26:29], v[38:39], off
	global_load_dwordx4 v[30:33], v[38:39], off offset:1024
	global_load_dwordx4 v[34:37], v[38:39], off offset:2048
	s_nop 0
	global_load_dwordx4 v[38:41], v[38:39], off offset:3072
.LBB0_968:
	s_waitcnt vmcnt(11)
	v_mfma_f32_16x16x32_bf16 v[62:65], v[6:9], v[22:25], 0
	v_lshl_add_u64 v[58:59], v[58:59], 0, s[28:29]
	s_cmp_lt_i32 s16, 12
	s_nop 5
	v_max_i32_e32 v62, 0, v62
	v_max_i32_e32 v63, 0, v63
	v_mul_f32_e32 v66, v2, v62
	v_max_i32_e32 v64, 0, v64
	v_fmac_f32_e32 v66, v3, v63
	v_max_i32_e32 v61, 0, v65
	v_fmac_f32_e32 v66, v4, v64
	s_waitcnt vmcnt(10)
	v_mfma_f32_16x16x32_bf16 v[62:65], v[6:9], v[18:21], 0
	v_fmac_f32_e32 v66, v5, v61
	s_nop 6
	v_max_i32_e32 v62, 0, v62
	v_max_i32_e32 v63, 0, v63
	v_mul_f32_e32 v67, v2, v62
	v_max_i32_e32 v64, 0, v64
	v_fmac_f32_e32 v67, v3, v63
	v_max_i32_e32 v61, 0, v65
	v_fmac_f32_e32 v67, v4, v64
	s_waitcnt vmcnt(9)
	v_mfma_f32_16x16x32_bf16 v[62:65], v[6:9], v[14:17], 0
	v_fmac_f32_e32 v67, v5, v61
	s_nop 6
	v_max_i32_e32 v62, 0, v62
	v_max_i32_e32 v63, 0, v63
	v_mul_f32_e32 v68, v2, v62
	v_max_i32_e32 v64, 0, v64
	v_fmac_f32_e32 v68, v3, v63
	v_max_i32_e32 v61, 0, v65
	v_fmac_f32_e32 v68, v4, v64
	s_waitcnt vmcnt(8)
	v_mfma_f32_16x16x32_bf16 v[62:65], v[6:9], v[10:13], 0
	v_fmac_f32_e32 v68, v5, v61
	s_nop 1
	v_permlane32_swap_b32_e32 v66, v68
	s_nop 3
	v_max_i32_e32 v62, 0, v62
	v_max_i32_e32 v63, 0, v63
	v_mul_f32_e32 v62, v2, v62
	v_max_i32_e32 v64, 0, v64
	v_fmac_f32_e32 v62, v3, v63
	v_max_i32_e32 v61, 0, v65
	v_fmac_f32_e32 v62, v4, v64
	v_fmac_f32_e32 v62, v5, v61
	v_add_f32_e32 v61, v66, v68
	s_nop 0
	v_permlane32_swap_b32_e32 v67, v62
	v_add_f32_e32 v62, v67, v62
	s_nop 1
	v_permlane16_swap_b32_e32 v61, v62
	s_nop 0
	v_add_co_u32_e32 v10, vcc, 0x2000, v58
	s_nop 1
	v_addc_co_u32_e32 v11, vcc, 0, v59, vcc
	global_load_dwordx4 v[22:25], v[10:11], off
	global_load_dwordx4 v[18:21], v[10:11], off offset:1024
	global_load_dwordx4 v[14:17], v[10:11], off offset:2048
	s_nop 0
	global_load_dwordx4 v[10:13], v[10:11], off offset:3072
; __device__ __forceinline__ SwapPair swap32p(float x, float y) { unsigned a = __builtin_bit_cast(unsigned, x), b = __builtin_bit_cast(unsigned, y); asm volatile("" : "+v"(a), "+v"(b)); auto r = __builtin_amdgcn_permlane32_swap(a, b, false, false); return SwapPair{r[0], r[1]}; }
; __device__ __forceinline__ SwapPair swap16p(float x, float y) { unsigned a = __builtin_bit_cast(unsigned, x), b = __builtin_bit_cast(unsigned, y); asm volatile("" : "+v"(a), "+v"(b)); auto r = __builtin_amdgcn_permlane16_swap(a, b, false, false); return SwapPair{r[0], r[1]}; }
; #define MFMA16(a, b, c) __builtin_amdgcn_mfma_f32_16x16x32_bf16((a), (b), (c), 0, 0, 0)
; __device__ __forceinline__ void dsa_token(Frame& F, int b, int t, const bf16* QI, const bf16* KI, const float* WI, const bf16* CKVN, const bf16* QLAT, bf16* OLAT) {
;     ...
;         for (int g4 = 0; g4 < 16; ++g4) {
;             if (4 * g4 <= cmax) {
; #pragma unroll
;                 for (int c = 4 * g4; c < 4 * g4 + 4; ++c) {
;                     asm volatile("" : "+v"(kp));
;                     if (c + 2 < 64) { if (c + 2 <= cmax4) DSA_KLOAD(c + 2, 2); }
;                     float v[4];
; #pragma unroll
;                     for (int tau = 0; tau < 4; ++tau) {
;                         const f32x4 d = MFMA16(qa, kbuf[c % 3][tau], ((f32x4){0.f, 0.f, 0.f, 0.f}));
;                         typedef int i32x4_ __attribute__((ext_vector_type(4)));
;                         const f32x4 rl = __builtin_bit_cast(f32x4, __builtin_elementwise_max(__builtin_bit_cast(i32x4_, d), ((i32x4_){0, 0, 0, 0})));
;                         v[tau] = fmaf(w4.w, rl[3], fmaf(w4.z, rl[2], fmaf(w4.y, rl[1], w4.x * rl[0])));
;                     }
;                     const SwapPair r0 = swap32p(v[0], v[2]), r1 = swap32p(v[1], v[3]);
;                     const float a0 = __builtin_bit_cast(float, r0.a) + __builtin_bit_cast(float, r0.b), a1 = __builtin_bit_cast(float, r1.a) + __builtin_bit_cast(float, r1.b);
;                     const SwapPair r2 = swap16p(a0, a1);
;                     const float keep = __builtin_bit_cast(float, r2.a) + __builtin_bit_cast(float, r2.b);
;                     const bool cand = 64 * c + lane <= t;
;                     sc[c] = cand ? keep : -INFINITY; vmax = fmaxf(vmax, sc[c]); vmin = fminf(vmin, cand ? keep : INFINITY);
;                     kp += 64 * 32;
.LBB0_970:
	s_waitcnt vmcnt(11)
	v_mfma_f32_16x16x32_bf16 v[64:67], v[6:9], v[42:45], 0
	v_lshl_add_u64 v[58:59], v[58:59], 0, s[28:29]
	s_cmp_lt_i32 s16, 13
	s_nop 5
	v_max_i32_e32 v64, 0, v64
	v_max_i32_e32 v65, 0, v65
	v_mul_f32_e32 v68, v2, v64
	v_max_i32_e32 v66, 0, v66
	v_fmac_f32_e32 v68, v3, v65
	v_max_i32_e32 v63, 0, v67
	v_fmac_f32_e32 v68, v4, v66
	s_waitcnt vmcnt(10)
	v_mfma_f32_16x16x32_bf16 v[64:67], v[6:9], v[46:49], 0
	v_fmac_f32_e32 v68, v5, v63
	s_nop 6
	v_max_i32_e32 v64, 0, v64
	v_max_i32_e32 v65, 0, v65
	v_mul_f32_e32 v69, v2, v64
	v_max_i32_e32 v66, 0, v66
	v_fmac_f32_e32 v69, v3, v65
	v_max_i32_e32 v63, 0, v67
	v_fmac_f32_e32 v69, v4, v66
	s_waitcnt vmcnt(9)
	v_mfma_f32_16x16x32_bf16 v[64:67], v[6:9], v[50:53], 0
	v_fmac_f32_e32 v69, v5, v63
	s_nop 6
	v_max_i32_e32 v64, 0, v64
	v_max_i32_e32 v65, 0, v65
	v_mul_f32_e32 v70, v2, v64
	v_max_i32_e32 v66, 0, v66
	v_fmac_f32_e32 v70, v3, v65
	v_max_i32_e32 v63, 0, v67
	v_fmac_f32_e32 v70, v4, v66
	s_waitcnt vmcnt(8)
	v_mfma_f32_16x16x32_bf16 v[64:67], v[6:9], v[54:57], 0
	v_fmac_f32_e32 v70, v5, v63
	s_nop 1
	v_permlane32_swap_b32_e32 v68, v70
	s_nop 3
	v_max_i32_e32 v64, 0, v64
	v_max_i32_e32 v65, 0, v65
	v_mul_f32_e32 v64, v2, v64
	v_max_i32_e32 v66, 0, v66
	v_fmac_f32_e32 v64, v3, v65
	v_max_i32_e32 v63, 0, v67
	v_fmac_f32_e32 v64, v4, v66
	v_fmac_f32_e32 v64, v5, v63
	v_add_f32_e32 v63, v68, v70
	s_nop 0
	v_permlane32_swap_b32_e32 v69, v64
	v_add_f32_e32 v64, v69, v64
	s_nop 1
	v_permlane16_swap_b32_e32 v63, v64
	s_nop 0
	v_add_co_u32_e32 v54, vcc, 0x2000, v58
	s_nop 1
	v_addc_co_u32_e32 v55, vcc, 0, v59, vcc
	global_load_dwordx4 v[42:45], v[54:55], off
	global_load_dwordx4 v[46:49], v[54:55], off offset:1024
	global_load_dwordx4 v[50:53], v[54:55], off offset:2048
	s_nop 0
	global_load_dwordx4 v[54:57], v[54:55], off offset:3072
.LBB0_972:
	v_add_f32_e32 v0, v0, v60
	v_or_b32_e32 v60, 0x200, v176
	v_cmp_lt_i32_e32 vcc, s2, v60
	v_add_f32_e32 v60, v61, v62
	v_or_b32_e32 v61, 0x240, v176
	v_cndmask_b32_e32 v86, v0, v206, vcc
	v_cndmask_b32_e32 v0, v0, v207, vcc
	v_cmp_lt_i32_e32 vcc, s2, v61
	v_or_b32_e32 v61, 0x280, v176
	v_lshl_add_u64 v[58:59], v[58:59], 0, s[28:29]
	v_cndmask_b32_e32 v84, v60, v206, vcc
	v_cndmask_b32_e32 v60, v60, v207, vcc
	v_min3_f32 v0, v108, v0, v60
	v_add_f32_e32 v60, v63, v64
	v_cmp_lt_i32_e32 vcc, s2, v61
	v_max3_f32 v65, v107, v86, v84
	s_nop 0
	v_cndmask_b32_e32 v83, v60, v206, vcc
	v_cndmask_b32_e32 v64, v60, v207, vcc
	s_waitcnt vmcnt(11)
	v_mfma_f32_16x16x32_bf16 v[60:63], v[6:9], v[26:29], 0
	s_nop 7
	v_max_i32_e32 v60, 0, v60
	v_max_i32_e32 v61, 0, v61
	v_mul_f32_e32 v66, v2, v60
	v_max_i32_e32 v62, 0, v62
	v_fmac_f32_e32 v66, v3, v61
	v_max_i32_e32 v63, 0, v63
	v_fmac_f32_e32 v66, v4, v62
	v_fmac_f32_e32 v66, v5, v63
	s_waitcnt vmcnt(10)
	v_mfma_f32_16x16x32_bf16 v[60:63], v[6:9], v[30:33], 0
	s_nop 7
	v_max_i32_e32 v60, 0, v60
	v_max_i32_e32 v61, 0, v61
	v_mul_f32_e32 v67, v2, v60
	v_max_i32_e32 v62, 0, v62
	v_fmac_f32_e32 v67, v3, v61
	v_max_i32_e32 v63, 0, v63
	v_fmac_f32_e32 v67, v4, v62
	v_fmac_f32_e32 v67, v5, v63
	s_waitcnt vmcnt(9)
	v_mfma_f32_16x16x32_bf16 v[60:63], v[6:9], v[34:37], 0
	s_nop 7
	v_max_i32_e32 v60, 0, v60
	v_max_i32_e32 v61, 0, v61
	v_mul_f32_e32 v68, v2, v60
	v_max_i32_e32 v62, 0, v62
	v_fmac_f32_e32 v68, v3, v61
	v_max_i32_e32 v63, 0, v63
	v_fmac_f32_e32 v68, v4, v62
	v_fmac_f32_e32 v68, v5, v63
	s_waitcnt vmcnt(8)
	v_mfma_f32_16x16x32_bf16 v[60:63], v[6:9], v[38:41], 0
	s_nop 0
	v_permlane32_swap_b32_e32 v66, v68
	s_nop 5
	v_max_i32_e32 v60, 0, v60
	v_max_i32_e32 v61, 0, v61
	v_mul_f32_e32 v60, v2, v60
	v_max_i32_e32 v62, 0, v62
	v_fmac_f32_e32 v60, v3, v61
	v_max_i32_e32 v63, 0, v63
	v_fmac_f32_e32 v60, v4, v62
	v_fmac_f32_e32 v60, v5, v63
	v_add_f32_e32 v61, v66, v68
	s_nop 0
	v_permlane32_swap_b32_e32 v67, v60
	v_add_f32_e32 v60, v67, v60
	s_nop 1
	v_permlane16_swap_b32_e32 v61, v60
	v_add_f32_e32 v60, v61, v60
	v_or_b32_e32 v61, 0x2c0, v176
	v_cmp_lt_i32_e32 vcc, s2, v61
	s_nop 1
	v_cndmask_b32_e32 v85, v60, v206, vcc
	v_cndmask_b32_e32 v60, v60, v207, vcc
	v_max3_f32 v107, v65, v83, v85
	v_min3_f32 v108, v0, v64, v60
	s_branch .LBB0_974

; __device__ __forceinline__ SwapPair swap32p(float x, float y) { unsigned a = __builtin_bit_cast(unsigned, x), b = __builtin_bit_cast(unsigned, y); asm volatile("" : "+v"(a), "+v"(b)); auto r = __builtin_amdgcn_permlane32_swap(a, b, false, false); return SwapPair{r[0], r[1]}; }
; __device__ __forceinline__ SwapPair swap16p(float x, float y) { unsigned a = __builtin_bit_cast(unsigned, x), b = __builtin_bit_cast(unsigned, y); asm volatile("" : "+v"(a), "+v"(b)); auto r = __builtin_amdgcn_permlane16_swap(a, b, false, false); return SwapPair{r[0], r[1]}; }
; #define MFMA16(a, b, c) __builtin_amdgcn_mfma_f32_16x16x32_bf16((a), (b), (c), 0, 0, 0)
; __device__ __forceinline__ void dsa_token(Frame& F, int b, int t, const bf16* QI, const bf16* KI, const float* WI, const bf16* CKVN, const bf16* QLAT, bf16* OLAT) {
;     ...
;         for (int g4 = 0; g4 < 16; ++g4) {
;             if (4 * g4 <= cmax) {
; #pragma unroll
;                 for (int c = 4 * g4; c < 4 * g4 + 4; ++c) {
;                     asm volatile("" : "+v"(kp));
;                     if (c + 2 < 64) { if (c + 2 <= cmax4) DSA_KLOAD(c + 2, 2); }
;                     float v[4];
; #pragma unroll
;                     for (int tau = 0; tau < 4; ++tau) {
;                         const f32x4 d = MFMA16(qa, kbuf[c % 3][tau], ((f32x4){0.f, 0.f, 0.f, 0.f}));
;                         typedef int i32x4_ __attribute__((ext_vector_type(4)));
;                         const f32x4 rl = __builtin_bit_cast(f32x4, __builtin_elementwise_max(__builtin_bit_cast(i32x4_, d), ((i32x4_){0, 0, 0, 0})));
;                         v[tau] = fmaf(w4.w, rl[3], fmaf(w4.z, rl[2], fmaf(w4.y, rl[1], w4.x * rl[0])));
;                     }
;                     const SwapPair r0 = swap32p(v[0], v[2]), r1 = swap32p(v[1], v[3]);
;                     const float a0 = __builtin_bit_cast(float, r0.a) + __builtin_bit_cast(float, r0.b), a1 = __builtin_bit_cast(float, r1.a) + __builtin_bit_cast(float, r1.b);
;                     const SwapPair r2 = swap16p(a0, a1);
;                     const float keep = __builtin_bit_cast(float, r2.a) + __builtin_bit_cast(float, r2.b);
;                     const bool cand = 64 * c + lane <= t;
;                     sc[c] = cand ? keep : -INFINITY; vmax = fmaxf(vmax, sc[c]); vmin = fminf(vmin, cand ? keep : INFINITY);
;                     kp += 64 * 32;
.LBB0_974:
	s_cmp_gt_i32 s18, 11
	s_cselect_b64 s[88:89], -1, 0
	s_cmp_lt_i32 s18, 12
	v_mov_b32_e32 v94, 0xff800000
	s_cbranch_scc1 .LBB0_984
	s_cmp_lt_i32 s16, 14
	s_nop 0
	v_add_co_u32_e32 v38, vcc, 0x2000, v58
	s_nop 1
	v_addc_co_u32_e32 v39, vcc, 0, v59, vcc
	global_load_dwordx4 v[26:29], v[38:39], off
	global_load_dwordx4 v[30:33], v[38:39], off offset:1024
	global_load_dwordx4 v[34:37], v[38:39], off offset:2048
	s_nop 0
	global_load_dwordx4 v[38:41], v[38:39], off offset:3072
.LBB0_977:
	s_waitcnt vmcnt(11)
	v_mfma_f32_16x16x32_bf16 v[60:63], v[6:9], v[22:25], 0
	v_lshl_add_u64 v[58:59], v[58:59], 0, s[28:29]
	s_cmp_lt_i32 s16, 15
	s_nop 5
	v_max_i32_e32 v60, 0, v60
	v_max_i32_e32 v61, 0, v61
	v_mul_f32_e32 v64, v2, v60
	v_max_i32_e32 v62, 0, v62
	v_fmac_f32_e32 v64, v3, v61
	v_max_i32_e32 v0, 0, v63
	v_fmac_f32_e32 v64, v4, v62
	s_waitcnt vmcnt(10)
	v_mfma_f32_16x16x32_bf16 v[60:63], v[6:9], v[18:21], 0
	v_fmac_f32_e32 v64, v5, v0
	s_nop 6
	v_max_i32_e32 v60, 0, v60
	v_max_i32_e32 v61, 0, v61
	v_mul_f32_e32 v65, v2, v60
	v_max_i32_e32 v62, 0, v62
	v_fmac_f32_e32 v65, v3, v61
	v_max_i32_e32 v0, 0, v63
	v_fmac_f32_e32 v65, v4, v62
	s_waitcnt vmcnt(9)
	v_mfma_f32_16x16x32_bf16 v[60:63], v[6:9], v[14:17], 0
	v_fmac_f32_e32 v65, v5, v0
	s_nop 6
	v_max_i32_e32 v60, 0, v60
	v_max_i32_e32 v61, 0, v61
	v_mul_f32_e32 v66, v2, v60
	v_max_i32_e32 v62, 0, v62
	v_fmac_f32_e32 v66, v3, v61
	v_max_i32_e32 v0, 0, v63
	v_fmac_f32_e32 v66, v4, v62
	s_waitcnt vmcnt(8)
	v_mfma_f32_16x16x32_bf16 v[60:63], v[6:9], v[10:13], 0
	v_fmac_f32_e32 v66, v5, v0
	s_nop 1
	v_permlane32_swap_b32_e32 v64, v66
	s_nop 3
	v_max_i32_e32 v60, 0, v60
	v_max_i32_e32 v61, 0, v61
	v_mul_f32_e32 v60, v2, v60
	v_max_i32_e32 v62, 0, v62
	v_fmac_f32_e32 v60, v3, v61
	v_max_i32_e32 v0, 0, v63
	v_fmac_f32_e32 v60, v4, v62
	v_fmac_f32_e32 v60, v5, v0
	v_add_f32_e32 v0, v64, v66
	s_nop 0
	v_permlane32_swap_b32_e32 v65, v60
	v_add_f32_e32 v60, v65, v60
	s_nop 1
	v_permlane16_swap_b32_e32 v0, v60
	s_nop 0
	v_add_co_u32_e32 v10, vcc, 0x2000, v58
	s_nop 1
	v_addc_co_u32_e32 v11, vcc, 0, v59, vcc
	global_load_dwordx4 v[22:25], v[10:11], off
	global_load_dwordx4 v[18:21], v[10:11], off offset:1024
	global_load_dwordx4 v[14:17], v[10:11], off offset:2048
	s_nop 0
	global_load_dwordx4 v[10:13], v[10:11], off offset:3072
.LBB0_979:
	s_waitcnt vmcnt(11)
	v_mfma_f32_16x16x32_bf16 v[62:65], v[6:9], v[42:45], 0
	v_lshl_add_u64 v[58:59], v[58:59], 0, s[28:29]
	s_cmp_lt_i32 s16, 16
	s_nop 5
	v_max_i32_e32 v62, 0, v62
	v_max_i32_e32 v63, 0, v63
	v_mul_f32_e32 v66, v2, v62
	v_max_i32_e32 v64, 0, v64
	v_fmac_f32_e32 v66, v3, v63
	v_max_i32_e32 v61, 0, v65
	v_fmac_f32_e32 v66, v4, v64
	s_waitcnt vmcnt(10)
	v_mfma_f32_16x16x32_bf16 v[62:65], v[6:9], v[46:49], 0
	v_fmac_f32_e32 v66, v5, v61
	s_nop 6
	v_max_i32_e32 v62, 0, v62
	v_max_i32_e32 v63, 0, v63
	v_mul_f32_e32 v67, v2, v62
	v_max_i32_e32 v64, 0, v64
	v_fmac_f32_e32 v67, v3, v63
	v_max_i32_e32 v61, 0, v65
	v_fmac_f32_e32 v67, v4, v64
	s_waitcnt vmcnt(9)
	v_mfma_f32_16x16x32_bf16 v[62:65], v[6:9], v[50:53], 0
	v_fmac_f32_e32 v67, v5, v61
	s_nop 6
	v_max_i32_e32 v62, 0, v62
	v_max_i32_e32 v63, 0, v63
	v_mul_f32_e32 v68, v2, v62
	v_max_i32_e32 v64, 0, v64
	v_fmac_f32_e32 v68, v3, v63
	v_max_i32_e32 v61, 0, v65
	v_fmac_f32_e32 v68, v4, v64
	s_waitcnt vmcnt(8)
	v_mfma_f32_16x16x32_bf16 v[62:65], v[6:9], v[54:57], 0
	v_fmac_f32_e32 v68, v5, v61
	s_nop 1
	v_permlane32_swap_b32_e32 v66, v68
	s_nop 3
	v_max_i32_e32 v62, 0, v62
	v_max_i32_e32 v63, 0, v63
	v_mul_f32_e32 v62, v2, v62
	v_max_i32_e32 v64, 0, v64
	v_fmac_f32_e32 v62, v3, v63
	v_max_i32_e32 v61, 0, v65
	v_fmac_f32_e32 v62, v4, v64
	v_fmac_f32_e32 v62, v5, v61
	v_add_f32_e32 v61, v66, v68
	s_nop 0
	v_permlane32_swap_b32_e32 v67, v62
	v_add_f32_e32 v62, v67, v62
	s_nop 1
	v_permlane16_swap_b32_e32 v61, v62
	s_nop 0
	v_add_co_u32_e32 v54, vcc, 0x2000, v58
	s_nop 1
	v_addc_co_u32_e32 v55, vcc, 0, v59, vcc
	global_load_dwordx4 v[42:45], v[54:55], off
	global_load_dwordx4 v[46:49], v[54:55], off offset:1024
	global_load_dwordx4 v[50:53], v[54:55], off offset:2048
	s_nop 0
	global_load_dwordx4 v[54:57], v[54:55], off offset:3072
; __device__ __forceinline__ SwapPair swap32p(float x, float y) { unsigned a = __builtin_bit_cast(unsigned, x), b = __builtin_bit_cast(unsigned, y); asm volatile("" : "+v"(a), "+v"(b)); auto r = __builtin_amdgcn_permlane32_swap(a, b, false, false); return SwapPair{r[0], r[1]}; }
; __device__ __forceinline__ SwapPair swap16p(float x, float y) { unsigned a = __builtin_bit_cast(unsigned, x), b = __builtin_bit_cast(unsigned, y); asm volatile("" : "+v"(a), "+v"(b)); auto r = __builtin_amdgcn_permlane16_swap(a, b, false, false); return SwapPair{r[0], r[1]}; }
; #define MFMA16(a, b, c) __builtin_amdgcn_mfma_f32_16x16x32_bf16((a), (b), (c), 0, 0, 0)
; __device__ __forceinline__ void dsa_token(Frame& F, int b, int t, const bf16* QI, const bf16* KI, const float* WI, const bf16* CKVN, const bf16* QLAT, bf16* OLAT) {
;     ...
;         for (int g4 = 0; g4 < 16; ++g4) {
;             if (4 * g4 <= cmax) {
; #pragma unroll
;                 for (int c = 4 * g4; c < 4 * g4 + 4; ++c) {
;                     asm volatile("" : "+v"(kp));
;                     if (c + 2 < 64) { if (c + 2 <= cmax4) DSA_KLOAD(c + 2, 2); }
;                     float v[4];
; #pragma unroll
;                     for (int tau = 0; tau < 4; ++tau) {
;                         const f32x4 d = MFMA16(qa, kbuf[c % 3][tau], ((f32x4){0.f, 0.f, 0.f, 0.f}));
;                         typedef int i32x4_ __attribute__((ext_vector_type(4)));
;                         const f32x4 rl = __builtin_bit_cast(f32x4, __builtin_elementwise_max(__builtin_bit_cast(i32x4_, d), ((i32x4_){0, 0, 0, 0})));
;                         v[tau] = fmaf(w4.w, rl[3], fmaf(w4.z, rl[2], fmaf(w4.y, rl[1], w4.x * rl[0])));
;                     }
;                     const SwapPair r0 = swap32p(v[0], v[2]), r1 = swap32p(v[1], v[3]);
;                     const float a0 = __builtin_bit_cast(float, r0.a) + __builtin_bit_cast(float, r0.b), a1 = __builtin_bit_cast(float, r1.a) + __builtin_bit_cast(float, r1.b);
;                     const SwapPair r2 = swap16p(a0, a1);
;                     const float keep = __builtin_bit_cast(float, r2.a) + __builtin_bit_cast(float, r2.b);
;                     const bool cand = 64 * c + lane <= t;
;                     sc[c] = cand ? keep : -INFINITY; vmax = fmaxf(vmax, sc[c]); vmin = fminf(vmin, cand ? keep : INFINITY);
;                     kp += 64 * 32;
.LBB0_981:
	s_waitcnt vmcnt(11)
	v_mfma_f32_16x16x32_bf16 v[64:67], v[6:9], v[26:29], 0
	v_lshl_add_u64 v[58:59], v[58:59], 0, s[28:29]
	s_cmp_lt_i32 s16, 17
	s_nop 5
	v_max_i32_e32 v64, 0, v64
	v_max_i32_e32 v65, 0, v65
	v_mul_f32_e32 v68, v2, v64
	v_max_i32_e32 v66, 0, v66
	v_fmac_f32_e32 v68, v3, v65
	v_max_i32_e32 v63, 0, v67
	v_fmac_f32_e32 v68, v4, v66
	s_waitcnt vmcnt(10)
	v_mfma_f32_16x16x32_bf16 v[64:67], v[6:9], v[30:33], 0
	v_fmac_f32_e32 v68, v5, v63
	s_nop 6
	v_max_i32_e32 v64, 0, v64
	v_max_i32_e32 v65, 0, v65
	v_mul_f32_e32 v69, v2, v64
	v_max_i32_e32 v66, 0, v66
	v_fmac_f32_e32 v69, v3, v65
	v_max_i32_e32 v63, 0, v67
	v_fmac_f32_e32 v69, v4, v66
	s_waitcnt vmcnt(9)
	v_mfma_f32_16x16x32_bf16 v[64:67], v[6:9], v[34:37], 0
	v_fmac_f32_e32 v69, v5, v63
	s_nop 6
	v_max_i32_e32 v64, 0, v64
	v_max_i32_e32 v65, 0, v65
	v_mul_f32_e32 v70, v2, v64
	v_max_i32_e32 v66, 0, v66
	v_fmac_f32_e32 v70, v3, v65
	v_max_i32_e32 v63, 0, v67
	v_fmac_f32_e32 v70, v4, v66
	s_waitcnt vmcnt(8)
	v_mfma_f32_16x16x32_bf16 v[64:67], v[6:9], v[38:41], 0
	v_fmac_f32_e32 v70, v5, v63
	s_nop 1
	v_permlane32_swap_b32_e32 v68, v70
	s_nop 3
	v_max_i32_e32 v64, 0, v64
	v_max_i32_e32 v65, 0, v65
	v_mul_f32_e32 v64, v2, v64
	v_max_i32_e32 v66, 0, v66
	v_fmac_f32_e32 v64, v3, v65
	v_max_i32_e32 v63, 0, v67
	v_fmac_f32_e32 v64, v4, v66
	v_fmac_f32_e32 v64, v5, v63
	v_add_f32_e32 v63, v68, v70
	s_nop 0
	v_permlane32_swap_b32_e32 v69, v64
	v_add_f32_e32 v64, v69, v64
	s_nop 1
	v_permlane16_swap_b32_e32 v63, v64
	s_nop 0
	v_add_co_u32_e32 v38, vcc, 0x2000, v58
	s_nop 1
	v_addc_co_u32_e32 v39, vcc, 0, v59, vcc
	global_load_dwordx4 v[26:29], v[38:39], off
	global_load_dwordx4 v[30:33], v[38:39], off offset:1024
	global_load_dwordx4 v[34:37], v[38:39], off offset:2048
	s_nop 0
	global_load_dwordx4 v[38:41], v[38:39], off offset:3072
.LBB0_983:
	v_add_f32_e32 v0, v0, v60
	v_or_b32_e32 v60, 0x300, v176
	v_cmp_lt_i32_e32 vcc, s2, v60
	v_add_f32_e32 v60, v61, v62
	v_or_b32_e32 v61, 0x340, v176
	v_cndmask_b32_e32 v94, v0, v206, vcc
	v_cndmask_b32_e32 v0, v0, v207, vcc
	v_cmp_lt_i32_e32 vcc, s2, v61
	v_or_b32_e32 v61, 0x380, v176
	v_lshl_add_u64 v[58:59], v[58:59], 0, s[28:29]
	v_cndmask_b32_e32 v92, v60, v206, vcc
	v_cndmask_b32_e32 v60, v60, v207, vcc
	v_min3_f32 v0, v108, v0, v60
	v_add_f32_e32 v60, v63, v64
	v_cmp_lt_i32_e32 vcc, s2, v61
	v_max3_f32 v65, v107, v94, v92
	s_nop 0
	v_cndmask_b32_e32 v91, v60, v206, vcc
	v_cndmask_b32_e32 v64, v60, v207, vcc
	s_waitcnt vmcnt(11)
	v_mfma_f32_16x16x32_bf16 v[60:63], v[6:9], v[22:25], 0
	s_nop 7
	v_max_i32_e32 v60, 0, v60
	v_max_i32_e32 v61, 0, v61
	v_mul_f32_e32 v66, v2, v60
	v_max_i32_e32 v62, 0, v62
	v_fmac_f32_e32 v66, v3, v61
	v_max_i32_e32 v63, 0, v63
	v_fmac_f32_e32 v66, v4, v62
	v_fmac_f32_e32 v66, v5, v63
	s_waitcnt vmcnt(10)
	v_mfma_f32_16x16x32_bf16 v[60:63], v[6:9], v[18:21], 0
	s_nop 7
	v_max_i32_e32 v60, 0, v60
	v_max_i32_e32 v61, 0, v61
	v_mul_f32_e32 v67, v2, v60
	v_max_i32_e32 v62, 0, v62
	v_fmac_f32_e32 v67, v3, v61
	v_max_i32_e32 v63, 0, v63
	v_fmac_f32_e32 v67, v4, v62
	v_fmac_f32_e32 v67, v5, v63
	s_waitcnt vmcnt(9)
	v_mfma_f32_16x16x32_bf16 v[60:63], v[6:9], v[14:17], 0
	s_nop 7
	v_max_i32_e32 v60, 0, v60
	v_max_i32_e32 v61, 0, v61
	v_mul_f32_e32 v68, v2, v60
	v_max_i32_e32 v62, 0, v62
	v_fmac_f32_e32 v68, v3, v61
	v_max_i32_e32 v63, 0, v63
	v_fmac_f32_e32 v68, v4, v62
	v_fmac_f32_e32 v68, v5, v63
	s_waitcnt vmcnt(8)
	v_mfma_f32_16x16x32_bf16 v[60:63], v[6:9], v[10:13], 0
	s_nop 0
	v_permlane32_swap_b32_e32 v66, v68
	s_nop 5
	v_max_i32_e32 v60, 0, v60
	v_max_i32_e32 v61, 0, v61
	v_mul_f32_e32 v60, v2, v60
	v_max_i32_e32 v62, 0, v62
	v_fmac_f32_e32 v60, v3, v61
	v_max_i32_e32 v63, 0, v63
	v_fmac_f32_e32 v60, v4, v62
	v_fmac_f32_e32 v60, v5, v63
	v_add_f32_e32 v61, v66, v68
	s_nop 0
	v_permlane32_swap_b32_e32 v67, v60
	v_add_f32_e32 v60, v67, v60
	s_nop 1
	v_permlane16_swap_b32_e32 v61, v60
	v_add_f32_e32 v60, v61, v60
	v_or_b32_e32 v61, 0x3c0, v176
	v_cmp_lt_i32_e32 vcc, s2, v61
	s_nop 1
	v_cndmask_b32_e32 v93, v60, v206, vcc
	v_cndmask_b32_e32 v60, v60, v207, vcc
	v_max3_f32 v107, v65, v91, v93
	v_min3_f32 v108, v0, v64, v60
	s_branch .LBB0_985

; __device__ __forceinline__ SwapPair swap32p(float x, float y) { unsigned a = __builtin_bit_cast(unsigned, x), b = __builtin_bit_cast(unsigned, y); asm volatile("" : "+v"(a), "+v"(b)); auto r = __builtin_amdgcn_permlane32_swap(a, b, false, false); return SwapPair{r[0], r[1]}; }
; __device__ __forceinline__ SwapPair swap16p(float x, float y) { unsigned a = __builtin_bit_cast(unsigned, x), b = __builtin_bit_cast(unsigned, y); asm volatile("" : "+v"(a), "+v"(b)); auto r = __builtin_amdgcn_permlane16_swap(a, b, false, false); return SwapPair{r[0], r[1]}; }
; #define MFMA16(a, b, c) __builtin_amdgcn_mfma_f32_16x16x32_bf16((a), (b), (c), 0, 0, 0)
; __device__ __forceinline__ void dsa_token(Frame& F, int b, int t, const bf16* QI, const bf16* KI, const float* WI, const bf16* CKVN, const bf16* QLAT, bf16* OLAT) {
;     ...
;         for (int g4 = 0; g4 < 16; ++g4) {
;             if (4 * g4 <= cmax) {
; #pragma unroll
;                 for (int c = 4 * g4; c < 4 * g4 + 4; ++c) {
;                     asm volatile("" : "+v"(kp));
;                     if (c + 2 < 64) { if (c + 2 <= cmax4) DSA_KLOAD(c + 2, 2); }
;                     float v[4];
; #pragma unroll
;                     for (int tau = 0; tau < 4; ++tau) {
;                         const f32x4 d = MFMA16(qa, kbuf[c % 3][tau], ((f32x4){0.f, 0.f, 0.f, 0.f}));
;                         typedef int i32x4_ __attribute__((ext_vector_type(4)));
;                         const f32x4 rl = __builtin_bit_cast(f32x4, __builtin_elementwise_max(__builtin_bit_cast(i32x4_, d), ((i32x4_){0, 0, 0, 0})));
;                         v[tau] = fmaf(w4.w, rl[3], fmaf(w4.z, rl[2], fmaf(w4.y, rl[1], w4.x * rl[0])));
;                     }
;                     const SwapPair r0 = swap32p(v[0], v[2]), r1 = swap32p(v[1], v[3]);
;                     const float a0 = __builtin_bit_cast(float, r0.a) + __builtin_bit_cast(float, r0.b), a1 = __builtin_bit_cast(float, r1.a) + __builtin_bit_cast(float, r1.b);
;                     const SwapPair r2 = swap16p(a0, a1);
;                     const float keep = __builtin_bit_cast(float, r2.a) + __builtin_bit_cast(float, r2.b);
;                     const bool cand = 64 * c + lane <= t;
;                     sc[c] = cand ? keep : -INFINITY; vmax = fmaxf(vmax, sc[c]); vmin = fminf(vmin, cand ? keep : INFINITY);
;                     kp += 64 * 32;
.LBB0_985:
	s_cmp_gt_i32 s18, 15
	s_cselect_b64 s[24:25], -1, 0
	s_cmp_lt_i32 s18, 16
	v_mov_b32_e32 v0, 0xff800000
	s_cbranch_scc1 .LBB0_995
	s_cmp_lt_i32 s16, 18
	s_nop 0
	s_nop 0
	v_add_co_u32_e32 v10, vcc, 0x2000, v58
	s_nop 1
	v_addc_co_u32_e32 v11, vcc, 0, v59, vcc
	global_load_dwordx4 v[22:25], v[10:11], off
	global_load_dwordx4 v[18:21], v[10:11], off offset:1024
	global_load_dwordx4 v[14:17], v[10:11], off offset:2048
	s_nop 0
	global_load_dwordx4 v[10:13], v[10:11], off offset:3072
.LBB0_988:
	s_waitcnt vmcnt(11)
	v_mfma_f32_16x16x32_bf16 v[60:63], v[6:9], v[42:45], 0
	v_lshl_add_u64 v[58:59], v[58:59], 0, s[28:29]
	s_cmp_lt_i32 s16, 19
	s_nop 5
	v_max_i32_e32 v60, 0, v60
	v_max_i32_e32 v61, 0, v61
	v_mul_f32_e32 v64, v2, v60
	v_max_i32_e32 v62, 0, v62
	v_fmac_f32_e32 v64, v3, v61
	v_max_i32_e32 v0, 0, v63
	v_fmac_f32_e32 v64, v4, v62
	s_waitcnt vmcnt(10)
	v_mfma_f32_16x16x32_bf16 v[60:63], v[6:9], v[46:49], 0
	v_fmac_f32_e32 v64, v5, v0
	s_nop 6
	v_max_i32_e32 v60, 0, v60
	v_max_i32_e32 v61, 0, v61
	v_mul_f32_e32 v65, v2, v60
	v_max_i32_e32 v62, 0, v62
	v_fmac_f32_e32 v65, v3, v61
	v_max_i32_e32 v0, 0, v63
	v_fmac_f32_e32 v65, v4, v62
	s_waitcnt vmcnt(9)
	v_mfma_f32_16x16x32_bf16 v[60:63], v[6:9], v[50:53], 0
	v_fmac_f32_e32 v65, v5, v0
	s_nop 6
	v_max_i32_e32 v60, 0, v60
	v_max_i32_e32 v61, 0, v61
	v_mul_f32_e32 v66, v2, v60
	v_max_i32_e32 v62, 0, v62
	v_fmac_f32_e32 v66, v3, v61
	v_max_i32_e32 v0, 0, v63
	v_fmac_f32_e32 v66, v4, v62
	s_waitcnt vmcnt(8)
	v_mfma_f32_16x16x32_bf16 v[60:63], v[6:9], v[54:57], 0
	v_fmac_f32_e32 v66, v5, v0
	s_nop 1
	v_permlane32_swap_b32_e32 v64, v66
	s_nop 3
	v_max_i32_e32 v60, 0, v60
	v_max_i32_e32 v61, 0, v61
	v_mul_f32_e32 v60, v2, v60
	v_max_i32_e32 v62, 0, v62
	v_fmac_f32_e32 v60, v3, v61
	v_max_i32_e32 v0, 0, v63
	v_fmac_f32_e32 v60, v4, v62
	v_fmac_f32_e32 v60, v5, v0
	v_add_f32_e32 v0, v64, v66
	s_nop 0
	v_permlane32_swap_b32_e32 v65, v60
	v_add_f32_e32 v60, v65, v60
	s_nop 1
	v_permlane16_swap_b32_e32 v0, v60
	s_nop 0
	v_add_co_u32_e32 v54, vcc, 0x2000, v58
	s_nop 1
	v_addc_co_u32_e32 v55, vcc, 0, v59, vcc
	global_load_dwordx4 v[42:45], v[54:55], off
	global_load_dwordx4 v[46:49], v[54:55], off offset:1024
	global_load_dwordx4 v[50:53], v[54:55], off offset:2048
	s_nop 0
	global_load_dwordx4 v[54:57], v[54:55], off offset:3072
.LBB0_990:
	s_waitcnt vmcnt(11)
	v_mfma_f32_16x16x32_bf16 v[62:65], v[6:9], v[26:29], 0
	v_lshl_add_u64 v[58:59], v[58:59], 0, s[28:29]
	s_cmp_lt_i32 s16, 20
	s_nop 5
	v_max_i32_e32 v62, 0, v62
	v_max_i32_e32 v63, 0, v63
	v_mul_f32_e32 v66, v2, v62
	v_max_i32_e32 v64, 0, v64
	v_fmac_f32_e32 v66, v3, v63
	v_max_i32_e32 v61, 0, v65
	v_fmac_f32_e32 v66, v4, v64
	s_waitcnt vmcnt(10)
	v_mfma_f32_16x16x32_bf16 v[62:65], v[6:9], v[30:33], 0
	v_fmac_f32_e32 v66, v5, v61
	s_nop 6
	v_max_i32_e32 v62, 0, v62
	v_max_i32_e32 v63, 0, v63
	v_mul_f32_e32 v67, v2, v62
	v_max_i32_e32 v64, 0, v64
	v_fmac_f32_e32 v67, v3, v63
	v_max_i32_e32 v61, 0, v65
	v_fmac_f32_e32 v67, v4, v64
	s_waitcnt vmcnt(9)
	v_mfma_f32_16x16x32_bf16 v[62:65], v[6:9], v[34:37], 0
	v_fmac_f32_e32 v67, v5, v61
	s_nop 6
	v_max_i32_e32 v62, 0, v62
	v_max_i32_e32 v63, 0, v63
	v_mul_f32_e32 v68, v2, v62
	v_max_i32_e32 v64, 0, v64
	v_fmac_f32_e32 v68, v3, v63
	v_max_i32_e32 v61, 0, v65
	v_fmac_f32_e32 v68, v4, v64
	s_waitcnt vmcnt(8)
	v_mfma_f32_16x16x32_bf16 v[62:65], v[6:9], v[38:41], 0
	v_fmac_f32_e32 v68, v5, v61
	s_nop 1
	v_permlane32_swap_b32_e32 v66, v68
	s_nop 3
	v_max_i32_e32 v62, 0, v62
	v_max_i32_e32 v63, 0, v63
	v_mul_f32_e32 v62, v2, v62
	v_max_i32_e32 v64, 0, v64
	v_fmac_f32_e32 v62, v3, v63
	v_max_i32_e32 v61, 0, v65
	v_fmac_f32_e32 v62, v4, v64
	v_fmac_f32_e32 v62, v5, v61
	v_add_f32_e32 v61, v66, v68
	s_nop 0
	v_permlane32_swap_b32_e32 v67, v62
	v_add_f32_e32 v62, v67, v62
	s_nop 1
	v_permlane16_swap_b32_e32 v61, v62
	s_nop 0
	v_add_co_u32_e32 v38, vcc, 0x2000, v58
	s_nop 1
	v_addc_co_u32_e32 v39, vcc, 0, v59, vcc
	global_load_dwordx4 v[26:29], v[38:39], off
	global_load_dwordx4 v[30:33], v[38:39], off offset:1024
	global_load_dwordx4 v[34:37], v[38:39], off offset:2048
	s_nop 0
	global_load_dwordx4 v[38:41], v[38:39], off offset:3072
; __device__ __forceinline__ SwapPair swap32p(float x, float y) { unsigned a = __builtin_bit_cast(unsigned, x), b = __builtin_bit_cast(unsigned, y); asm volatile("" : "+v"(a), "+v"(b)); auto r = __builtin_amdgcn_permlane32_swap(a, b, false, false); return SwapPair{r[0], r[1]}; }
; __device__ __forceinline__ SwapPair swap16p(float x, float y) { unsigned a = __builtin_bit_cast(unsigned, x), b = __builtin_bit_cast(unsigned, y); asm volatile("" : "+v"(a), "+v"(b)); auto r = __builtin_amdgcn_permlane16_swap(a, b, false, false); return SwapPair{r[0], r[1]}; }
; #define MFMA16(a, b, c) __builtin_amdgcn_mfma_f32_16x16x32_bf16((a), (b), (c), 0, 0, 0)
; __device__ __forceinline__ void dsa_token(Frame& F, int b, int t, const bf16* QI, const bf16* KI, const float* WI, const bf16* CKVN, const bf16* QLAT, bf16* OLAT) {
;     ...
;         for (int g4 = 0; g4 < 16; ++g4) {
;             if (4 * g4 <= cmax) {
; #pragma unroll
;                 for (int c = 4 * g4; c < 4 * g4 + 4; ++c) {
;                     asm volatile("" : "+v"(kp));
;                     if (c + 2 < 64) { if (c + 2 <= cmax4) DSA_KLOAD(c + 2, 2); }
;                     float v[4];
; #pragma unroll
;                     for (int tau = 0; tau < 4; ++tau) {
;                         const f32x4 d = MFMA16(qa, kbuf[c % 3][tau], ((f32x4){0.f, 0.f, 0.f, 0.f}));
;                         typedef int i32x4_ __attribute__((ext_vector_type(4)));
;                         const f32x4 rl = __builtin_bit_cast(f32x4, __builtin_elementwise_max(__builtin_bit_cast(i32x4_, d), ((i32x4_){0, 0, 0, 0})));
;                         v[tau] = fmaf(w4.w, rl[3], fmaf(w4.z, rl[2], fmaf(w4.y, rl[1], w4.x * rl[0])));
;                     }
;                     const SwapPair r0 = swap32p(v[0], v[2]), r1 = swap32p(v[1], v[3]);
;                     const float a0 = __builtin_bit_cast(float, r0.a) + __builtin_bit_cast(float, r0.b), a1 = __builtin_bit_cast(float, r1.a) + __builtin_bit_cast(float, r1.b);
;                     const SwapPair r2 = swap16p(a0, a1);
;                     const float keep = __builtin_bit_cast(float, r2.a) + __builtin_bit_cast(float, r2.b);
;                     const bool cand = 64 * c + lane <= t;
;                     sc[c] = cand ? keep : -INFINITY; vmax = fmaxf(vmax, sc[c]); vmin = fminf(vmin, cand ? keep : INFINITY);
;                     kp += 64 * 32;
.LBB0_992:
	s_waitcnt vmcnt(11)
	v_mfma_f32_16x16x32_bf16 v[64:67], v[6:9], v[22:25], 0
	v_lshl_add_u64 v[58:59], v[58:59], 0, s[28:29]
	s_cmp_lt_i32 s16, 21
	s_nop 5
	v_max_i32_e32 v64, 0, v64
	v_max_i32_e32 v65, 0, v65
	v_mul_f32_e32 v68, v2, v64
	v_max_i32_e32 v66, 0, v66
	v_fmac_f32_e32 v68, v3, v65
	v_max_i32_e32 v63, 0, v67
	v_fmac_f32_e32 v68, v4, v66
	s_waitcnt vmcnt(10)
	v_mfma_f32_16x16x32_bf16 v[64:67], v[6:9], v[18:21], 0
	v_fmac_f32_e32 v68, v5, v63
	s_nop 6
	v_max_i32_e32 v64, 0, v64
	v_max_i32_e32 v65, 0, v65
	v_mul_f32_e32 v69, v2, v64
	v_max_i32_e32 v66, 0, v66
	v_fmac_f32_e32 v69, v3, v65
	v_max_i32_e32 v63, 0, v67
	v_fmac_f32_e32 v69, v4, v66
	s_waitcnt vmcnt(9)
	v_mfma_f32_16x16x32_bf16 v[64:67], v[6:9], v[14:17], 0
	v_fmac_f32_e32 v69, v5, v63
	s_nop 6
	v_max_i32_e32 v64, 0, v64
	v_max_i32_e32 v65, 0, v65
	v_mul_f32_e32 v70, v2, v64
	v_max_i32_e32 v66, 0, v66
	v_fmac_f32_e32 v70, v3, v65
	v_max_i32_e32 v63, 0, v67
	v_fmac_f32_e32 v70, v4, v66
	s_waitcnt vmcnt(8)
	v_mfma_f32_16x16x32_bf16 v[64:67], v[6:9], v[10:13], 0
	v_fmac_f32_e32 v70, v5, v63
	s_nop 1
	v_permlane32_swap_b32_e32 v68, v70
	s_nop 3
	v_max_i32_e32 v64, 0, v64
	v_max_i32_e32 v65, 0, v65
	v_mul_f32_e32 v64, v2, v64
	v_max_i32_e32 v66, 0, v66
	v_fmac_f32_e32 v64, v3, v65
	v_max_i32_e32 v63, 0, v67
	v_fmac_f32_e32 v64, v4, v66
	v_fmac_f32_e32 v64, v5, v63
	v_add_f32_e32 v63, v68, v70
	s_nop 0
	v_permlane32_swap_b32_e32 v69, v64
	v_add_f32_e32 v64, v69, v64
	s_nop 1
	v_permlane16_swap_b32_e32 v63, v64
	s_nop 0
	v_add_co_u32_e32 v10, vcc, 0x2000, v58
	s_nop 1
	v_addc_co_u32_e32 v11, vcc, 0, v59, vcc
	global_load_dwordx4 v[22:25], v[10:11], off
	global_load_dwordx4 v[18:21], v[10:11], off offset:1024
	global_load_dwordx4 v[14:17], v[10:11], off offset:2048
	s_nop 0
	global_load_dwordx4 v[10:13], v[10:11], off offset:3072
.LBB0_994:
	v_add_f32_e32 v60, v0, v60
	v_or_b32_e32 v0, 0x400, v176
	v_cmp_lt_i32_e32 vcc, s2, v0
	v_add_f32_e32 v62, v61, v62
	v_or_b32_e32 v61, 0x440, v176
	v_cndmask_b32_e32 v0, v60, v206, vcc
	v_cndmask_b32_e32 v60, v60, v207, vcc
	v_cmp_lt_i32_e32 vcc, s2, v61
	v_lshl_add_u64 v[58:59], v[58:59], 0, s[28:29]
	s_nop 0
	v_cndmask_b32_e32 v61, v62, v206, vcc
	v_cndmask_b32_e32 v62, v62, v207, vcc
	v_min3_f32 v67, v108, v60, v62
	v_or_b32_e32 v60, 0x480, v176
	v_add_f32_e32 v62, v63, v64
	v_cmp_lt_i32_e32 vcc, s2, v60
	v_max3_f32 v66, v107, v0, v61
	s_nop 0
	v_cndmask_b32_e32 v60, v62, v206, vcc
	v_cndmask_b32_e32 v68, v62, v207, vcc
	s_waitcnt vmcnt(11)
	v_mfma_f32_16x16x32_bf16 v[62:65], v[6:9], v[42:45], 0
	s_nop 7
	v_max_i32_e32 v62, 0, v62
	v_max_i32_e32 v63, 0, v63
	v_mul_f32_e32 v69, v2, v62
	v_max_i32_e32 v64, 0, v64
	v_fmac_f32_e32 v69, v3, v63
	v_max_i32_e32 v65, 0, v65
	v_fmac_f32_e32 v69, v4, v64
	v_fmac_f32_e32 v69, v5, v65
	s_waitcnt vmcnt(10)
	v_mfma_f32_16x16x32_bf16 v[62:65], v[6:9], v[46:49], 0
	s_nop 7
	v_max_i32_e32 v62, 0, v62
	v_max_i32_e32 v63, 0, v63
	v_mul_f32_e32 v70, v2, v62
	v_max_i32_e32 v64, 0, v64
	v_fmac_f32_e32 v70, v3, v63
	v_max_i32_e32 v65, 0, v65
	v_fmac_f32_e32 v70, v4, v64
	v_fmac_f32_e32 v70, v5, v65
	s_waitcnt vmcnt(9)
	v_mfma_f32_16x16x32_bf16 v[62:65], v[6:9], v[50:53], 0
	s_nop 7
	v_max_i32_e32 v62, 0, v62
	v_max_i32_e32 v63, 0, v63
	v_mul_f32_e32 v75, v2, v62
	v_max_i32_e32 v64, 0, v64
	v_fmac_f32_e32 v75, v3, v63
	v_max_i32_e32 v65, 0, v65
	v_fmac_f32_e32 v75, v4, v64
	v_fmac_f32_e32 v75, v5, v65
	s_waitcnt vmcnt(8)
	v_mfma_f32_16x16x32_bf16 v[62:65], v[6:9], v[54:57], 0
	s_nop 0
	v_permlane32_swap_b32_e32 v69, v75
	s_nop 5
	v_max_i32_e32 v62, 0, v62
	v_max_i32_e32 v63, 0, v63
	v_mul_f32_e32 v62, v2, v62
	v_max_i32_e32 v64, 0, v64
	v_fmac_f32_e32 v62, v3, v63
	v_max_i32_e32 v65, 0, v65
	v_fmac_f32_e32 v62, v4, v64
	v_fmac_f32_e32 v62, v5, v65
	v_add_f32_e32 v63, v69, v75
	s_nop 0
	v_permlane32_swap_b32_e32 v70, v62
	v_add_f32_e32 v62, v70, v62
	s_nop 1
	v_permlane16_swap_b32_e32 v63, v62
	v_add_f32_e32 v63, v63, v62
	v_or_b32_e32 v62, 0x4c0, v176
	v_cmp_lt_i32_e32 vcc, s2, v62
	s_nop 1
	v_cndmask_b32_e32 v62, v63, v206, vcc
	v_cndmask_b32_e32 v63, v63, v207, vcc
	v_max3_f32 v107, v66, v60, v62
	v_min3_f32 v108, v67, v68, v63
	s_branch .LBB0_996

; __device__ __forceinline__ SwapPair swap32p(float x, float y) { unsigned a = __builtin_bit_cast(unsigned, x), b = __builtin_bit_cast(unsigned, y); asm volatile("" : "+v"(a), "+v"(b)); auto r = __builtin_amdgcn_permlane32_swap(a, b, false, false); return SwapPair{r[0], r[1]}; }
; __device__ __forceinline__ SwapPair swap16p(float x, float y) { unsigned a = __builtin_bit_cast(unsigned, x), b = __builtin_bit_cast(unsigned, y); asm volatile("" : "+v"(a), "+v"(b)); auto r = __builtin_amdgcn_permlane16_swap(a, b, false, false); return SwapPair{r[0], r[1]}; }
; #define MFMA16(a, b, c) __builtin_amdgcn_mfma_f32_16x16x32_bf16((a), (b), (c), 0, 0, 0)
; __device__ __forceinline__ void dsa_token(Frame& F, int b, int t, const bf16* QI, const bf16* KI, const float* WI, const bf16* CKVN, const bf16* QLAT, bf16* OLAT) {
;     ...
;         for (int g4 = 0; g4 < 16; ++g4) {
;             if (4 * g4 <= cmax) {
; #pragma unroll
;                 for (int c = 4 * g4; c < 4 * g4 + 4; ++c) {
;                     asm volatile("" : "+v"(kp));
;                     if (c + 2 < 64) { if (c + 2 <= cmax4) DSA_KLOAD(c + 2, 2); }
;                     float v[4];
; #pragma unroll
;                     for (int tau = 0; tau < 4; ++tau) {
;                         const f32x4 d = MFMA16(qa, kbuf[c % 3][tau], ((f32x4){0.f, 0.f, 0.f, 0.f}));
;                         typedef int i32x4_ __attribute__((ext_vector_type(4)));
;                         const f32x4 rl = __builtin_bit_cast(f32x4, __builtin_elementwise_max(__builtin_bit_cast(i32x4_, d), ((i32x4_){0, 0, 0, 0})));
;                         v[tau] = fmaf(w4.w, rl[3], fmaf(w4.z, rl[2], fmaf(w4.y, rl[1], w4.x * rl[0])));
;                     }
;                     const SwapPair r0 = swap32p(v[0], v[2]), r1 = swap32p(v[1], v[3]);
;                     const float a0 = __builtin_bit_cast(float, r0.a) + __builtin_bit_cast(float, r0.b), a1 = __builtin_bit_cast(float, r1.a) + __builtin_bit_cast(float, r1.b);
;                     const SwapPair r2 = swap16p(a0, a1);
;                     const float keep = __builtin_bit_cast(float, r2.a) + __builtin_bit_cast(float, r2.b);
;                     const bool cand = 64 * c + lane <= t;
;                     sc[c] = cand ? keep : -INFINITY; vmax = fmaxf(vmax, sc[c]); vmin = fminf(vmin, cand ? keep : INFINITY);
;                     kp += 64 * 32;
.LBB0_996:
	s_cmp_gt_i32 s18, 19
	s_cselect_b64 s[56:57], -1, 0
	s_cmp_lt_i32 s18, 20
	v_mov_b32_e32 v63, 0xff800000
	s_cbranch_scc1 .LBB0_1006
	s_cmp_lt_i32 s16, 22
	s_nop 0
	s_nop 0
	v_add_co_u32_e32 v54, vcc, 0x2000, v58
	s_nop 1
	v_addc_co_u32_e32 v55, vcc, 0, v59, vcc
	global_load_dwordx4 v[42:45], v[54:55], off
	global_load_dwordx4 v[46:49], v[54:55], off offset:1024
	global_load_dwordx4 v[50:53], v[54:55], off offset:2048
	s_nop 0
	global_load_dwordx4 v[54:57], v[54:55], off offset:3072
.LBB0_999:
	s_waitcnt vmcnt(11)
	v_mfma_f32_16x16x32_bf16 v[64:67], v[6:9], v[26:29], 0
	v_lshl_add_u64 v[58:59], v[58:59], 0, s[28:29]
	s_cmp_lt_i32 s16, 23
	s_nop 5
	v_max_i32_e32 v64, 0, v64
	v_max_i32_e32 v65, 0, v65
	v_mul_f32_e32 v68, v2, v64
	v_max_i32_e32 v66, 0, v66
	v_fmac_f32_e32 v68, v3, v65
	v_max_i32_e32 v63, 0, v67
	v_fmac_f32_e32 v68, v4, v66
	s_waitcnt vmcnt(10)
	v_mfma_f32_16x16x32_bf16 v[64:67], v[6:9], v[30:33], 0
	v_fmac_f32_e32 v68, v5, v63
	s_nop 6
	v_max_i32_e32 v64, 0, v64
	v_max_i32_e32 v65, 0, v65
	v_mul_f32_e32 v69, v2, v64
	v_max_i32_e32 v66, 0, v66
	v_fmac_f32_e32 v69, v3, v65
	v_max_i32_e32 v63, 0, v67
	v_fmac_f32_e32 v69, v4, v66
	s_waitcnt vmcnt(9)
	v_mfma_f32_16x16x32_bf16 v[64:67], v[6:9], v[34:37], 0
	v_fmac_f32_e32 v69, v5, v63
	s_nop 6
	v_max_i32_e32 v64, 0, v64
	v_max_i32_e32 v65, 0, v65
	v_mul_f32_e32 v70, v2, v64
	v_max_i32_e32 v66, 0, v66
	v_fmac_f32_e32 v70, v3, v65
	v_max_i32_e32 v63, 0, v67
	v_fmac_f32_e32 v70, v4, v66
	s_waitcnt vmcnt(8)
	v_mfma_f32_16x16x32_bf16 v[64:67], v[6:9], v[38:41], 0
	v_fmac_f32_e32 v70, v5, v63
	s_nop 1
	v_permlane32_swap_b32_e32 v68, v70
	s_nop 3
	v_max_i32_e32 v64, 0, v64
	v_max_i32_e32 v65, 0, v65
	v_mul_f32_e32 v64, v2, v64
	v_max_i32_e32 v66, 0, v66
	v_fmac_f32_e32 v64, v3, v65
	v_max_i32_e32 v63, 0, v67
	v_fmac_f32_e32 v64, v4, v66
	v_fmac_f32_e32 v64, v5, v63
	v_add_f32_e32 v63, v68, v70
	s_nop 0
	v_permlane32_swap_b32_e32 v69, v64
	v_add_f32_e32 v64, v69, v64
	s_nop 1
	v_permlane16_swap_b32_e32 v63, v64
	s_nop 0
	v_add_co_u32_e32 v38, vcc, 0x2000, v58
	s_nop 1
	v_addc_co_u32_e32 v39, vcc, 0, v59, vcc
	global_load_dwordx4 v[26:29], v[38:39], off
	global_load_dwordx4 v[30:33], v[38:39], off offset:1024
	global_load_dwordx4 v[34:37], v[38:39], off offset:2048
	s_nop 0
	global_load_dwordx4 v[38:41], v[38:39], off offset:3072
.LBB0_1001:
	s_waitcnt vmcnt(11)
	v_mfma_f32_16x16x32_bf16 v[66:69], v[6:9], v[22:25], 0
	v_lshl_add_u64 v[58:59], v[58:59], 0, s[28:29]
	s_cmp_lt_i32 s16, 24
	s_nop 5
	v_max_i32_e32 v66, 0, v66
	v_max_i32_e32 v67, 0, v67
	v_mul_f32_e32 v70, v2, v66
	v_max_i32_e32 v68, 0, v68
	v_fmac_f32_e32 v70, v3, v67
	v_max_i32_e32 v65, 0, v69
	v_fmac_f32_e32 v70, v4, v68
	s_waitcnt vmcnt(10)
	v_mfma_f32_16x16x32_bf16 v[66:69], v[6:9], v[18:21], 0
	v_fmac_f32_e32 v70, v5, v65
	s_nop 6
	v_max_i32_e32 v66, 0, v66
	v_max_i32_e32 v67, 0, v67
	v_mul_f32_e32 v75, v2, v66
	v_max_i32_e32 v68, 0, v68
	v_fmac_f32_e32 v75, v3, v67
	v_max_i32_e32 v65, 0, v69
	v_fmac_f32_e32 v75, v4, v68
	s_waitcnt vmcnt(9)
	v_mfma_f32_16x16x32_bf16 v[66:69], v[6:9], v[14:17], 0
	v_fmac_f32_e32 v75, v5, v65
	s_nop 6
	v_max_i32_e32 v66, 0, v66
	v_max_i32_e32 v67, 0, v67
	v_mul_f32_e32 v76, v2, v66
	v_max_i32_e32 v68, 0, v68
	v_fmac_f32_e32 v76, v3, v67
	v_max_i32_e32 v65, 0, v69
	v_fmac_f32_e32 v76, v4, v68
	s_waitcnt vmcnt(8)
	v_mfma_f32_16x16x32_bf16 v[66:69], v[6:9], v[10:13], 0
	v_fmac_f32_e32 v76, v5, v65
	s_nop 1
	v_permlane32_swap_b32_e32 v70, v76
	s_nop 3
	v_max_i32_e32 v66, 0, v66
	v_max_i32_e32 v67, 0, v67
	v_mul_f32_e32 v66, v2, v66
	v_max_i32_e32 v68, 0, v68
	v_fmac_f32_e32 v66, v3, v67
	v_max_i32_e32 v65, 0, v69
	v_fmac_f32_e32 v66, v4, v68
	v_fmac_f32_e32 v66, v5, v65
	v_add_f32_e32 v65, v70, v76
	s_nop 0
	v_permlane32_swap_b32_e32 v75, v66
	v_add_f32_e32 v66, v75, v66
	s_nop 1
	v_permlane16_swap_b32_e32 v65, v66
	s_nop 0
	v_add_co_u32_e32 v10, vcc, 0x2000, v58
	s_nop 1
	v_addc_co_u32_e32 v11, vcc, 0, v59, vcc
	global_load_dwordx4 v[22:25], v[10:11], off
	global_load_dwordx4 v[18:21], v[10:11], off offset:1024
	global_load_dwordx4 v[14:17], v[10:11], off offset:2048
	s_nop 0
	global_load_dwordx4 v[10:13], v[10:11], off offset:3072
; __device__ __forceinline__ SwapPair swap32p(float x, float y) { unsigned a = __builtin_bit_cast(unsigned, x), b = __builtin_bit_cast(unsigned, y); asm volatile("" : "+v"(a), "+v"(b)); auto r = __builtin_amdgcn_permlane32_swap(a, b, false, false); return SwapPair{r[0], r[1]}; }
; __device__ __forceinline__ SwapPair swap16p(float x, float y) { unsigned a = __builtin_bit_cast(unsigned, x), b = __builtin_bit_cast(unsigned, y); asm volatile("" : "+v"(a), "+v"(b)); auto r = __builtin_amdgcn_permlane16_swap(a, b, false, false); return SwapPair{r[0], r[1]}; }
; #define MFMA16(a, b, c) __builtin_amdgcn_mfma_f32_16x16x32_bf16((a), (b), (c), 0, 0, 0)
; __device__ __forceinline__ void dsa_token(Frame& F, int b, int t, const bf16* QI, const bf16* KI, const float* WI, const bf16* CKVN, const bf16* QLAT, bf16* OLAT) {
;     ...
;         for (int g4 = 0; g4 < 16; ++g4) {
;             if (4 * g4 <= cmax) {
; #pragma unroll
;                 for (int c = 4 * g4; c < 4 * g4 + 4; ++c) {
;                     asm volatile("" : "+v"(kp));
;                     if (c + 2 < 64) { if (c + 2 <= cmax4) DSA_KLOAD(c + 2, 2); }
;                     float v[4];
; #pragma unroll
;                     for (int tau = 0; tau < 4; ++tau) {
;                         const f32x4 d = MFMA16(qa, kbuf[c % 3][tau], ((f32x4){0.f, 0.f, 0.f, 0.f}));
;                         typedef int i32x4_ __attribute__((ext_vector_type(4)));
;                         const f32x4 rl = __builtin_bit_cast(f32x4, __builtin_elementwise_max(__builtin_bit_cast(i32x4_, d), ((i32x4_){0, 0, 0, 0})));
;                         v[tau] = fmaf(w4.w, rl[3], fmaf(w4.z, rl[2], fmaf(w4.y, rl[1], w4.x * rl[0])));
;                     }
;                     const SwapPair r0 = swap32p(v[0], v[2]), r1 = swap32p(v[1], v[3]);
;                     const float a0 = __builtin_bit_cast(float, r0.a) + __builtin_bit_cast(float, r0.b), a1 = __builtin_bit_cast(float, r1.a) + __builtin_bit_cast(float, r1.b);
;                     const SwapPair r2 = swap16p(a0, a1);
;                     const float keep = __builtin_bit_cast(float, r2.a) + __builtin_bit_cast(float, r2.b);
;                     const bool cand = 64 * c + lane <= t;
;                     sc[c] = cand ? keep : -INFINITY; vmax = fmaxf(vmax, sc[c]); vmin = fminf(vmin, cand ? keep : INFINITY);
;                     kp += 64 * 32;
.LBB0_1003:
	s_waitcnt vmcnt(11)
	v_mfma_f32_16x16x32_bf16 v[96:99], v[6:9], v[42:45], 0
	v_lshl_add_u64 v[58:59], v[58:59], 0, s[28:29]
	s_cmp_lt_i32 s16, 25
	s_nop 5
	v_max_i32_e32 v67, 0, v99
	v_max_i32_e32 v68, 0, v98
	v_max_i32_e32 v69, 0, v97
	v_max_i32_e32 v70, 0, v96
	s_waitcnt vmcnt(10)
	v_mfma_f32_16x16x32_bf16 v[96:99], v[6:9], v[46:49], 0
	v_mul_f32_e32 v70, v2, v70
	v_fmac_f32_e32 v70, v3, v69
	v_fmac_f32_e32 v70, v4, v68
	v_fmac_f32_e32 v70, v5, v67
	s_nop 3
	v_max_i32_e32 v67, 0, v99
	v_max_i32_e32 v68, 0, v98
	v_max_i32_e32 v69, 0, v97
	v_max_i32_e32 v75, 0, v96
	s_waitcnt vmcnt(9)
	v_mfma_f32_16x16x32_bf16 v[96:99], v[6:9], v[50:53], 0
	v_mul_f32_e32 v75, v2, v75
	v_fmac_f32_e32 v75, v3, v69
	v_fmac_f32_e32 v75, v4, v68
	v_fmac_f32_e32 v75, v5, v67
	s_nop 3
	v_max_i32_e32 v67, 0, v99
	v_max_i32_e32 v68, 0, v98
	v_max_i32_e32 v69, 0, v97
	v_max_i32_e32 v76, 0, v96
	s_waitcnt vmcnt(8)
	v_mfma_f32_16x16x32_bf16 v[96:99], v[6:9], v[54:57], 0
	v_mul_f32_e32 v76, v2, v76
	v_fmac_f32_e32 v76, v3, v69
	v_fmac_f32_e32 v76, v4, v68
	v_fmac_f32_e32 v76, v5, v67
	s_nop 3
	v_max_i32_e32 v77, 0, v96
	v_max_i32_e32 v69, 0, v97
	v_mul_f32_e32 v77, v2, v77
	v_max_i32_e32 v68, 0, v98
	v_fmac_f32_e32 v77, v3, v69
	v_max_i32_e32 v67, 0, v99
	v_fmac_f32_e32 v77, v4, v68
	v_fmac_f32_e32 v77, v5, v67
	v_permlane32_swap_b32_e32 v70, v76
	s_nop 0
	v_permlane32_swap_b32_e32 v75, v77
	v_add_f32_e32 v67, v70, v76
	v_add_f32_e32 v68, v75, v77
	s_nop 1
	v_permlane16_swap_b32_e32 v67, v68
	s_nop 0
	v_add_co_u32_e32 v54, vcc, 0x2000, v58
	s_nop 1
	v_addc_co_u32_e32 v55, vcc, 0, v59, vcc
	global_load_dwordx4 v[42:45], v[54:55], off
	global_load_dwordx4 v[46:49], v[54:55], off offset:1024
	global_load_dwordx4 v[50:53], v[54:55], off offset:2048
	s_nop 0
	global_load_dwordx4 v[54:57], v[54:55], off offset:3072
.LBB0_1005:
	v_add_f32_e32 v64, v63, v64
	v_or_b32_e32 v63, 0x500, v176
	v_cmp_lt_i32_e32 vcc, s2, v63
	v_add_f32_e32 v66, v65, v66
	v_or_b32_e32 v65, 0x540, v176
	v_cndmask_b32_e32 v63, v64, v206, vcc
	v_cndmask_b32_e32 v64, v64, v207, vcc
	v_cmp_lt_i32_e32 vcc, s2, v65
	v_lshl_add_u64 v[58:59], v[58:59], 0, s[28:29]
	s_nop 0
	v_cndmask_b32_e32 v65, v66, v206, vcc
	v_cndmask_b32_e32 v66, v66, v207, vcc
	v_min3_f32 v75, v108, v64, v66
	v_or_b32_e32 v64, 0x580, v176
	v_add_f32_e32 v66, v67, v68
	v_cmp_lt_i32_e32 vcc, s2, v64
	v_max3_f32 v70, v107, v63, v65
	s_nop 0
	v_cndmask_b32_e32 v64, v66, v206, vcc
	v_cndmask_b32_e32 v76, v66, v207, vcc
	s_waitcnt vmcnt(11)
	v_mfma_f32_16x16x32_bf16 v[66:69], v[6:9], v[26:29], 0
	s_nop 7
	v_max_i32_e32 v66, 0, v66
	v_max_i32_e32 v67, 0, v67
	v_mul_f32_e32 v77, v2, v66
	v_max_i32_e32 v68, 0, v68
	v_fmac_f32_e32 v77, v3, v67
	v_max_i32_e32 v69, 0, v69
	v_fmac_f32_e32 v77, v4, v68
	v_fmac_f32_e32 v77, v5, v69
	s_waitcnt vmcnt(10)
	v_mfma_f32_16x16x32_bf16 v[66:69], v[6:9], v[30:33], 0
	s_nop 7
	v_max_i32_e32 v66, 0, v66
	v_max_i32_e32 v67, 0, v67
	v_mul_f32_e32 v79, v2, v66
	v_max_i32_e32 v68, 0, v68
	v_fmac_f32_e32 v79, v3, v67
	v_max_i32_e32 v69, 0, v69
	v_fmac_f32_e32 v79, v4, v68
	v_fmac_f32_e32 v79, v5, v69
	s_waitcnt vmcnt(9)
	v_mfma_f32_16x16x32_bf16 v[66:69], v[6:9], v[34:37], 0
	s_nop 7
	v_max_i32_e32 v66, 0, v66
	v_max_i32_e32 v67, 0, v67
	v_mul_f32_e32 v87, v2, v66
	v_max_i32_e32 v68, 0, v68
	v_fmac_f32_e32 v87, v3, v67
	v_max_i32_e32 v69, 0, v69
	v_fmac_f32_e32 v87, v4, v68
	v_fmac_f32_e32 v87, v5, v69
	s_waitcnt vmcnt(8)
	v_mfma_f32_16x16x32_bf16 v[66:69], v[6:9], v[38:41], 0
	s_nop 0
	v_permlane32_swap_b32_e32 v77, v87
	s_nop 5
	v_max_i32_e32 v66, 0, v66
	v_max_i32_e32 v67, 0, v67
	v_mul_f32_e32 v66, v2, v66
	v_max_i32_e32 v68, 0, v68
	v_fmac_f32_e32 v66, v3, v67
	v_max_i32_e32 v69, 0, v69
	v_fmac_f32_e32 v66, v4, v68
	v_fmac_f32_e32 v66, v5, v69
	v_add_f32_e32 v67, v77, v87
	s_nop 0
	v_permlane32_swap_b32_e32 v79, v66
	v_add_f32_e32 v66, v79, v66
	s_nop 1
	v_permlane16_swap_b32_e32 v67, v66
	v_add_f32_e32 v67, v67, v66
	v_or_b32_e32 v66, 0x5c0, v176
	v_cmp_lt_i32_e32 vcc, s2, v66
	s_nop 1
	v_cndmask_b32_e32 v66, v67, v206, vcc
	v_cndmask_b32_e32 v67, v67, v207, vcc
	v_max3_f32 v107, v70, v64, v66
	v_min3_f32 v108, v75, v76, v67
	s_branch .LBB0_1007

; __device__ __forceinline__ SwapPair swap32p(float x, float y) { unsigned a = __builtin_bit_cast(unsigned, x), b = __builtin_bit_cast(unsigned, y); asm volatile("" : "+v"(a), "+v"(b)); auto r = __builtin_amdgcn_permlane32_swap(a, b, false, false); return SwapPair{r[0], r[1]}; }
; __device__ __forceinline__ SwapPair swap16p(float x, float y) { unsigned a = __builtin_bit_cast(unsigned, x), b = __builtin_bit_cast(unsigned, y); asm volatile("" : "+v"(a), "+v"(b)); auto r = __builtin_amdgcn_permlane16_swap(a, b, false, false); return SwapPair{r[0], r[1]}; }
; #define MFMA16(a, b, c) __builtin_amdgcn_mfma_f32_16x16x32_bf16((a), (b), (c), 0, 0, 0)
; __device__ __forceinline__ void dsa_token(Frame& F, int b, int t, const bf16* QI, const bf16* KI, const float* WI, const bf16* CKVN, const bf16* QLAT, bf16* OLAT) {
;     ...
;         for (int g4 = 0; g4 < 16; ++g4) {
;             if (4 * g4 <= cmax) {
; #pragma unroll
;                 for (int c = 4 * g4; c < 4 * g4 + 4; ++c) {
;                     asm volatile("" : "+v"(kp));
;                     if (c + 2 < 64) { if (c + 2 <= cmax4) DSA_KLOAD(c + 2, 2); }
;                     float v[4];
; #pragma unroll
;                     for (int tau = 0; tau < 4; ++tau) {
;                         const f32x4 d = MFMA16(qa, kbuf[c % 3][tau], ((f32x4){0.f, 0.f, 0.f, 0.f}));
;                         typedef int i32x4_ __attribute__((ext_vector_type(4)));
;                         const f32x4 rl = __builtin_bit_cast(f32x4, __builtin_elementwise_max(__builtin_bit_cast(i32x4_, d), ((i32x4_){0, 0, 0, 0})));
;                         v[tau] = fmaf(w4.w, rl[3], fmaf(w4.z, rl[2], fmaf(w4.y, rl[1], w4.x * rl[0])));
;                     }
;                     const SwapPair r0 = swap32p(v[0], v[2]), r1 = swap32p(v[1], v[3]);
;                     const float a0 = __builtin_bit_cast(float, r0.a) + __builtin_bit_cast(float, r0.b), a1 = __builtin_bit_cast(float, r1.a) + __builtin_bit_cast(float, r1.b);
;                     const SwapPair r2 = swap16p(a0, a1);
;                     const float keep = __builtin_bit_cast(float, r2.a) + __builtin_bit_cast(float, r2.b);
;                     const bool cand = 64 * c + lane <= t;
;                     sc[c] = cand ? keep : -INFINITY; vmax = fmaxf(vmax, sc[c]); vmin = fminf(vmin, cand ? keep : INFINITY);
;                     kp += 64 * 32;
.LBB0_1007:
	s_cmp_gt_i32 s18, 23
	s_cselect_b64 s[64:65], -1, 0
	s_cmp_lt_i32 s18, 24
	v_mov_b32_e32 v67, 0xff800000
	s_cbranch_scc1 .LBB0_1017
	s_cmp_lt_i32 s16, 26
	s_nop 0
	s_nop 0
	v_add_co_u32_e32 v38, vcc, 0x2000, v58
	s_nop 1
	v_addc_co_u32_e32 v39, vcc, 0, v59, vcc
	global_load_dwordx4 v[26:29], v[38:39], off
	global_load_dwordx4 v[30:33], v[38:39], off offset:1024
	global_load_dwordx4 v[34:37], v[38:39], off offset:2048
	s_nop 0
	global_load_dwordx4 v[38:41], v[38:39], off offset:3072
.LBB0_1010:
	s_waitcnt vmcnt(11)
	v_mfma_f32_16x16x32_bf16 v[96:99], v[6:9], v[22:25], 0
	v_lshl_add_u64 v[58:59], v[58:59], 0, s[28:29]
	s_cmp_lt_i32 s16, 27
	s_nop 5
	v_max_i32_e32 v67, 0, v99
	v_max_i32_e32 v68, 0, v98
	v_max_i32_e32 v69, 0, v97
	v_max_i32_e32 v70, 0, v96
	s_waitcnt vmcnt(10)
	v_mfma_f32_16x16x32_bf16 v[96:99], v[6:9], v[18:21], 0
	v_mul_f32_e32 v70, v2, v70
	v_fmac_f32_e32 v70, v3, v69
	v_fmac_f32_e32 v70, v4, v68
	v_fmac_f32_e32 v70, v5, v67
	s_nop 3
	v_max_i32_e32 v67, 0, v99
	v_max_i32_e32 v68, 0, v98
	v_max_i32_e32 v69, 0, v97
	v_max_i32_e32 v75, 0, v96
	s_waitcnt vmcnt(9)
	v_mfma_f32_16x16x32_bf16 v[96:99], v[6:9], v[14:17], 0
	v_mul_f32_e32 v75, v2, v75
	v_fmac_f32_e32 v75, v3, v69
	v_fmac_f32_e32 v75, v4, v68
	v_fmac_f32_e32 v75, v5, v67
	s_nop 3
	v_max_i32_e32 v67, 0, v99
	v_max_i32_e32 v68, 0, v98
	v_max_i32_e32 v69, 0, v97
	v_max_i32_e32 v76, 0, v96
	s_waitcnt vmcnt(8)
	v_mfma_f32_16x16x32_bf16 v[96:99], v[6:9], v[10:13], 0
	v_mul_f32_e32 v76, v2, v76
	v_fmac_f32_e32 v76, v3, v69
	v_fmac_f32_e32 v76, v4, v68
	v_fmac_f32_e32 v76, v5, v67
	s_nop 3
	v_max_i32_e32 v77, 0, v96
	v_max_i32_e32 v69, 0, v97
	v_mul_f32_e32 v77, v2, v77
	v_max_i32_e32 v68, 0, v98
	v_fmac_f32_e32 v77, v3, v69
	v_max_i32_e32 v67, 0, v99
	v_fmac_f32_e32 v77, v4, v68
	v_fmac_f32_e32 v77, v5, v67
	v_permlane32_swap_b32_e32 v70, v76
	s_nop 0
	v_permlane32_swap_b32_e32 v75, v77
	v_add_f32_e32 v67, v70, v76
	v_add_f32_e32 v68, v75, v77
	s_nop 1
	v_permlane16_swap_b32_e32 v67, v68
	s_nop 0
	v_add_co_u32_e32 v10, vcc, 0x2000, v58
	s_nop 1
	v_addc_co_u32_e32 v11, vcc, 0, v59, vcc
	global_load_dwordx4 v[22:25], v[10:11], off
	global_load_dwordx4 v[18:21], v[10:11], off offset:1024
	global_load_dwordx4 v[14:17], v[10:11], off offset:2048
	s_nop 0
	global_load_dwordx4 v[10:13], v[10:11], off offset:3072
.LBB0_1012:
	s_waitcnt vmcnt(11)
	v_mfma_f32_16x16x32_bf16 v[96:99], v[6:9], v[42:45], 0
	v_lshl_add_u64 v[58:59], v[58:59], 0, s[28:29]
	s_cmp_lt_i32 s16, 28
	s_nop 5
	v_max_i32_e32 v69, 0, v99
	v_max_i32_e32 v70, 0, v98
	v_max_i32_e32 v75, 0, v97
	v_max_i32_e32 v76, 0, v96
	s_waitcnt vmcnt(10)
	v_mfma_f32_16x16x32_bf16 v[96:99], v[6:9], v[46:49], 0
	v_mul_f32_e32 v76, v2, v76
	v_fmac_f32_e32 v76, v3, v75
	v_fmac_f32_e32 v76, v4, v70
	v_fmac_f32_e32 v76, v5, v69
	s_nop 3
	v_max_i32_e32 v69, 0, v99
	v_max_i32_e32 v70, 0, v98
	v_max_i32_e32 v75, 0, v97
	v_max_i32_e32 v77, 0, v96
	s_waitcnt vmcnt(9)
	v_mfma_f32_16x16x32_bf16 v[96:99], v[6:9], v[50:53], 0
	v_mul_f32_e32 v77, v2, v77
	v_fmac_f32_e32 v77, v3, v75
	v_fmac_f32_e32 v77, v4, v70
	v_fmac_f32_e32 v77, v5, v69
	s_nop 3
	v_max_i32_e32 v69, 0, v99
	v_max_i32_e32 v70, 0, v98
	v_max_i32_e32 v75, 0, v97
	v_max_i32_e32 v79, 0, v96
	s_waitcnt vmcnt(8)
	v_mfma_f32_16x16x32_bf16 v[96:99], v[6:9], v[54:57], 0
	v_mul_f32_e32 v79, v2, v79
	v_fmac_f32_e32 v79, v3, v75
	v_fmac_f32_e32 v79, v4, v70
	v_fmac_f32_e32 v79, v5, v69
	s_nop 3
	v_max_i32_e32 v87, 0, v96
	v_max_i32_e32 v75, 0, v97
	v_mul_f32_e32 v87, v2, v87
	v_max_i32_e32 v70, 0, v98
	v_fmac_f32_e32 v87, v3, v75
	v_max_i32_e32 v69, 0, v99
	v_fmac_f32_e32 v87, v4, v70
	v_fmac_f32_e32 v87, v5, v69
	v_permlane32_swap_b32_e32 v76, v79
	s_nop 0
	v_permlane32_swap_b32_e32 v77, v87
	v_add_f32_e32 v69, v76, v79
	v_add_f32_e32 v70, v77, v87
	s_nop 1
	v_permlane16_swap_b32_e32 v69, v70
	s_nop 0
	v_add_co_u32_e32 v54, vcc, 0x2000, v58
	s_nop 1
	v_addc_co_u32_e32 v55, vcc, 0, v59, vcc
	global_load_dwordx4 v[42:45], v[54:55], off
	global_load_dwordx4 v[46:49], v[54:55], off offset:1024
	global_load_dwordx4 v[50:53], v[54:55], off offset:2048
	s_nop 0
	global_load_dwordx4 v[54:57], v[54:55], off offset:3072
; __device__ __forceinline__ SwapPair swap32p(float x, float y) { unsigned a = __builtin_bit_cast(unsigned, x), b = __builtin_bit_cast(unsigned, y); asm volatile("" : "+v"(a), "+v"(b)); auto r = __builtin_amdgcn_permlane32_swap(a, b, false, false); return SwapPair{r[0], r[1]}; }
; __device__ __forceinline__ SwapPair swap16p(float x, float y) { unsigned a = __builtin_bit_cast(unsigned, x), b = __builtin_bit_cast(unsigned, y); asm volatile("" : "+v"(a), "+v"(b)); auto r = __builtin_amdgcn_permlane16_swap(a, b, false, false); return SwapPair{r[0], r[1]}; }
; #define MFMA16(a, b, c) __builtin_amdgcn_mfma_f32_16x16x32_bf16((a), (b), (c), 0, 0, 0)
; __device__ __forceinline__ void dsa_token(Frame& F, int b, int t, const bf16* QI, const bf16* KI, const float* WI, const bf16* CKVN, const bf16* QLAT, bf16* OLAT) {
;     ...
;         for (int g4 = 0; g4 < 16; ++g4) {
;             if (4 * g4 <= cmax) {
; #pragma unroll
;                 for (int c = 4 * g4; c < 4 * g4 + 4; ++c) {
;                     asm volatile("" : "+v"(kp));
;                     if (c + 2 < 64) { if (c + 2 <= cmax4) DSA_KLOAD(c + 2, 2); }
;                     float v[4];
; #pragma unroll
;                     for (int tau = 0; tau < 4; ++tau) {
;                         const f32x4 d = MFMA16(qa, kbuf[c % 3][tau], ((f32x4){0.f, 0.f, 0.f, 0.f}));
;                         typedef int i32x4_ __attribute__((ext_vector_type(4)));
;                         const f32x4 rl = __builtin_bit_cast(f32x4, __builtin_elementwise_max(__builtin_bit_cast(i32x4_, d), ((i32x4_){0, 0, 0, 0})));
;                         v[tau] = fmaf(w4.w, rl[3], fmaf(w4.z, rl[2], fmaf(w4.y, rl[1], w4.x * rl[0])));
;                     }
;                     const SwapPair r0 = swap32p(v[0], v[2]), r1 = swap32p(v[1], v[3]);
;                     const float a0 = __builtin_bit_cast(float, r0.a) + __builtin_bit_cast(float, r0.b), a1 = __builtin_bit_cast(float, r1.a) + __builtin_bit_cast(float, r1.b);
;                     const SwapPair r2 = swap16p(a0, a1);
;                     const float keep = __builtin_bit_cast(float, r2.a) + __builtin_bit_cast(float, r2.b);
;                     const bool cand = 64 * c + lane <= t;
;                     sc[c] = cand ? keep : -INFINITY; vmax = fmaxf(vmax, sc[c]); vmin = fminf(vmin, cand ? keep : INFINITY);
;                     kp += 64 * 32;
.LBB0_1014:
	s_waitcnt vmcnt(11)
	v_mfma_f32_16x16x32_bf16 v[96:99], v[6:9], v[26:29], 0
	v_lshl_add_u64 v[58:59], v[58:59], 0, s[28:29]
	s_cmp_lt_i32 s16, 29
	s_nop 5
	v_max_i32_e32 v75, 0, v99
	v_max_i32_e32 v76, 0, v98
	v_max_i32_e32 v77, 0, v97
	v_max_i32_e32 v79, 0, v96
	s_waitcnt vmcnt(10)
	v_mfma_f32_16x16x32_bf16 v[96:99], v[6:9], v[30:33], 0
	v_mul_f32_e32 v79, v2, v79
	v_fmac_f32_e32 v79, v3, v77
	v_fmac_f32_e32 v79, v4, v76
	v_fmac_f32_e32 v79, v5, v75
	s_nop 3
	v_max_i32_e32 v75, 0, v99
	v_max_i32_e32 v76, 0, v98
	v_max_i32_e32 v77, 0, v97
	v_max_i32_e32 v87, 0, v96
	s_waitcnt vmcnt(9)
	v_mfma_f32_16x16x32_bf16 v[96:99], v[6:9], v[34:37], 0
	v_mul_f32_e32 v87, v2, v87
	v_fmac_f32_e32 v87, v3, v77
	v_fmac_f32_e32 v87, v4, v76
	v_fmac_f32_e32 v87, v5, v75
	s_nop 3
	v_max_i32_e32 v75, 0, v99
	v_max_i32_e32 v76, 0, v98
	v_max_i32_e32 v77, 0, v97
	v_max_i32_e32 v88, 0, v96
	s_waitcnt vmcnt(8)
	v_mfma_f32_16x16x32_bf16 v[96:99], v[6:9], v[38:41], 0
	v_mul_f32_e32 v88, v2, v88
	v_fmac_f32_e32 v88, v3, v77
	v_fmac_f32_e32 v88, v4, v76
	v_fmac_f32_e32 v88, v5, v75
	s_nop 3
	v_max_i32_e32 v89, 0, v96
	v_max_i32_e32 v77, 0, v97
	v_mul_f32_e32 v89, v2, v89
	v_max_i32_e32 v76, 0, v98
	v_fmac_f32_e32 v89, v3, v77
	v_max_i32_e32 v75, 0, v99
	v_fmac_f32_e32 v89, v4, v76
	v_fmac_f32_e32 v89, v5, v75
	v_permlane32_swap_b32_e32 v79, v88
	s_nop 0
	v_permlane32_swap_b32_e32 v87, v89
	v_add_f32_e32 v75, v79, v88
	v_add_f32_e32 v76, v87, v89
	s_nop 1
	v_permlane16_swap_b32_e32 v75, v76
	s_nop 0
	v_add_co_u32_e32 v38, vcc, 0x2000, v58
	s_nop 1
	v_addc_co_u32_e32 v39, vcc, 0, v59, vcc
	global_load_dwordx4 v[26:29], v[38:39], off
	global_load_dwordx4 v[30:33], v[38:39], off offset:1024
	global_load_dwordx4 v[34:37], v[38:39], off offset:2048
	s_nop 0
	global_load_dwordx4 v[38:41], v[38:39], off offset:3072
.LBB0_1016:
	v_add_f32_e32 v68, v67, v68
	v_or_b32_e32 v67, 0x600, v176
	v_cmp_lt_i32_e32 vcc, s2, v67
	v_add_f32_e32 v70, v69, v70
	v_or_b32_e32 v69, 0x640, v176
	v_cndmask_b32_e32 v67, v68, v206, vcc
	v_cndmask_b32_e32 v68, v68, v207, vcc
	v_cmp_lt_i32_e32 vcc, s2, v69
	s_waitcnt vmcnt(11)
	v_mfma_f32_16x16x32_bf16 v[96:99], v[6:9], v[22:25], 0
	v_lshl_add_u64 v[58:59], v[58:59], 0, s[28:29]
	v_cndmask_b32_e32 v69, v70, v206, vcc
	v_cndmask_b32_e32 v70, v70, v207, vcc
	v_min3_f32 v79, v108, v68, v70
	v_or_b32_e32 v68, 0x680, v176
	v_add_f32_e32 v70, v75, v76
	v_cmp_lt_i32_e32 vcc, s2, v68
	s_nop 0
	v_max_i32_e32 v76, 0, v98
	v_max_i32_e32 v87, 0, v97
	v_cndmask_b32_e32 v68, v70, v206, vcc
	v_cndmask_b32_e32 v75, v70, v207, vcc
	v_max_i32_e32 v70, 0, v99
	v_max_i32_e32 v88, 0, v96
	s_waitcnt vmcnt(10)
	v_mfma_f32_16x16x32_bf16 v[96:99], v[6:9], v[18:21], 0
	v_mul_f32_e32 v88, v2, v88
	v_fmac_f32_e32 v88, v3, v87
	v_fmac_f32_e32 v88, v4, v76
	v_fmac_f32_e32 v88, v5, v70
	v_max3_f32 v77, v107, v67, v69
	s_nop 2
	v_max_i32_e32 v70, 0, v99
	v_max_i32_e32 v76, 0, v98
	v_max_i32_e32 v87, 0, v97
	v_max_i32_e32 v89, 0, v96
	s_waitcnt vmcnt(9)
	v_mfma_f32_16x16x32_bf16 v[96:99], v[6:9], v[14:17], 0
	v_mul_f32_e32 v89, v2, v89
	v_fmac_f32_e32 v89, v3, v87
	v_fmac_f32_e32 v89, v4, v76
	v_fmac_f32_e32 v89, v5, v70
	s_nop 3
	v_max_i32_e32 v70, 0, v99
	v_max_i32_e32 v76, 0, v98
	v_max_i32_e32 v87, 0, v97
	v_max_i32_e32 v90, 0, v96
	s_waitcnt vmcnt(8)
	v_mfma_f32_16x16x32_bf16 v[96:99], v[6:9], v[10:13], 0
	v_mul_f32_e32 v90, v2, v90
	v_fmac_f32_e32 v90, v3, v87
	v_fmac_f32_e32 v90, v4, v76
	v_fmac_f32_e32 v90, v5, v70
	s_nop 3
	v_max_i32_e32 v95, 0, v96
	v_max_i32_e32 v87, 0, v97
	v_mul_f32_e32 v95, v2, v95
	v_max_i32_e32 v76, 0, v98
	v_fmac_f32_e32 v95, v3, v87
	v_max_i32_e32 v70, 0, v99
	v_fmac_f32_e32 v95, v4, v76
	v_fmac_f32_e32 v95, v5, v70
	v_permlane32_swap_b32_e32 v88, v90
	s_nop 0
	v_permlane32_swap_b32_e32 v89, v95
	v_add_f32_e32 v70, v88, v90
	v_add_f32_e32 v76, v89, v95
	s_nop 1
	v_permlane16_swap_b32_e32 v70, v76
	v_add_f32_e32 v76, v70, v76
	v_or_b32_e32 v70, 0x6c0, v176
	v_cmp_lt_i32_e32 vcc, s2, v70
	s_nop 1
	v_cndmask_b32_e32 v70, v76, v206, vcc
	v_cndmask_b32_e32 v76, v76, v207, vcc
	v_max3_f32 v107, v77, v68, v70
	v_min3_f32 v108, v79, v75, v76
	s_branch .LBB0_1018

; __device__ __forceinline__ SwapPair swap32p(float x, float y) { unsigned a = __builtin_bit_cast(unsigned, x), b = __builtin_bit_cast(unsigned, y); asm volatile("" : "+v"(a), "+v"(b)); auto r = __builtin_amdgcn_permlane32_swap(a, b, false, false); return SwapPair{r[0], r[1]}; }
; __device__ __forceinline__ SwapPair swap16p(float x, float y) { unsigned a = __builtin_bit_cast(unsigned, x), b = __builtin_bit_cast(unsigned, y); asm volatile("" : "+v"(a), "+v"(b)); auto r = __builtin_amdgcn_permlane16_swap(a, b, false, false); return SwapPair{r[0], r[1]}; }
; #define MFMA16(a, b, c) __builtin_amdgcn_mfma_f32_16x16x32_bf16((a), (b), (c), 0, 0, 0)
; __device__ __forceinline__ void dsa_token(Frame& F, int b, int t, const bf16* QI, const bf16* KI, const float* WI, const bf16* CKVN, const bf16* QLAT, bf16* OLAT) {
;     ...
;         for (int g4 = 0; g4 < 16; ++g4) {
;             if (4 * g4 <= cmax) {
; #pragma unroll
;                 for (int c = 4 * g4; c < 4 * g4 + 4; ++c) {
;                     asm volatile("" : "+v"(kp));
;                     if (c + 2 < 64) { if (c + 2 <= cmax4) DSA_KLOAD(c + 2, 2); }
;                     float v[4];
; #pragma unroll
;                     for (int tau = 0; tau < 4; ++tau) {
;                         const f32x4 d = MFMA16(qa, kbuf[c % 3][tau], ((f32x4){0.f, 0.f, 0.f, 0.f}));
;                         typedef int i32x4_ __attribute__((ext_vector_type(4)));
;                         const f32x4 rl = __builtin_bit_cast(f32x4, __builtin_elementwise_max(__builtin_bit_cast(i32x4_, d), ((i32x4_){0, 0, 0, 0})));
;                         v[tau] = fmaf(w4.w, rl[3], fmaf(w4.z, rl[2], fmaf(w4.y, rl[1], w4.x * rl[0])));
;                     }
;                     const SwapPair r0 = swap32p(v[0], v[2]), r1 = swap32p(v[1], v[3]);
;                     const float a0 = __builtin_bit_cast(float, r0.a) + __builtin_bit_cast(float, r0.b), a1 = __builtin_bit_cast(float, r1.a) + __builtin_bit_cast(float, r1.b);
;                     const SwapPair r2 = swap16p(a0, a1);
;                     const float keep = __builtin_bit_cast(float, r2.a) + __builtin_bit_cast(float, r2.b);
;                     const bool cand = 64 * c + lane <= t;
;                     sc[c] = cand ? keep : -INFINITY; vmax = fmaxf(vmax, sc[c]); vmin = fminf(vmin, cand ? keep : INFINITY);
;                     kp += 64 * 32;
.LBB0_1018:
	s_cmp_gt_i32 s18, 27
	s_cselect_b64 s[84:85], -1, 0
	s_cmp_lt_i32 s18, 28
	v_mov_b32_e32 v75, 0xff800000
	s_cbranch_scc1 .LBB0_1028
	s_cmp_lt_i32 s16, 30
	s_nop 0
	s_nop 0
	v_add_co_u32_e32 v10, vcc, 0x2000, v58
	s_nop 1
	v_addc_co_u32_e32 v11, vcc, 0, v59, vcc
	global_load_dwordx4 v[22:25], v[10:11], off
	global_load_dwordx4 v[18:21], v[10:11], off offset:1024
	global_load_dwordx4 v[14:17], v[10:11], off offset:2048
	s_nop 0
	global_load_dwordx4 v[10:13], v[10:11], off offset:3072
.LBB0_1021:
	s_waitcnt vmcnt(11)
	v_mfma_f32_16x16x32_bf16 v[96:99], v[6:9], v[42:45], 0
	v_lshl_add_u64 v[58:59], v[58:59], 0, s[28:29]
	s_cmp_lt_i32 s16, 31
	s_nop 5
	v_max_i32_e32 v75, 0, v99
	v_max_i32_e32 v76, 0, v98
	v_max_i32_e32 v77, 0, v97
	v_max_i32_e32 v79, 0, v96
	s_waitcnt vmcnt(10)
	v_mfma_f32_16x16x32_bf16 v[96:99], v[6:9], v[46:49], 0
	v_mul_f32_e32 v79, v2, v79
	v_fmac_f32_e32 v79, v3, v77
	v_fmac_f32_e32 v79, v4, v76
	v_fmac_f32_e32 v79, v5, v75
	s_nop 3
	v_max_i32_e32 v75, 0, v99
	v_max_i32_e32 v76, 0, v98
	v_max_i32_e32 v77, 0, v97
	v_max_i32_e32 v87, 0, v96
	s_waitcnt vmcnt(9)
	v_mfma_f32_16x16x32_bf16 v[96:99], v[6:9], v[50:53], 0
	v_mul_f32_e32 v87, v2, v87
	v_fmac_f32_e32 v87, v3, v77
	v_fmac_f32_e32 v87, v4, v76
	v_fmac_f32_e32 v87, v5, v75
	s_nop 3
	v_max_i32_e32 v75, 0, v99
	v_max_i32_e32 v76, 0, v98
	v_max_i32_e32 v77, 0, v97
	v_max_i32_e32 v88, 0, v96
	s_waitcnt vmcnt(8)
	v_mfma_f32_16x16x32_bf16 v[96:99], v[6:9], v[54:57], 0
	v_mul_f32_e32 v88, v2, v88
	v_fmac_f32_e32 v88, v3, v77
	v_fmac_f32_e32 v88, v4, v76
	v_fmac_f32_e32 v88, v5, v75
	s_nop 3
	v_max_i32_e32 v89, 0, v96
	v_max_i32_e32 v77, 0, v97
	v_mul_f32_e32 v89, v2, v89
	v_max_i32_e32 v76, 0, v98
	v_fmac_f32_e32 v89, v3, v77
	v_max_i32_e32 v75, 0, v99
	v_fmac_f32_e32 v89, v4, v76
	v_fmac_f32_e32 v89, v5, v75
	v_permlane32_swap_b32_e32 v79, v88
	s_nop 0
	v_permlane32_swap_b32_e32 v87, v89
	v_add_f32_e32 v75, v79, v88
	v_add_f32_e32 v76, v87, v89
	s_nop 1
	v_permlane16_swap_b32_e32 v75, v76
	s_nop 0
	v_add_co_u32_e32 v54, vcc, 0x2000, v58
	s_nop 1
	v_addc_co_u32_e32 v55, vcc, 0, v59, vcc
	global_load_dwordx4 v[42:45], v[54:55], off
	global_load_dwordx4 v[46:49], v[54:55], off offset:1024
	global_load_dwordx4 v[50:53], v[54:55], off offset:2048
	s_nop 0
	global_load_dwordx4 v[54:57], v[54:55], off offset:3072
.LBB0_1023:
	s_waitcnt vmcnt(11)
	v_mfma_f32_16x16x32_bf16 v[96:99], v[6:9], v[26:29], 0
	v_lshl_add_u64 v[58:59], v[58:59], 0, s[28:29]
	s_cmp_lt_i32 s16, 32
	s_nop 5
	v_max_i32_e32 v77, 0, v99
	v_max_i32_e32 v79, 0, v98
	v_max_i32_e32 v87, 0, v97
	v_max_i32_e32 v88, 0, v96
	s_waitcnt vmcnt(10)
	v_mfma_f32_16x16x32_bf16 v[96:99], v[6:9], v[30:33], 0
	v_mul_f32_e32 v88, v2, v88
	v_fmac_f32_e32 v88, v3, v87
	v_fmac_f32_e32 v88, v4, v79
	v_fmac_f32_e32 v88, v5, v77
	s_nop 3
	v_max_i32_e32 v77, 0, v99
	v_max_i32_e32 v79, 0, v98
	v_max_i32_e32 v87, 0, v97
	v_max_i32_e32 v89, 0, v96
	s_waitcnt vmcnt(9)
	v_mfma_f32_16x16x32_bf16 v[96:99], v[6:9], v[34:37], 0
	v_mul_f32_e32 v89, v2, v89
	v_fmac_f32_e32 v89, v3, v87
	v_fmac_f32_e32 v89, v4, v79
	v_fmac_f32_e32 v89, v5, v77
	s_nop 3
	v_max_i32_e32 v77, 0, v99
	v_max_i32_e32 v79, 0, v98
	v_max_i32_e32 v87, 0, v97
	v_max_i32_e32 v90, 0, v96
	s_waitcnt vmcnt(8)
	v_mfma_f32_16x16x32_bf16 v[96:99], v[6:9], v[38:41], 0
	v_mul_f32_e32 v90, v2, v90
	v_fmac_f32_e32 v90, v3, v87
	v_fmac_f32_e32 v90, v4, v79
	v_fmac_f32_e32 v90, v5, v77
	s_nop 3
	v_max_i32_e32 v95, 0, v96
	v_max_i32_e32 v87, 0, v97
	v_mul_f32_e32 v95, v2, v95
	v_max_i32_e32 v79, 0, v98
	v_fmac_f32_e32 v95, v3, v87
	v_max_i32_e32 v77, 0, v99
	v_fmac_f32_e32 v95, v4, v79
	v_fmac_f32_e32 v95, v5, v77
	v_permlane32_swap_b32_e32 v88, v90
	s_nop 0
	v_permlane32_swap_b32_e32 v89, v95
	v_add_f32_e32 v77, v88, v90
	v_add_f32_e32 v79, v89, v95
	s_nop 1
	v_permlane16_swap_b32_e32 v77, v79
	s_nop 0
	v_add_co_u32_e32 v38, vcc, 0x2000, v58
	s_nop 1
	v_addc_co_u32_e32 v39, vcc, 0, v59, vcc
	global_load_dwordx4 v[26:29], v[38:39], off
	global_load_dwordx4 v[30:33], v[38:39], off offset:1024
	global_load_dwordx4 v[34:37], v[38:39], off offset:2048
	s_nop 0
	global_load_dwordx4 v[38:41], v[38:39], off offset:3072
; __device__ __forceinline__ SwapPair swap32p(float x, float y) { unsigned a = __builtin_bit_cast(unsigned, x), b = __builtin_bit_cast(unsigned, y); asm volatile("" : "+v"(a), "+v"(b)); auto r = __builtin_amdgcn_permlane32_swap(a, b, false, false); return SwapPair{r[0], r[1]}; }
; __device__ __forceinline__ SwapPair swap16p(float x, float y) { unsigned a = __builtin_bit_cast(unsigned, x), b = __builtin_bit_cast(unsigned, y); asm volatile("" : "+v"(a), "+v"(b)); auto r = __builtin_amdgcn_permlane16_swap(a, b, false, false); return SwapPair{r[0], r[1]}; }
; #define MFMA16(a, b, c) __builtin_amdgcn_mfma_f32_16x16x32_bf16((a), (b), (c), 0, 0, 0)
; __device__ __forceinline__ void dsa_token(Frame& F, int b, int t, const bf16* QI, const bf16* KI, const float* WI, const bf16* CKVN, const bf16* QLAT, bf16* OLAT) {
;     ...
;         for (int g4 = 0; g4 < 16; ++g4) {
;             if (4 * g4 <= cmax) {
; #pragma unroll
;                 for (int c = 4 * g4; c < 4 * g4 + 4; ++c) {
;                     asm volatile("" : "+v"(kp));
;                     if (c + 2 < 64) { if (c + 2 <= cmax4) DSA_KLOAD(c + 2, 2); }
;                     float v[4];
; #pragma unroll
;                     for (int tau = 0; tau < 4; ++tau) {
;                         const f32x4 d = MFMA16(qa, kbuf[c % 3][tau], ((f32x4){0.f, 0.f, 0.f, 0.f}));
;                         typedef int i32x4_ __attribute__((ext_vector_type(4)));
;                         const f32x4 rl = __builtin_bit_cast(f32x4, __builtin_elementwise_max(__builtin_bit_cast(i32x4_, d), ((i32x4_){0, 0, 0, 0})));
;                         v[tau] = fmaf(w4.w, rl[3], fmaf(w4.z, rl[2], fmaf(w4.y, rl[1], w4.x * rl[0])));
;                     }
;                     const SwapPair r0 = swap32p(v[0], v[2]), r1 = swap32p(v[1], v[3]);
;                     const float a0 = __builtin_bit_cast(float, r0.a) + __builtin_bit_cast(float, r0.b), a1 = __builtin_bit_cast(float, r1.a) + __builtin_bit_cast(float, r1.b);
;                     const SwapPair r2 = swap16p(a0, a1);
;                     const float keep = __builtin_bit_cast(float, r2.a) + __builtin_bit_cast(float, r2.b);
;                     const bool cand = 64 * c + lane <= t;
;                     sc[c] = cand ? keep : -INFINITY; vmax = fmaxf(vmax, sc[c]); vmin = fminf(vmin, cand ? keep : INFINITY);
;                     kp += 64 * 32;
.LBB0_1025:
	s_waitcnt vmcnt(11)
	v_mfma_f32_16x16x32_bf16 v[96:99], v[6:9], v[22:25], 0
	v_lshl_add_u64 v[58:59], v[58:59], 0, s[28:29]
	s_cmp_lt_i32 s16, 33
	s_nop 5
	v_max_i32_e32 v87, 0, v99
	v_max_i32_e32 v88, 0, v98
	v_max_i32_e32 v89, 0, v97
	v_max_i32_e32 v90, 0, v96
	s_waitcnt vmcnt(10)
	v_mfma_f32_16x16x32_bf16 v[96:99], v[6:9], v[18:21], 0
	v_mul_f32_e32 v90, v2, v90
	v_fmac_f32_e32 v90, v3, v89
	v_fmac_f32_e32 v90, v4, v88
	v_fmac_f32_e32 v90, v5, v87
	s_nop 3
	v_max_i32_e32 v87, 0, v99
	v_max_i32_e32 v88, 0, v98
	v_max_i32_e32 v89, 0, v97
	v_max_i32_e32 v95, 0, v96
	s_waitcnt vmcnt(9)
	v_mfma_f32_16x16x32_bf16 v[96:99], v[6:9], v[14:17], 0
	v_mul_f32_e32 v95, v2, v95
	v_fmac_f32_e32 v95, v3, v89
	v_fmac_f32_e32 v95, v4, v88
	v_fmac_f32_e32 v95, v5, v87
	s_nop 3
	v_max_i32_e32 v96, 0, v96
	v_max_i32_e32 v87, 0, v99
	v_max_i32_e32 v88, 0, v98
	v_max_i32_e32 v89, 0, v97
	v_mul_f32_e32 v100, v2, v96
	s_waitcnt vmcnt(8)
	v_mfma_f32_16x16x32_bf16 v[96:99], v[6:9], v[10:13], 0
	v_fmac_f32_e32 v100, v3, v89
	v_fmac_f32_e32 v100, v4, v88
	v_fmac_f32_e32 v100, v5, v87
	s_nop 1
	v_permlane32_swap_b32_e32 v90, v100
	s_nop 1
	v_max_i32_e32 v96, 0, v96
	v_max_i32_e32 v89, 0, v97
	v_mul_f32_e32 v96, v2, v96
	v_max_i32_e32 v88, 0, v98
	v_fmac_f32_e32 v96, v3, v89
	v_max_i32_e32 v87, 0, v99
	v_fmac_f32_e32 v96, v4, v88
	v_fmac_f32_e32 v96, v5, v87
	v_add_f32_e32 v87, v90, v100
	s_nop 0
	v_permlane32_swap_b32_e32 v95, v96
	v_add_f32_e32 v88, v95, v96
	s_nop 1
	v_permlane16_swap_b32_e32 v87, v88
	s_nop 0
	v_add_co_u32_e32 v10, vcc, 0x2000, v58
	s_nop 1
	v_addc_co_u32_e32 v11, vcc, 0, v59, vcc
	global_load_dwordx4 v[22:25], v[10:11], off
	global_load_dwordx4 v[18:21], v[10:11], off offset:1024
	global_load_dwordx4 v[14:17], v[10:11], off offset:2048
	s_nop 0
	global_load_dwordx4 v[10:13], v[10:11], off offset:3072
.LBB0_1027:
	v_add_f32_e32 v76, v75, v76
	v_or_b32_e32 v75, 0x700, v176
	v_cmp_lt_i32_e32 vcc, s2, v75
	v_add_f32_e32 v79, v77, v79
	v_or_b32_e32 v77, 0x740, v176
	s_waitcnt vmcnt(11)
	v_mfma_f32_16x16x32_bf16 v[96:99], v[6:9], v[42:45], 0
	v_cndmask_b32_e32 v75, v76, v206, vcc
	v_cndmask_b32_e32 v76, v76, v207, vcc
	v_cmp_lt_i32_e32 vcc, s2, v77
	v_lshl_add_u64 v[58:59], v[58:59], 0, s[28:29]
	s_nop 0
	v_cndmask_b32_e32 v77, v79, v206, vcc
	v_cndmask_b32_e32 v79, v79, v207, vcc
	v_min3_f32 v90, v108, v76, v79
	v_or_b32_e32 v76, 0x780, v176
	v_add_f32_e32 v79, v87, v88
	v_cmp_lt_i32_e32 vcc, s2, v76
	v_max_i32_e32 v96, 0, v96
	v_max_i32_e32 v88, 0, v98
	v_cndmask_b32_e32 v76, v79, v206, vcc
	v_cndmask_b32_e32 v87, v79, v207, vcc
	v_max_i32_e32 v79, 0, v99
	v_max_i32_e32 v95, 0, v97
	v_mul_f32_e32 v100, v2, v96
	s_waitcnt vmcnt(10)
	v_mfma_f32_16x16x32_bf16 v[96:99], v[6:9], v[46:49], 0
	v_fmac_f32_e32 v100, v3, v95
	v_fmac_f32_e32 v100, v4, v88
	v_fmac_f32_e32 v100, v5, v79
	v_max3_f32 v89, v107, v75, v77
	s_nop 3
	v_max_i32_e32 v96, 0, v96
	v_max_i32_e32 v79, 0, v99
	v_max_i32_e32 v88, 0, v98
	v_max_i32_e32 v95, 0, v97
	v_mul_f32_e32 v101, v2, v96
	s_waitcnt vmcnt(9)
	v_mfma_f32_16x16x32_bf16 v[96:99], v[6:9], v[50:53], 0
	v_fmac_f32_e32 v101, v3, v95
	v_fmac_f32_e32 v101, v4, v88
	v_fmac_f32_e32 v101, v5, v79
	s_nop 4
	v_max_i32_e32 v96, 0, v96
	v_max_i32_e32 v79, 0, v99
	v_max_i32_e32 v88, 0, v98
	v_max_i32_e32 v95, 0, v97
	v_mul_f32_e32 v102, v2, v96
	s_waitcnt vmcnt(8)
	v_mfma_f32_16x16x32_bf16 v[96:99], v[6:9], v[54:57], 0
	v_fmac_f32_e32 v102, v3, v95
	v_fmac_f32_e32 v102, v4, v88
	v_fmac_f32_e32 v102, v5, v79
	s_nop 1
	v_permlane32_swap_b32_e32 v100, v102
	s_nop 1
	v_max_i32_e32 v96, 0, v96
	v_max_i32_e32 v95, 0, v97
	v_mul_f32_e32 v96, v2, v96
	v_max_i32_e32 v88, 0, v98
	v_fmac_f32_e32 v96, v3, v95
	v_max_i32_e32 v79, 0, v99
	v_fmac_f32_e32 v96, v4, v88
	v_fmac_f32_e32 v96, v5, v79
	v_add_f32_e32 v79, v100, v102
	s_nop 0
	v_permlane32_swap_b32_e32 v101, v96
	v_add_f32_e32 v88, v101, v96
	s_nop 1
	v_permlane16_swap_b32_e32 v79, v88
	v_add_f32_e32 v88, v79, v88
	v_or_b32_e32 v79, 0x7c0, v176
	v_cmp_lt_i32_e32 vcc, s2, v79
	s_nop 1
	v_cndmask_b32_e32 v79, v88, v206, vcc
	v_cndmask_b32_e32 v88, v88, v207, vcc
	v_max3_f32 v107, v89, v76, v79
	v_min3_f32 v108, v90, v87, v88
	s_branch .LBB0_1029

; __device__ __forceinline__ SwapPair swap32p(float x, float y) { unsigned a = __builtin_bit_cast(unsigned, x), b = __builtin_bit_cast(unsigned, y); asm volatile("" : "+v"(a), "+v"(b)); auto r = __builtin_amdgcn_permlane32_swap(a, b, false, false); return SwapPair{r[0], r[1]}; }
; __device__ __forceinline__ SwapPair swap16p(float x, float y) { unsigned a = __builtin_bit_cast(unsigned, x), b = __builtin_bit_cast(unsigned, y); asm volatile("" : "+v"(a), "+v"(b)); auto r = __builtin_amdgcn_permlane16_swap(a, b, false, false); return SwapPair{r[0], r[1]}; }
; #define MFMA16(a, b, c) __builtin_amdgcn_mfma_f32_16x16x32_bf16((a), (b), (c), 0, 0, 0)
; __device__ __forceinline__ void dsa_token(Frame& F, int b, int t, const bf16* QI, const bf16* KI, const float* WI, const bf16* CKVN, const bf16* QLAT, bf16* OLAT) {
;     ...
;         for (int g4 = 0; g4 < 16; ++g4) {
;             if (4 * g4 <= cmax) {
; #pragma unroll
;                 for (int c = 4 * g4; c < 4 * g4 + 4; ++c) {
;                     asm volatile("" : "+v"(kp));
;                     if (c + 2 < 64) { if (c + 2 <= cmax4) DSA_KLOAD(c + 2, 2); }
;                     float v[4];
; #pragma unroll
;                     for (int tau = 0; tau < 4; ++tau) {
;                         const f32x4 d = MFMA16(qa, kbuf[c % 3][tau], ((f32x4){0.f, 0.f, 0.f, 0.f}));
;                         typedef int i32x4_ __attribute__((ext_vector_type(4)));
;                         const f32x4 rl = __builtin_bit_cast(f32x4, __builtin_elementwise_max(__builtin_bit_cast(i32x4_, d), ((i32x4_){0, 0, 0, 0})));
;                         v[tau] = fmaf(w4.w, rl[3], fmaf(w4.z, rl[2], fmaf(w4.y, rl[1], w4.x * rl[0])));
;                     }
;                     const SwapPair r0 = swap32p(v[0], v[2]), r1 = swap32p(v[1], v[3]);
;                     const float a0 = __builtin_bit_cast(float, r0.a) + __builtin_bit_cast(float, r0.b), a1 = __builtin_bit_cast(float, r1.a) + __builtin_bit_cast(float, r1.b);
;                     const SwapPair r2 = swap16p(a0, a1);
;                     const float keep = __builtin_bit_cast(float, r2.a) + __builtin_bit_cast(float, r2.b);
;                     const bool cand = 64 * c + lane <= t;
;                     sc[c] = cand ? keep : -INFINITY; vmax = fmaxf(vmax, sc[c]); vmin = fminf(vmin, cand ? keep : INFINITY);
;                     kp += 64 * 32;
.LBB0_1029:
	s_cmp_gt_i32 s18, 31
	s_cselect_b64 s[6:7], -1, 0
	s_cmp_lt_i32 s18, 32
	v_mov_b32_e32 v87, 0xff800000
	s_cbranch_scc1 .LBB0_1039
	s_cmp_lt_i32 s16, 34
	s_nop 0
	s_nop 0
	v_add_co_u32_e32 v54, vcc, 0x2000, v58
	s_nop 1
	v_addc_co_u32_e32 v55, vcc, 0, v59, vcc
	global_load_dwordx4 v[42:45], v[54:55], off
	global_load_dwordx4 v[46:49], v[54:55], off offset:1024
	global_load_dwordx4 v[50:53], v[54:55], off offset:2048
	s_nop 0
	global_load_dwordx4 v[54:57], v[54:55], off offset:3072
.LBB0_1032:
	s_waitcnt vmcnt(11)
	v_mfma_f32_16x16x32_bf16 v[96:99], v[6:9], v[26:29], 0
	v_lshl_add_u64 v[58:59], v[58:59], 0, s[28:29]
	s_cmp_lt_i32 s16, 35
	s_nop 5
	v_max_i32_e32 v87, 0, v99
	v_max_i32_e32 v88, 0, v98
	v_max_i32_e32 v89, 0, v97
	v_max_i32_e32 v90, 0, v96
	s_waitcnt vmcnt(10)
	v_mfma_f32_16x16x32_bf16 v[96:99], v[6:9], v[30:33], 0
	v_mul_f32_e32 v90, v2, v90
	v_fmac_f32_e32 v90, v3, v89
	v_fmac_f32_e32 v90, v4, v88
	v_fmac_f32_e32 v90, v5, v87
	s_nop 3
	v_max_i32_e32 v87, 0, v99
	v_max_i32_e32 v88, 0, v98
	v_max_i32_e32 v89, 0, v97
	v_max_i32_e32 v95, 0, v96
	s_waitcnt vmcnt(9)
	v_mfma_f32_16x16x32_bf16 v[96:99], v[6:9], v[34:37], 0
	v_mul_f32_e32 v95, v2, v95
	v_fmac_f32_e32 v95, v3, v89
	v_fmac_f32_e32 v95, v4, v88
	v_fmac_f32_e32 v95, v5, v87
	s_nop 3
	v_max_i32_e32 v96, 0, v96
	v_max_i32_e32 v87, 0, v99
	v_max_i32_e32 v88, 0, v98
	v_max_i32_e32 v89, 0, v97
	v_mul_f32_e32 v100, v2, v96
	s_waitcnt vmcnt(8)
	v_mfma_f32_16x16x32_bf16 v[96:99], v[6:9], v[38:41], 0
	v_fmac_f32_e32 v100, v3, v89
	v_fmac_f32_e32 v100, v4, v88
	v_fmac_f32_e32 v100, v5, v87
	s_nop 1
	v_permlane32_swap_b32_e32 v90, v100
	s_nop 1
	v_max_i32_e32 v96, 0, v96
	v_max_i32_e32 v89, 0, v97
	v_mul_f32_e32 v96, v2, v96
	v_max_i32_e32 v88, 0, v98
	v_fmac_f32_e32 v96, v3, v89
	v_max_i32_e32 v87, 0, v99
	v_fmac_f32_e32 v96, v4, v88
	v_fmac_f32_e32 v96, v5, v87
	v_add_f32_e32 v87, v90, v100
	s_nop 0
	v_permlane32_swap_b32_e32 v95, v96
	v_add_f32_e32 v88, v95, v96
	s_nop 1
	v_permlane16_swap_b32_e32 v87, v88
	s_nop 0
	v_add_co_u32_e32 v38, vcc, 0x2000, v58
	s_nop 1
	v_addc_co_u32_e32 v39, vcc, 0, v59, vcc
	global_load_dwordx4 v[26:29], v[38:39], off
	global_load_dwordx4 v[30:33], v[38:39], off offset:1024
	global_load_dwordx4 v[34:37], v[38:39], off offset:2048
	s_nop 0
	global_load_dwordx4 v[38:41], v[38:39], off offset:3072
.LBB0_1034:
	s_waitcnt vmcnt(11)
	v_mfma_f32_16x16x32_bf16 v[96:99], v[6:9], v[22:25], 0
	v_lshl_add_u64 v[58:59], v[58:59], 0, s[28:29]
	s_cmp_lt_i32 s16, 36
	s_nop 5
	v_max_i32_e32 v96, 0, v96
	v_max_i32_e32 v89, 0, v99
	v_max_i32_e32 v90, 0, v98
	v_max_i32_e32 v95, 0, v97
	v_mul_f32_e32 v100, v2, v96
	s_waitcnt vmcnt(10)
	v_mfma_f32_16x16x32_bf16 v[96:99], v[6:9], v[18:21], 0
	v_fmac_f32_e32 v100, v3, v95
	v_fmac_f32_e32 v100, v4, v90
	v_fmac_f32_e32 v100, v5, v89
	s_nop 4
	v_max_i32_e32 v96, 0, v96
	v_max_i32_e32 v89, 0, v99
	v_max_i32_e32 v90, 0, v98
	v_max_i32_e32 v95, 0, v97
	v_mul_f32_e32 v101, v2, v96
	s_waitcnt vmcnt(9)
	v_mfma_f32_16x16x32_bf16 v[96:99], v[6:9], v[14:17], 0
	v_fmac_f32_e32 v101, v3, v95
	v_fmac_f32_e32 v101, v4, v90
	v_fmac_f32_e32 v101, v5, v89
	s_nop 4
	v_max_i32_e32 v96, 0, v96
	v_max_i32_e32 v89, 0, v99
	v_max_i32_e32 v90, 0, v98
	v_max_i32_e32 v95, 0, v97
	v_mul_f32_e32 v102, v2, v96
	s_waitcnt vmcnt(8)
	v_mfma_f32_16x16x32_bf16 v[96:99], v[6:9], v[10:13], 0
	v_fmac_f32_e32 v102, v3, v95
	v_fmac_f32_e32 v102, v4, v90
	v_fmac_f32_e32 v102, v5, v89
	s_nop 1
	v_permlane32_swap_b32_e32 v100, v102
	s_nop 1
	v_max_i32_e32 v96, 0, v96
	v_max_i32_e32 v95, 0, v97
	v_mul_f32_e32 v96, v2, v96
	v_max_i32_e32 v90, 0, v98
	v_fmac_f32_e32 v96, v3, v95
	v_max_i32_e32 v89, 0, v99
	v_fmac_f32_e32 v96, v4, v90
	v_fmac_f32_e32 v96, v5, v89
	v_add_f32_e32 v89, v100, v102
	s_nop 0
	v_permlane32_swap_b32_e32 v101, v96
	v_add_f32_e32 v90, v101, v96
	s_nop 1
	v_permlane16_swap_b32_e32 v89, v90
	s_nop 0
	v_add_co_u32_e32 v10, vcc, 0x2000, v58
	s_nop 1
	v_addc_co_u32_e32 v11, vcc, 0, v59, vcc
	global_load_dwordx4 v[22:25], v[10:11], off
	global_load_dwordx4 v[18:21], v[10:11], off offset:1024
	global_load_dwordx4 v[14:17], v[10:11], off offset:2048
	s_nop 0
	global_load_dwordx4 v[10:13], v[10:11], off offset:3072
; __device__ __forceinline__ SwapPair swap32p(float x, float y) { unsigned a = __builtin_bit_cast(unsigned, x), b = __builtin_bit_cast(unsigned, y); asm volatile("" : "+v"(a), "+v"(b)); auto r = __builtin_amdgcn_permlane32_swap(a, b, false, false); return SwapPair{r[0], r[1]}; }
; __device__ __forceinline__ SwapPair swap16p(float x, float y) { unsigned a = __builtin_bit_cast(unsigned, x), b = __builtin_bit_cast(unsigned, y); asm volatile("" : "+v"(a), "+v"(b)); auto r = __builtin_amdgcn_permlane16_swap(a, b, false, false); return SwapPair{r[0], r[1]}; }
; #define MFMA16(a, b, c) __builtin_amdgcn_mfma_f32_16x16x32_bf16((a), (b), (c), 0, 0, 0)
; __device__ __forceinline__ void dsa_token(Frame& F, int b, int t, const bf16* QI, const bf16* KI, const float* WI, const bf16* CKVN, const bf16* QLAT, bf16* OLAT) {
;     ...
;         for (int g4 = 0; g4 < 16; ++g4) {
;             if (4 * g4 <= cmax) {
; #pragma unroll
;                 for (int c = 4 * g4; c < 4 * g4 + 4; ++c) {
;                     asm volatile("" : "+v"(kp));
;                     if (c + 2 < 64) { if (c + 2 <= cmax4) DSA_KLOAD(c + 2, 2); }
;                     float v[4];
; #pragma unroll
;                     for (int tau = 0; tau < 4; ++tau) {
;                         const f32x4 d = MFMA16(qa, kbuf[c % 3][tau], ((f32x4){0.f, 0.f, 0.f, 0.f}));
;                         typedef int i32x4_ __attribute__((ext_vector_type(4)));
;                         const f32x4 rl = __builtin_bit_cast(f32x4, __builtin_elementwise_max(__builtin_bit_cast(i32x4_, d), ((i32x4_){0, 0, 0, 0})));
;                         v[tau] = fmaf(w4.w, rl[3], fmaf(w4.z, rl[2], fmaf(w4.y, rl[1], w4.x * rl[0])));
;                     }
;                     const SwapPair r0 = swap32p(v[0], v[2]), r1 = swap32p(v[1], v[3]);
;                     const float a0 = __builtin_bit_cast(float, r0.a) + __builtin_bit_cast(float, r0.b), a1 = __builtin_bit_cast(float, r1.a) + __builtin_bit_cast(float, r1.b);
;                     const SwapPair r2 = swap16p(a0, a1);
;                     const float keep = __builtin_bit_cast(float, r2.a) + __builtin_bit_cast(float, r2.b);
;                     const bool cand = 64 * c + lane <= t;
;                     sc[c] = cand ? keep : -INFINITY; vmax = fmaxf(vmax, sc[c]); vmin = fminf(vmin, cand ? keep : INFINITY);
;                     kp += 64 * 32;
.LBB0_1036:
	s_waitcnt vmcnt(11)
	v_mfma_f32_16x16x32_bf16 v[96:99], v[6:9], v[42:45], 0
	v_lshl_add_u64 v[58:59], v[58:59], 0, s[28:29]
	s_cmp_lt_i32 s16, 37
	s_nop 5
	v_max_i32_e32 v96, 0, v96
	v_max_i32_e32 v97, 0, v97
	v_mul_f32_e32 v100, v2, v96
	v_max_i32_e32 v98, 0, v98
	v_fmac_f32_e32 v100, v3, v97
	v_max_i32_e32 v95, 0, v99
	v_fmac_f32_e32 v100, v4, v98
	s_waitcnt vmcnt(10)
	v_mfma_f32_16x16x32_bf16 v[96:99], v[6:9], v[46:49], 0
	v_fmac_f32_e32 v100, v5, v95
	s_nop 6
	v_max_i32_e32 v96, 0, v96
	v_max_i32_e32 v97, 0, v97
	v_mul_f32_e32 v101, v2, v96
	v_max_i32_e32 v98, 0, v98
	v_fmac_f32_e32 v101, v3, v97
	v_max_i32_e32 v95, 0, v99
	v_fmac_f32_e32 v101, v4, v98
	s_waitcnt vmcnt(9)
	v_mfma_f32_16x16x32_bf16 v[96:99], v[6:9], v[50:53], 0
	v_fmac_f32_e32 v101, v5, v95
	s_nop 6
	v_max_i32_e32 v96, 0, v96
	v_max_i32_e32 v97, 0, v97
	v_mul_f32_e32 v102, v2, v96
	v_max_i32_e32 v98, 0, v98
	v_fmac_f32_e32 v102, v3, v97
	v_max_i32_e32 v95, 0, v99
	v_fmac_f32_e32 v102, v4, v98
	s_waitcnt vmcnt(8)
	v_mfma_f32_16x16x32_bf16 v[96:99], v[6:9], v[54:57], 0
	v_fmac_f32_e32 v102, v5, v95
	s_nop 1
	v_permlane32_swap_b32_e32 v100, v102
	s_nop 3
	v_max_i32_e32 v96, 0, v96
	v_max_i32_e32 v97, 0, v97
	v_mul_f32_e32 v96, v2, v96
	v_max_i32_e32 v98, 0, v98
	v_fmac_f32_e32 v96, v3, v97
	v_max_i32_e32 v95, 0, v99
	v_fmac_f32_e32 v96, v4, v98
	v_fmac_f32_e32 v96, v5, v95
	v_add_f32_e32 v95, v100, v102
	s_nop 0
	v_permlane32_swap_b32_e32 v101, v96
	v_add_f32_e32 v96, v101, v96
	s_nop 1
	v_permlane16_swap_b32_e32 v95, v96
	s_nop 0
	v_add_co_u32_e32 v54, vcc, 0x2000, v58
	s_nop 1
	v_addc_co_u32_e32 v55, vcc, 0, v59, vcc
	global_load_dwordx4 v[42:45], v[54:55], off
	global_load_dwordx4 v[46:49], v[54:55], off offset:1024
	global_load_dwordx4 v[50:53], v[54:55], off offset:2048
	s_nop 0
	global_load_dwordx4 v[54:57], v[54:55], off offset:3072
.LBB0_1038:
	v_add_f32_e32 v88, v87, v88
	v_or_b32_e32 v87, 0x800, v176
	v_cmp_lt_i32_e32 vcc, s2, v87
	v_add_f32_e32 v90, v89, v90
	v_or_b32_e32 v89, 0x840, v176
	v_cndmask_b32_e32 v87, v88, v206, vcc
	v_cndmask_b32_e32 v88, v88, v207, vcc
	v_cmp_lt_i32_e32 vcc, s2, v89
	v_lshl_add_u64 v[58:59], v[58:59], 0, s[28:29]
	s_nop 0
	v_cndmask_b32_e32 v89, v90, v206, vcc
	v_cndmask_b32_e32 v90, v90, v207, vcc
	v_min3_f32 v101, v108, v88, v90
	v_add_f32_e32 v90, v95, v96
	s_waitcnt vmcnt(11)
	v_mfma_f32_16x16x32_bf16 v[96:99], v[6:9], v[26:29], 0
	v_or_b32_e32 v88, 0x880, v176
	v_cmp_lt_i32_e32 vcc, s2, v88
	v_max3_f32 v100, v107, v87, v89
	s_nop 0
	v_cndmask_b32_e32 v88, v90, v206, vcc
	s_nop 2
	v_max_i32_e32 v96, 0, v96
	v_max_i32_e32 v97, 0, v97
	v_mul_f32_e32 v102, v2, v96
	v_max_i32_e32 v98, 0, v98
	v_fmac_f32_e32 v102, v3, v97
	v_cndmask_b32_e32 v95, v90, v207, vcc
	v_max_i32_e32 v90, 0, v99
	v_fmac_f32_e32 v102, v4, v98
	s_waitcnt vmcnt(10)
	v_mfma_f32_16x16x32_bf16 v[96:99], v[6:9], v[30:33], 0
	v_fmac_f32_e32 v102, v5, v90
	s_nop 6
	v_max_i32_e32 v96, 0, v96
	v_max_i32_e32 v97, 0, v97
	v_mul_f32_e32 v103, v2, v96
	v_max_i32_e32 v98, 0, v98
	v_fmac_f32_e32 v103, v3, v97
	v_max_i32_e32 v90, 0, v99
	v_fmac_f32_e32 v103, v4, v98
	s_waitcnt vmcnt(9)
	v_mfma_f32_16x16x32_bf16 v[96:99], v[6:9], v[34:37], 0
	v_fmac_f32_e32 v103, v5, v90
	s_nop 6
	v_max_i32_e32 v96, 0, v96
	v_max_i32_e32 v97, 0, v97
	v_mul_f32_e32 v104, v2, v96
	v_max_i32_e32 v98, 0, v98
	v_fmac_f32_e32 v104, v3, v97
	v_max_i32_e32 v90, 0, v99
	v_fmac_f32_e32 v104, v4, v98
	s_waitcnt vmcnt(8)
	v_mfma_f32_16x16x32_bf16 v[96:99], v[6:9], v[38:41], 0
	v_fmac_f32_e32 v104, v5, v90
	s_nop 1
	v_permlane32_swap_b32_e32 v102, v104
	s_nop 3
	v_max_i32_e32 v96, 0, v96
	v_max_i32_e32 v97, 0, v97
	v_mul_f32_e32 v96, v2, v96
	v_max_i32_e32 v98, 0, v98
	v_fmac_f32_e32 v96, v3, v97
	v_max_i32_e32 v90, 0, v99
	v_fmac_f32_e32 v96, v4, v98
	v_fmac_f32_e32 v96, v5, v90
	v_add_f32_e32 v90, v102, v104
	s_nop 0
	v_permlane32_swap_b32_e32 v103, v96
	v_add_f32_e32 v96, v103, v96
	s_nop 1
	v_permlane16_swap_b32_e32 v90, v96
	v_add_f32_e32 v96, v90, v96
	v_or_b32_e32 v90, 0x8c0, v176
	v_cmp_lt_i32_e32 vcc, s2, v90
	s_nop 1
	v_cndmask_b32_e32 v90, v96, v206, vcc
	v_cndmask_b32_e32 v96, v96, v207, vcc
	v_max3_f32 v107, v100, v88, v90
	v_min3_f32 v108, v101, v95, v96
	s_branch .LBB0_1040

; __device__ __forceinline__ SwapPair swap32p(float x, float y) { unsigned a = __builtin_bit_cast(unsigned, x), b = __builtin_bit_cast(unsigned, y); asm volatile("" : "+v"(a), "+v"(b)); auto r = __builtin_amdgcn_permlane32_swap(a, b, false, false); return SwapPair{r[0], r[1]}; }
; __device__ __forceinline__ SwapPair swap16p(float x, float y) { unsigned a = __builtin_bit_cast(unsigned, x), b = __builtin_bit_cast(unsigned, y); asm volatile("" : "+v"(a), "+v"(b)); auto r = __builtin_amdgcn_permlane16_swap(a, b, false, false); return SwapPair{r[0], r[1]}; }
; #define MFMA16(a, b, c) __builtin_amdgcn_mfma_f32_16x16x32_bf16((a), (b), (c), 0, 0, 0)
; __device__ __forceinline__ void dsa_token(Frame& F, int b, int t, const bf16* QI, const bf16* KI, const float* WI, const bf16* CKVN, const bf16* QLAT, bf16* OLAT) {
;     ...
;         for (int g4 = 0; g4 < 16; ++g4) {
;             if (4 * g4 <= cmax) {
; #pragma unroll
;                 for (int c = 4 * g4; c < 4 * g4 + 4; ++c) {
;                     asm volatile("" : "+v"(kp));
;                     if (c + 2 < 64) { if (c + 2 <= cmax4) DSA_KLOAD(c + 2, 2); }
;                     float v[4];
; #pragma unroll
;                     for (int tau = 0; tau < 4; ++tau) {
;                         const f32x4 d = MFMA16(qa, kbuf[c % 3][tau], ((f32x4){0.f, 0.f, 0.f, 0.f}));
;                         typedef int i32x4_ __attribute__((ext_vector_type(4)));
;                         const f32x4 rl = __builtin_bit_cast(f32x4, __builtin_elementwise_max(__builtin_bit_cast(i32x4_, d), ((i32x4_){0, 0, 0, 0})));
;                         v[tau] = fmaf(w4.w, rl[3], fmaf(w4.z, rl[2], fmaf(w4.y, rl[1], w4.x * rl[0])));
;                     }
;                     const SwapPair r0 = swap32p(v[0], v[2]), r1 = swap32p(v[1], v[3]);
;                     const float a0 = __builtin_bit_cast(float, r0.a) + __builtin_bit_cast(float, r0.b), a1 = __builtin_bit_cast(float, r1.a) + __builtin_bit_cast(float, r1.b);
;                     const SwapPair r2 = swap16p(a0, a1);
;                     const float keep = __builtin_bit_cast(float, r2.a) + __builtin_bit_cast(float, r2.b);
;                     const bool cand = 64 * c + lane <= t;
;                     sc[c] = cand ? keep : -INFINITY; vmax = fmaxf(vmax, sc[c]); vmin = fminf(vmin, cand ? keep : INFINITY);
;                     kp += 64 * 32;
.LBB0_1040:
	s_cmp_gt_i32 s18, 35
	s_cselect_b64 s[10:11], -1, 0
	s_cmp_lt_i32 s18, 36
	v_mov_b32_e32 v95, 0xff800000
	s_cbranch_scc1 .LBB0_1050
	s_cmp_lt_i32 s16, 38
	s_nop 0
	s_nop 0
	v_add_co_u32_e32 v38, vcc, 0x2000, v58
	s_nop 1
	v_addc_co_u32_e32 v39, vcc, 0, v59, vcc
	global_load_dwordx4 v[26:29], v[38:39], off
	global_load_dwordx4 v[30:33], v[38:39], off offset:1024
	global_load_dwordx4 v[34:37], v[38:39], off offset:2048
	s_nop 0
	global_load_dwordx4 v[38:41], v[38:39], off offset:3072
.LBB0_1043:
	s_waitcnt vmcnt(11)
	v_mfma_f32_16x16x32_bf16 v[96:99], v[6:9], v[22:25], 0
	v_lshl_add_u64 v[58:59], v[58:59], 0, s[28:29]
	s_cmp_lt_i32 s16, 39
	s_nop 5
	v_max_i32_e32 v96, 0, v96
	v_max_i32_e32 v97, 0, v97
	v_mul_f32_e32 v100, v2, v96
	v_max_i32_e32 v98, 0, v98
	v_fmac_f32_e32 v100, v3, v97
	v_max_i32_e32 v95, 0, v99
	v_fmac_f32_e32 v100, v4, v98
	s_waitcnt vmcnt(10)
	v_mfma_f32_16x16x32_bf16 v[96:99], v[6:9], v[18:21], 0
	v_fmac_f32_e32 v100, v5, v95
	s_nop 6
	v_max_i32_e32 v96, 0, v96
	v_max_i32_e32 v97, 0, v97
	v_mul_f32_e32 v101, v2, v96
	v_max_i32_e32 v98, 0, v98
	v_fmac_f32_e32 v101, v3, v97
	v_max_i32_e32 v95, 0, v99
	v_fmac_f32_e32 v101, v4, v98
	s_waitcnt vmcnt(9)
	v_mfma_f32_16x16x32_bf16 v[96:99], v[6:9], v[14:17], 0
	v_fmac_f32_e32 v101, v5, v95
	s_nop 6
	v_max_i32_e32 v96, 0, v96
	v_max_i32_e32 v97, 0, v97
	v_mul_f32_e32 v102, v2, v96
	v_max_i32_e32 v98, 0, v98
	v_fmac_f32_e32 v102, v3, v97
	v_max_i32_e32 v95, 0, v99
	v_fmac_f32_e32 v102, v4, v98
	s_waitcnt vmcnt(8)
	v_mfma_f32_16x16x32_bf16 v[96:99], v[6:9], v[10:13], 0
	v_fmac_f32_e32 v102, v5, v95
	s_nop 1
	v_permlane32_swap_b32_e32 v100, v102
	s_nop 3
	v_max_i32_e32 v96, 0, v96
	v_max_i32_e32 v97, 0, v97
	v_mul_f32_e32 v96, v2, v96
	v_max_i32_e32 v98, 0, v98
	v_fmac_f32_e32 v96, v3, v97
	v_max_i32_e32 v95, 0, v99
	v_fmac_f32_e32 v96, v4, v98
	v_fmac_f32_e32 v96, v5, v95
	v_add_f32_e32 v95, v100, v102
	s_nop 0
	v_permlane32_swap_b32_e32 v101, v96
	v_add_f32_e32 v96, v101, v96
	s_nop 1
	v_permlane16_swap_b32_e32 v95, v96
	s_nop 0
	v_add_co_u32_e32 v10, vcc, 0x2000, v58
	s_nop 1
	v_addc_co_u32_e32 v11, vcc, 0, v59, vcc
	global_load_dwordx4 v[22:25], v[10:11], off
	global_load_dwordx4 v[18:21], v[10:11], off offset:1024
	global_load_dwordx4 v[14:17], v[10:11], off offset:2048
	s_nop 0
	global_load_dwordx4 v[10:13], v[10:11], off offset:3072
.LBB0_1045:
	s_waitcnt vmcnt(11)
	v_mfma_f32_16x16x32_bf16 v[98:101], v[6:9], v[42:45], 0
	v_lshl_add_u64 v[58:59], v[58:59], 0, s[28:29]
	s_cmp_lt_i32 s16, 40
	s_nop 5
	v_max_i32_e32 v98, 0, v98
	v_max_i32_e32 v99, 0, v99
	v_mul_f32_e32 v102, v2, v98
	v_max_i32_e32 v100, 0, v100
	v_fmac_f32_e32 v102, v3, v99
	v_max_i32_e32 v97, 0, v101
	v_fmac_f32_e32 v102, v4, v100
	s_waitcnt vmcnt(10)
	v_mfma_f32_16x16x32_bf16 v[98:101], v[6:9], v[46:49], 0
	v_fmac_f32_e32 v102, v5, v97
	s_nop 6
	v_max_i32_e32 v98, 0, v98
	v_max_i32_e32 v99, 0, v99
	v_mul_f32_e32 v103, v2, v98
	v_max_i32_e32 v100, 0, v100
	v_fmac_f32_e32 v103, v3, v99
	v_max_i32_e32 v97, 0, v101
	v_fmac_f32_e32 v103, v4, v100
	s_waitcnt vmcnt(9)
	v_mfma_f32_16x16x32_bf16 v[98:101], v[6:9], v[50:53], 0
	v_fmac_f32_e32 v103, v5, v97
	s_nop 6
	v_max_i32_e32 v98, 0, v98
	v_max_i32_e32 v99, 0, v99
	v_mul_f32_e32 v104, v2, v98
	v_max_i32_e32 v100, 0, v100
	v_fmac_f32_e32 v104, v3, v99
	v_max_i32_e32 v97, 0, v101
	v_fmac_f32_e32 v104, v4, v100
	s_waitcnt vmcnt(8)
	v_mfma_f32_16x16x32_bf16 v[98:101], v[6:9], v[54:57], 0
	v_fmac_f32_e32 v104, v5, v97
	s_nop 1
	v_permlane32_swap_b32_e32 v102, v104
	s_nop 3
	v_max_i32_e32 v98, 0, v98
	v_max_i32_e32 v99, 0, v99
	v_mul_f32_e32 v98, v2, v98
	v_max_i32_e32 v100, 0, v100
	v_fmac_f32_e32 v98, v3, v99
	v_max_i32_e32 v97, 0, v101
	v_fmac_f32_e32 v98, v4, v100
	v_fmac_f32_e32 v98, v5, v97
	v_add_f32_e32 v97, v102, v104
	s_nop 0
	v_permlane32_swap_b32_e32 v103, v98
	v_add_f32_e32 v98, v103, v98
	s_nop 1
	v_permlane16_swap_b32_e32 v97, v98
	s_nop 0
	v_add_co_u32_e32 v54, vcc, 0x2000, v58
	s_nop 1
	v_addc_co_u32_e32 v55, vcc, 0, v59, vcc
	global_load_dwordx4 v[42:45], v[54:55], off
	global_load_dwordx4 v[46:49], v[54:55], off offset:1024
	global_load_dwordx4 v[50:53], v[54:55], off offset:2048
	s_nop 0
	global_load_dwordx4 v[54:57], v[54:55], off offset:3072
.LBB0_1047:
	s_waitcnt vmcnt(11)
	v_mfma_f32_16x16x32_bf16 v[100:103], v[6:9], v[26:29], 0
	v_lshl_add_u64 v[58:59], v[58:59], 0, s[28:29]
	s_cmp_lt_i32 s16, 41
	s_nop 5
	v_max_i32_e32 v100, 0, v100
	v_max_i32_e32 v101, 0, v101
	v_mul_f32_e32 v104, v2, v100
	v_max_i32_e32 v102, 0, v102
	v_fmac_f32_e32 v104, v3, v101
	v_max_i32_e32 v99, 0, v103
	v_fmac_f32_e32 v104, v4, v102
	s_waitcnt vmcnt(10)
	v_mfma_f32_16x16x32_bf16 v[100:103], v[6:9], v[30:33], 0
	v_fmac_f32_e32 v104, v5, v99
	s_nop 6
	v_max_i32_e32 v100, 0, v100
	v_max_i32_e32 v101, 0, v101
	v_mul_f32_e32 v105, v2, v100
	v_max_i32_e32 v102, 0, v102
	v_fmac_f32_e32 v105, v3, v101
	v_max_i32_e32 v99, 0, v103
	v_fmac_f32_e32 v105, v4, v102
	s_waitcnt vmcnt(9)
	v_mfma_f32_16x16x32_bf16 v[100:103], v[6:9], v[34:37], 0
	v_fmac_f32_e32 v105, v5, v99
	s_nop 6
	v_max_i32_e32 v100, 0, v100
	v_max_i32_e32 v101, 0, v101
	v_mul_f32_e32 v106, v2, v100
	v_max_i32_e32 v102, 0, v102
	v_fmac_f32_e32 v106, v3, v101
	v_max_i32_e32 v99, 0, v103
	v_fmac_f32_e32 v106, v4, v102
	s_waitcnt vmcnt(8)
	v_mfma_f32_16x16x32_bf16 v[100:103], v[6:9], v[38:41], 0
	v_fmac_f32_e32 v106, v5, v99
	s_nop 1
	v_permlane32_swap_b32_e32 v104, v106
	s_nop 3
	v_max_i32_e32 v100, 0, v100
	v_max_i32_e32 v101, 0, v101
	v_mul_f32_e32 v100, v2, v100
	v_max_i32_e32 v102, 0, v102
	v_fmac_f32_e32 v100, v3, v101
	v_max_i32_e32 v99, 0, v103
	v_fmac_f32_e32 v100, v4, v102
	v_fmac_f32_e32 v100, v5, v99
	v_add_f32_e32 v99, v104, v106
	s_nop 0
	v_permlane32_swap_b32_e32 v105, v100
	v_add_f32_e32 v100, v105, v100
	s_nop 1
	v_permlane16_swap_b32_e32 v99, v100
	s_nop 0
	v_add_co_u32_e32 v38, vcc, 0x2000, v58
	s_nop 1
	v_addc_co_u32_e32 v39, vcc, 0, v59, vcc
	global_load_dwordx4 v[26:29], v[38:39], off
	global_load_dwordx4 v[30:33], v[38:39], off offset:1024
	global_load_dwordx4 v[34:37], v[38:39], off offset:2048
	s_nop 0
	global_load_dwordx4 v[38:41], v[38:39], off offset:3072
; __device__ __forceinline__ SwapPair swap32p(float x, float y) { unsigned a = __builtin_bit_cast(unsigned, x), b = __builtin_bit_cast(unsigned, y); asm volatile("" : "+v"(a), "+v"(b)); auto r = __builtin_amdgcn_permlane32_swap(a, b, false, false); return SwapPair{r[0], r[1]}; }
; __device__ __forceinline__ SwapPair swap16p(float x, float y) { unsigned a = __builtin_bit_cast(unsigned, x), b = __builtin_bit_cast(unsigned, y); asm volatile("" : "+v"(a), "+v"(b)); auto r = __builtin_amdgcn_permlane16_swap(a, b, false, false); return SwapPair{r[0], r[1]}; }
; #define MFMA16(a, b, c) __builtin_amdgcn_mfma_f32_16x16x32_bf16((a), (b), (c), 0, 0, 0)
; __device__ __forceinline__ void dsa_token(Frame& F, int b, int t, const bf16* QI, const bf16* KI, const float* WI, const bf16* CKVN, const bf16* QLAT, bf16* OLAT) {
;     ...
;         for (int g4 = 0; g4 < 16; ++g4) {
;             if (4 * g4 <= cmax) {
; #pragma unroll
;                 for (int c = 4 * g4; c < 4 * g4 + 4; ++c) {
;                     asm volatile("" : "+v"(kp));
;                     if (c + 2 < 64) { if (c + 2 <= cmax4) DSA_KLOAD(c + 2, 2); }
;                     float v[4];
; #pragma unroll
;                     for (int tau = 0; tau < 4; ++tau) {
;                         const f32x4 d = MFMA16(qa, kbuf[c % 3][tau], ((f32x4){0.f, 0.f, 0.f, 0.f}));
;                         typedef int i32x4_ __attribute__((ext_vector_type(4)));
;                         const f32x4 rl = __builtin_bit_cast(f32x4, __builtin_elementwise_max(__builtin_bit_cast(i32x4_, d), ((i32x4_){0, 0, 0, 0})));
;                         v[tau] = fmaf(w4.w, rl[3], fmaf(w4.z, rl[2], fmaf(w4.y, rl[1], w4.x * rl[0])));
;                     }
;                     const SwapPair r0 = swap32p(v[0], v[2]), r1 = swap32p(v[1], v[3]);
;                     const float a0 = __builtin_bit_cast(float, r0.a) + __builtin_bit_cast(float, r0.b), a1 = __builtin_bit_cast(float, r1.a) + __builtin_bit_cast(float, r1.b);
;                     const SwapPair r2 = swap16p(a0, a1);
;                     const float keep = __builtin_bit_cast(float, r2.a) + __builtin_bit_cast(float, r2.b);
;                     const bool cand = 64 * c + lane <= t;
;                     sc[c] = cand ? keep : -INFINITY; vmax = fmaxf(vmax, sc[c]); vmin = fminf(vmin, cand ? keep : INFINITY);
;                     kp += 64 * 32;
.LBB0_1049:
	v_add_f32_e32 v96, v95, v96
	v_or_b32_e32 v95, 0x900, v176
	v_cmp_lt_i32_e32 vcc, s2, v95
	v_add_f32_e32 v98, v97, v98
	v_lshl_add_u64 v[58:59], v[58:59], 0, s[28:29]
	v_cndmask_b32_e32 v95, v96, v206, vcc
	v_cndmask_b32_e32 v96, v96, v207, vcc
	v_cmp_lt_i32_e32 vcc, s2, v244
	s_nop 1
	v_cndmask_b32_e32 v97, v98, v206, vcc
	v_cndmask_b32_e32 v98, v98, v207, vcc
	v_min3_f32 v103, v108, v96, v98
	v_add_f32_e32 v98, v99, v100
	v_cmp_lt_i32_e32 vcc, s2, v245
	v_max3_f32 v102, v107, v95, v97
	s_nop 0
	v_cndmask_b32_e32 v96, v98, v206, vcc
	v_cndmask_b32_e32 v104, v98, v207, vcc
	s_waitcnt vmcnt(11)
	v_mfma_f32_16x16x32_bf16 v[98:101], v[6:9], v[22:25], 0
	v_cmp_lt_i32_e32 vcc, s2, v246
	s_nop 6
	v_max_i32_e32 v98, 0, v98
	v_max_i32_e32 v99, 0, v99
	v_mul_f32_e32 v105, v2, v98
	v_max_i32_e32 v100, 0, v100
	v_fmac_f32_e32 v105, v3, v99
	v_max_i32_e32 v101, 0, v101
	v_fmac_f32_e32 v105, v4, v100
	v_fmac_f32_e32 v105, v5, v101
	s_waitcnt vmcnt(10)
	v_mfma_f32_16x16x32_bf16 v[98:101], v[6:9], v[18:21], 0
	s_nop 7
	v_max_i32_e32 v98, 0, v98
	v_max_i32_e32 v99, 0, v99
	v_mul_f32_e32 v106, v2, v98
	v_max_i32_e32 v100, 0, v100
	v_fmac_f32_e32 v106, v3, v99
	v_max_i32_e32 v101, 0, v101
	v_fmac_f32_e32 v106, v4, v100
	v_fmac_f32_e32 v106, v5, v101
	s_waitcnt vmcnt(9)
	v_mfma_f32_16x16x32_bf16 v[98:101], v[6:9], v[14:17], 0
	s_nop 7
	v_max_i32_e32 v98, 0, v98
	v_max_i32_e32 v99, 0, v99
	v_mul_f32_e32 v107, v2, v98
	v_max_i32_e32 v100, 0, v100
	v_fmac_f32_e32 v107, v3, v99
	v_max_i32_e32 v101, 0, v101
	v_fmac_f32_e32 v107, v4, v100
	v_fmac_f32_e32 v107, v5, v101
	s_waitcnt vmcnt(8)
	v_mfma_f32_16x16x32_bf16 v[98:101], v[6:9], v[10:13], 0
	s_nop 0
	v_permlane32_swap_b32_e32 v105, v107
	s_nop 5
	v_max_i32_e32 v98, 0, v98
	v_max_i32_e32 v99, 0, v99
	v_mul_f32_e32 v98, v2, v98
	v_max_i32_e32 v100, 0, v100
	v_fmac_f32_e32 v98, v3, v99
	v_max_i32_e32 v101, 0, v101
	v_fmac_f32_e32 v98, v4, v100
	v_fmac_f32_e32 v98, v5, v101
	v_add_f32_e32 v99, v105, v107
	s_nop 0
	v_permlane32_swap_b32_e32 v106, v98
	v_add_f32_e32 v98, v106, v98
	s_nop 1
	v_permlane16_swap_b32_e32 v99, v98
	v_add_f32_e32 v99, v99, v98
	v_cndmask_b32_e32 v98, v99, v206, vcc
	v_cndmask_b32_e32 v99, v99, v207, vcc
	v_max3_f32 v107, v102, v96, v98
	v_min3_f32 v108, v103, v104, v99
	s_branch .LBB0_1051
.LBB0_1050:
	s_nop 0
	v_mov_b32_e32 v97, 0xff800000
	v_mov_b32_e32 v96, 0xff800000
	v_mov_b32_e32 v98, 0xff800000
.LBB0_1051:
	s_cmp_gt_i32 s18, 39
	s_cselect_b64 s[12:13], -1, 0
	s_cmp_lt_i32 s18, 40
	v_mov_b32_e32 v99, 0xff800000
	s_cbranch_scc1 .LBB0_1061
	s_cmp_lt_i32 s16, 42
	s_nop 0
	s_nop 0
	v_add_co_u32_e32 v10, vcc, 0x2000, v58
	s_nop 1
	v_addc_co_u32_e32 v11, vcc, 0, v59, vcc
	global_load_dwordx4 v[22:25], v[10:11], off
	global_load_dwordx4 v[18:21], v[10:11], off offset:1024
	global_load_dwordx4 v[14:17], v[10:11], off offset:2048
	s_nop 0
	global_load_dwordx4 v[10:13], v[10:11], off offset:3072
.LBB0_1054:
	s_waitcnt vmcnt(11)
	v_mfma_f32_16x16x32_bf16 v[100:103], v[6:9], v[42:45], 0
	v_lshl_add_u64 v[58:59], v[58:59], 0, s[28:29]
	s_cmp_lt_i32 s16, 43
	s_nop 5
	v_max_i32_e32 v100, 0, v100
	v_max_i32_e32 v101, 0, v101
	v_mul_f32_e32 v104, v2, v100
	v_max_i32_e32 v102, 0, v102
	v_fmac_f32_e32 v104, v3, v101
	v_max_i32_e32 v99, 0, v103
	v_fmac_f32_e32 v104, v4, v102
	s_waitcnt vmcnt(10)
	v_mfma_f32_16x16x32_bf16 v[100:103], v[6:9], v[46:49], 0
	v_fmac_f32_e32 v104, v5, v99
	s_nop 6
	v_max_i32_e32 v100, 0, v100
	v_max_i32_e32 v101, 0, v101
	v_mul_f32_e32 v105, v2, v100
	v_max_i32_e32 v102, 0, v102
	v_fmac_f32_e32 v105, v3, v101
	v_max_i32_e32 v99, 0, v103
	v_fmac_f32_e32 v105, v4, v102
	s_waitcnt vmcnt(9)
	v_mfma_f32_16x16x32_bf16 v[100:103], v[6:9], v[50:53], 0
	v_fmac_f32_e32 v105, v5, v99
	s_nop 6
	v_max_i32_e32 v100, 0, v100
	v_max_i32_e32 v101, 0, v101
	v_mul_f32_e32 v106, v2, v100
	v_max_i32_e32 v102, 0, v102
	v_fmac_f32_e32 v106, v3, v101
	v_max_i32_e32 v99, 0, v103
	v_fmac_f32_e32 v106, v4, v102
	s_waitcnt vmcnt(8)
	v_mfma_f32_16x16x32_bf16 v[100:103], v[6:9], v[54:57], 0
	v_fmac_f32_e32 v106, v5, v99
	s_nop 1
	v_permlane32_swap_b32_e32 v104, v106
	s_nop 3
	v_max_i32_e32 v100, 0, v100
	v_max_i32_e32 v101, 0, v101
	v_mul_f32_e32 v100, v2, v100
	v_max_i32_e32 v102, 0, v102
	v_fmac_f32_e32 v100, v3, v101
	v_max_i32_e32 v99, 0, v103
	v_fmac_f32_e32 v100, v4, v102
	v_fmac_f32_e32 v100, v5, v99
	v_add_f32_e32 v99, v104, v106
	s_nop 0
	v_permlane32_swap_b32_e32 v105, v100
	v_add_f32_e32 v100, v105, v100
	s_nop 1
	v_permlane16_swap_b32_e32 v99, v100
	s_nop 0
	v_add_co_u32_e32 v54, vcc, 0x2000, v58
	s_nop 1
	v_addc_co_u32_e32 v55, vcc, 0, v59, vcc
	global_load_dwordx4 v[42:45], v[54:55], off
	global_load_dwordx4 v[46:49], v[54:55], off offset:1024
	global_load_dwordx4 v[50:53], v[54:55], off offset:2048
	s_nop 0
	global_load_dwordx4 v[54:57], v[54:55], off offset:3072
; __device__ __forceinline__ SwapPair swap32p(float x, float y) { unsigned a = __builtin_bit_cast(unsigned, x), b = __builtin_bit_cast(unsigned, y); asm volatile("" : "+v"(a), "+v"(b)); auto r = __builtin_amdgcn_permlane32_swap(a, b, false, false); return SwapPair{r[0], r[1]}; }
; __device__ __forceinline__ SwapPair swap16p(float x, float y) { unsigned a = __builtin_bit_cast(unsigned, x), b = __builtin_bit_cast(unsigned, y); asm volatile("" : "+v"(a), "+v"(b)); auto r = __builtin_amdgcn_permlane16_swap(a, b, false, false); return SwapPair{r[0], r[1]}; }
; #define MFMA16(a, b, c) __builtin_amdgcn_mfma_f32_16x16x32_bf16((a), (b), (c), 0, 0, 0)
; __device__ __forceinline__ void dsa_token(Frame& F, int b, int t, const bf16* QI, const bf16* KI, const float* WI, const bf16* CKVN, const bf16* QLAT, bf16* OLAT) {
;     ...
;         for (int g4 = 0; g4 < 16; ++g4) {
;             if (4 * g4 <= cmax) {
; #pragma unroll
;                 for (int c = 4 * g4; c < 4 * g4 + 4; ++c) {
;                     asm volatile("" : "+v"(kp));
;                     if (c + 2 < 64) { if (c + 2 <= cmax4) DSA_KLOAD(c + 2, 2); }
;                     float v[4];
; #pragma unroll
;                     for (int tau = 0; tau < 4; ++tau) {
;                         const f32x4 d = MFMA16(qa, kbuf[c % 3][tau], ((f32x4){0.f, 0.f, 0.f, 0.f}));
;                         typedef int i32x4_ __attribute__((ext_vector_type(4)));
;                         const f32x4 rl = __builtin_bit_cast(f32x4, __builtin_elementwise_max(__builtin_bit_cast(i32x4_, d), ((i32x4_){0, 0, 0, 0})));
;                         v[tau] = fmaf(w4.w, rl[3], fmaf(w4.z, rl[2], fmaf(w4.y, rl[1], w4.x * rl[0])));
;                     }
;                     const SwapPair r0 = swap32p(v[0], v[2]), r1 = swap32p(v[1], v[3]);
;                     const float a0 = __builtin_bit_cast(float, r0.a) + __builtin_bit_cast(float, r0.b), a1 = __builtin_bit_cast(float, r1.a) + __builtin_bit_cast(float, r1.b);
;                     const SwapPair r2 = swap16p(a0, a1);
;                     const float keep = __builtin_bit_cast(float, r2.a) + __builtin_bit_cast(float, r2.b);
;                     const bool cand = 64 * c + lane <= t;
;                     sc[c] = cand ? keep : -INFINITY; vmax = fmaxf(vmax, sc[c]); vmin = fminf(vmin, cand ? keep : INFINITY);
;                     kp += 64 * 32;
;                 }
;             }
;         }
.LBB0_1056:
	s_waitcnt vmcnt(11)
	v_mfma_f32_16x16x32_bf16 v[102:105], v[6:9], v[26:29], 0
	v_lshl_add_u64 v[58:59], v[58:59], 0, s[28:29]
	s_cmp_lt_i32 s16, 44
	s_nop 5
	v_max_i32_e32 v102, 0, v102
	v_max_i32_e32 v103, 0, v103
	v_mul_f32_e32 v106, v2, v102
	v_max_i32_e32 v104, 0, v104
	v_fmac_f32_e32 v106, v3, v103
	v_max_i32_e32 v101, 0, v105
	v_fmac_f32_e32 v106, v4, v104
	s_waitcnt vmcnt(10)
	v_mfma_f32_16x16x32_bf16 v[102:105], v[6:9], v[30:33], 0
	v_fmac_f32_e32 v106, v5, v101
	s_nop 6
	v_max_i32_e32 v102, 0, v102
	v_max_i32_e32 v103, 0, v103
	v_mul_f32_e32 v109, v2, v102
	v_max_i32_e32 v104, 0, v104
	v_fmac_f32_e32 v109, v3, v103
	v_max_i32_e32 v101, 0, v105
	v_fmac_f32_e32 v109, v4, v104
	s_waitcnt vmcnt(9)
	v_mfma_f32_16x16x32_bf16 v[102:105], v[6:9], v[34:37], 0
	v_fmac_f32_e32 v109, v5, v101
	s_nop 6
	v_max_i32_e32 v102, 0, v102
	v_max_i32_e32 v103, 0, v103
	v_mul_f32_e32 v110, v2, v102
	v_max_i32_e32 v104, 0, v104
	v_fmac_f32_e32 v110, v3, v103
	v_max_i32_e32 v101, 0, v105
	v_fmac_f32_e32 v110, v4, v104
	s_waitcnt vmcnt(8)
	v_mfma_f32_16x16x32_bf16 v[102:105], v[6:9], v[38:41], 0
	v_fmac_f32_e32 v110, v5, v101
	s_nop 1
	v_permlane32_swap_b32_e32 v106, v110
	s_nop 3
	v_max_i32_e32 v102, 0, v102
	v_max_i32_e32 v103, 0, v103
	v_mul_f32_e32 v102, v2, v102
	v_max_i32_e32 v104, 0, v104
	v_fmac_f32_e32 v102, v3, v103
	v_max_i32_e32 v101, 0, v105
	v_fmac_f32_e32 v102, v4, v104
	v_fmac_f32_e32 v102, v5, v101
	v_add_f32_e32 v101, v106, v110
	s_nop 0
	v_permlane32_swap_b32_e32 v109, v102
	v_add_f32_e32 v102, v109, v102
	s_nop 1
	v_permlane16_swap_b32_e32 v101, v102
	s_nop 0
	v_add_co_u32_e32 v38, vcc, 0x2000, v58
	s_nop 1
	v_addc_co_u32_e32 v39, vcc, 0, v59, vcc
	global_load_dwordx4 v[26:29], v[38:39], off
	global_load_dwordx4 v[30:33], v[38:39], off offset:1024
	global_load_dwordx4 v[34:37], v[38:39], off offset:2048
	s_nop 0
	global_load_dwordx4 v[38:41], v[38:39], off offset:3072
.LBB0_1058:
	s_waitcnt vmcnt(11)
	v_mfma_f32_16x16x32_bf16 v[110:113], v[6:9], v[22:25], 0
	v_lshl_add_u64 v[58:59], v[58:59], 0, s[28:29]
	s_cmp_lt_i32 s16, 45
	s_nop 5
	v_max_i32_e32 v103, 0, v113
	v_max_i32_e32 v104, 0, v112
	v_max_i32_e32 v105, 0, v111
	v_max_i32_e32 v106, 0, v110
	s_waitcnt vmcnt(10)
	v_mfma_f32_16x16x32_bf16 v[110:113], v[6:9], v[18:21], 0
	v_mul_f32_e32 v106, v2, v106
	v_fmac_f32_e32 v106, v3, v105
	v_fmac_f32_e32 v106, v4, v104
	v_fmac_f32_e32 v106, v5, v103
	s_nop 3
	v_max_i32_e32 v103, 0, v113
	v_max_i32_e32 v104, 0, v112
	v_max_i32_e32 v105, 0, v111
	v_max_i32_e32 v109, 0, v110
	s_waitcnt vmcnt(9)
	v_mfma_f32_16x16x32_bf16 v[110:113], v[6:9], v[14:17], 0
	v_mul_f32_e32 v109, v2, v109
	v_fmac_f32_e32 v109, v3, v105
	v_fmac_f32_e32 v109, v4, v104
	v_fmac_f32_e32 v109, v5, v103
	s_nop 3
	v_max_i32_e32 v110, 0, v110
	v_max_i32_e32 v103, 0, v113
	v_max_i32_e32 v104, 0, v112
	v_max_i32_e32 v105, 0, v111
	v_mul_f32_e32 v114, v2, v110
	s_waitcnt vmcnt(8)
	v_mfma_f32_16x16x32_bf16 v[110:113], v[6:9], v[10:13], 0
	v_fmac_f32_e32 v114, v3, v105
	v_fmac_f32_e32 v114, v4, v104
	v_fmac_f32_e32 v114, v5, v103
	s_nop 1
	v_permlane32_swap_b32_e32 v106, v114
	s_nop 1
	v_max_i32_e32 v110, 0, v110
	v_max_i32_e32 v105, 0, v111
	v_mul_f32_e32 v110, v2, v110
	v_max_i32_e32 v104, 0, v112
	v_fmac_f32_e32 v110, v3, v105
	v_max_i32_e32 v103, 0, v113
	v_fmac_f32_e32 v110, v4, v104
	v_fmac_f32_e32 v110, v5, v103
	v_add_f32_e32 v103, v106, v114
	s_nop 0
	v_permlane32_swap_b32_e32 v109, v110
	v_add_f32_e32 v104, v109, v110
	s_nop 1
	v_permlane16_swap_b32_e32 v103, v104
	s_nop 0
	v_add_co_u32_e32 v10, vcc, 0x2000, v58
	s_nop 1
	v_addc_co_u32_e32 v11, vcc, 0, v59, vcc
	global_load_dwordx4 v[22:25], v[10:11], off
	global_load_dwordx4 v[18:21], v[10:11], off offset:1024
	global_load_dwordx4 v[14:17], v[10:11], off offset:2048
	s_nop 0
	global_load_dwordx4 v[10:13], v[10:11], off offset:3072
.LBB0_1060:
	v_add_f32_e32 v100, v99, v100
	v_cmp_lt_i32_e32 vcc, s2, v247
	v_add_f32_e32 v102, v101, v102
	v_lshl_add_u64 v[58:59], v[58:59], 0, s[28:29]
	v_cndmask_b32_e32 v99, v100, v206, vcc
	v_cndmask_b32_e32 v100, v100, v207, vcc
	v_cmp_lt_i32_e32 vcc, s2, v248
	s_nop 1
	v_cndmask_b32_e32 v101, v102, v206, vcc
	v_cndmask_b32_e32 v102, v102, v207, vcc
	v_min3_f32 v108, v108, v100, v102
	v_add_f32_e32 v102, v103, v104
	v_cmp_lt_i32_e32 vcc, s2, v249
	v_max3_f32 v106, v107, v99, v101
	s_nop 0
	v_cndmask_b32_e32 v100, v102, v206, vcc
	v_cndmask_b32_e32 v109, v102, v207, vcc
	s_waitcnt vmcnt(11)
	v_mfma_f32_16x16x32_bf16 v[102:105], v[6:9], v[42:45], 0
	v_cmp_lt_i32_e32 vcc, s2, v250
	s_nop 6
	v_max_i32_e32 v102, 0, v102
	v_max_i32_e32 v103, 0, v103
	v_mul_f32_e32 v107, v2, v102
	v_max_i32_e32 v104, 0, v104
	v_fmac_f32_e32 v107, v3, v103
	v_max_i32_e32 v105, 0, v105
	v_fmac_f32_e32 v107, v4, v104
	v_fmac_f32_e32 v107, v5, v105
	s_waitcnt vmcnt(10)
	v_mfma_f32_16x16x32_bf16 v[102:105], v[6:9], v[46:49], 0
	s_nop 7
	v_max_i32_e32 v102, 0, v102
	v_max_i32_e32 v103, 0, v103
	v_mul_f32_e32 v110, v2, v102
	v_max_i32_e32 v104, 0, v104
	v_fmac_f32_e32 v110, v3, v103
	v_max_i32_e32 v105, 0, v105
	v_fmac_f32_e32 v110, v4, v104
	v_fmac_f32_e32 v110, v5, v105
	s_waitcnt vmcnt(9)
	v_mfma_f32_16x16x32_bf16 v[102:105], v[6:9], v[50:53], 0
	s_nop 7
	v_max_i32_e32 v102, 0, v102
	v_max_i32_e32 v103, 0, v103
	v_mul_f32_e32 v111, v2, v102
	v_max_i32_e32 v104, 0, v104
	v_fmac_f32_e32 v111, v3, v103
	v_max_i32_e32 v105, 0, v105
	v_fmac_f32_e32 v111, v4, v104
	v_fmac_f32_e32 v111, v5, v105
	s_waitcnt vmcnt(8)
	v_mfma_f32_16x16x32_bf16 v[102:105], v[6:9], v[54:57], 0
	s_nop 0
	v_permlane32_swap_b32_e32 v107, v111
	s_nop 5
	v_max_i32_e32 v102, 0, v102
	v_max_i32_e32 v103, 0, v103
	v_mul_f32_e32 v102, v2, v102
	v_max_i32_e32 v104, 0, v104
	v_fmac_f32_e32 v102, v3, v103
	v_max_i32_e32 v105, 0, v105
	v_fmac_f32_e32 v102, v4, v104
	v_fmac_f32_e32 v102, v5, v105
	v_add_f32_e32 v103, v107, v111
	s_nop 0
	v_permlane32_swap_b32_e32 v110, v102
	v_add_f32_e32 v102, v110, v102
	s_nop 1
	v_permlane16_swap_b32_e32 v103, v102
	v_add_f32_e32 v103, v103, v102
	v_cndmask_b32_e32 v102, v103, v206, vcc
	v_cndmask_b32_e32 v103, v103, v207, vcc
	v_max3_f32 v107, v106, v100, v102
	v_min3_f32 v108, v108, v109, v103
	s_branch .LBB0_1062
; __device__ __forceinline__ SwapPair swap32p(float x, float y) { unsigned a = __builtin_bit_cast(unsigned, x), b = __builtin_bit_cast(unsigned, y); asm volatile("" : "+v"(a), "+v"(b)); auto r = __builtin_amdgcn_permlane32_swap(a, b, false, false); return SwapPair{r[0], r[1]}; }
; __device__ __forceinline__ SwapPair swap16p(float x, float y) { unsigned a = __builtin_bit_cast(unsigned, x), b = __builtin_bit_cast(unsigned, y); asm volatile("" : "+v"(a), "+v"(b)); auto r = __builtin_amdgcn_permlane16_swap(a, b, false, false); return SwapPair{r[0], r[1]}; }
; #define MFMA16(a, b, c) __builtin_amdgcn_mfma_f32_16x16x32_bf16((a), (b), (c), 0, 0, 0)
; __device__ __forceinline__ void dsa_token(Frame& F, int b, int t, const bf16* QI, const bf16* KI, const float* WI, const bf16* CKVN, const bf16* QLAT, bf16* OLAT) {
;     ...
;         for (int g4 = 0; g4 < 16; ++g4) {
;             if (4 * g4 <= cmax) {
; #pragma unroll
;                 for (int c = 4 * g4; c < 4 * g4 + 4; ++c) {
;                     asm volatile("" : "+v"(kp));
;                     if (c + 2 < 64) { if (c + 2 <= cmax4) DSA_KLOAD(c + 2, 2); }
;                     float v[4];
; #pragma unroll
;                     for (int tau = 0; tau < 4; ++tau) {
;                         const f32x4 d = MFMA16(qa, kbuf[c % 3][tau], ((f32x4){0.f, 0.f, 0.f, 0.f}));
;                         typedef int i32x4_ __attribute__((ext_vector_type(4)));
;                         const f32x4 rl = __builtin_bit_cast(f32x4, __builtin_elementwise_max(__builtin_bit_cast(i32x4_, d), ((i32x4_){0, 0, 0, 0})));
;                         v[tau] = fmaf(w4.w, rl[3], fmaf(w4.z, rl[2], fmaf(w4.y, rl[1], w4.x * rl[0])));
;                     }
;                     const SwapPair r0 = swap32p(v[0], v[2]), r1 = swap32p(v[1], v[3]);
;                     const float a0 = __builtin_bit_cast(float, r0.a) + __builtin_bit_cast(float, r0.b), a1 = __builtin_bit_cast(float, r1.a) + __builtin_bit_cast(float, r1.b);
;                     const SwapPair r2 = swap16p(a0, a1);
;                     const float keep = __builtin_bit_cast(float, r2.a) + __builtin_bit_cast(float, r2.b);
;                     const bool cand = 64 * c + lane <= t;
;                     sc[c] = cand ? keep : -INFINITY; vmax = fmaxf(vmax, sc[c]); vmin = fminf(vmin, cand ? keep : INFINITY);
;                     kp += 64 * 32;
;                 }
;             }
;         }
.LBB0_1061:
	s_nop 0
	v_mov_b32_e32 v101, 0xff800000
	v_mov_b32_e32 v100, 0xff800000
	v_mov_b32_e32 v102, 0xff800000
.LBB0_1062:
	s_cmp_gt_i32 s18, 43
	s_cselect_b64 s[48:49], -1, 0
	s_cmp_lt_i32 s18, 44
	v_mov_b32_e32 v103, 0xff800000
	s_cbranch_scc1 .LBB0_1072
	s_cmp_lt_i32 s16, 46
	s_nop 0
	s_nop 0
	v_add_co_u32_e32 v54, vcc, 0x2000, v58
	s_nop 1
	v_addc_co_u32_e32 v55, vcc, 0, v59, vcc
	global_load_dwordx4 v[42:45], v[54:55], off
	global_load_dwordx4 v[46:49], v[54:55], off offset:1024
	global_load_dwordx4 v[50:53], v[54:55], off offset:2048
	s_nop 0
	global_load_dwordx4 v[54:57], v[54:55], off offset:3072
.LBB0_1065:
	s_waitcnt vmcnt(11)
	v_mfma_f32_16x16x32_bf16 v[110:113], v[6:9], v[26:29], 0
	v_lshl_add_u64 v[58:59], v[58:59], 0, s[28:29]
	s_cmp_lt_i32 s16, 47
	s_nop 5
	v_max_i32_e32 v103, 0, v113
	v_max_i32_e32 v104, 0, v112
	v_max_i32_e32 v105, 0, v111
	v_max_i32_e32 v106, 0, v110
	s_waitcnt vmcnt(10)
	v_mfma_f32_16x16x32_bf16 v[110:113], v[6:9], v[30:33], 0
	v_mul_f32_e32 v106, v2, v106
	v_fmac_f32_e32 v106, v3, v105
	v_fmac_f32_e32 v106, v4, v104
	v_fmac_f32_e32 v106, v5, v103
	s_nop 3
	v_max_i32_e32 v103, 0, v113
	v_max_i32_e32 v104, 0, v112
	v_max_i32_e32 v105, 0, v111
	v_max_i32_e32 v109, 0, v110
	s_waitcnt vmcnt(9)
	v_mfma_f32_16x16x32_bf16 v[110:113], v[6:9], v[34:37], 0
	v_mul_f32_e32 v109, v2, v109
	v_fmac_f32_e32 v109, v3, v105
	v_fmac_f32_e32 v109, v4, v104
	v_fmac_f32_e32 v109, v5, v103
	s_nop 3
	v_max_i32_e32 v110, 0, v110
	v_max_i32_e32 v103, 0, v113
	v_max_i32_e32 v104, 0, v112
	v_max_i32_e32 v105, 0, v111
	v_mul_f32_e32 v114, v2, v110
	s_waitcnt vmcnt(8)
	v_mfma_f32_16x16x32_bf16 v[110:113], v[6:9], v[38:41], 0
	v_fmac_f32_e32 v114, v3, v105
	v_fmac_f32_e32 v114, v4, v104
	v_fmac_f32_e32 v114, v5, v103
	s_nop 1
	v_permlane32_swap_b32_e32 v106, v114
	s_nop 1
	v_max_i32_e32 v110, 0, v110
	v_max_i32_e32 v105, 0, v111
	v_mul_f32_e32 v110, v2, v110
	v_max_i32_e32 v104, 0, v112
	v_fmac_f32_e32 v110, v3, v105
	v_max_i32_e32 v103, 0, v113
	v_fmac_f32_e32 v110, v4, v104
	v_fmac_f32_e32 v110, v5, v103
	v_add_f32_e32 v103, v106, v114
	s_nop 0
	v_permlane32_swap_b32_e32 v109, v110
	v_add_f32_e32 v104, v109, v110
	s_nop 1
	v_permlane16_swap_b32_e32 v103, v104
	s_nop 0
	v_add_co_u32_e32 v38, vcc, 0x2000, v58
	s_nop 1
	v_addc_co_u32_e32 v39, vcc, 0, v59, vcc
	global_load_dwordx4 v[26:29], v[38:39], off
	global_load_dwordx4 v[30:33], v[38:39], off offset:1024
	global_load_dwordx4 v[34:37], v[38:39], off offset:2048
	s_nop 0
	global_load_dwordx4 v[38:41], v[38:39], off offset:3072
.LBB0_1067:
	s_waitcnt vmcnt(11)
	v_mfma_f32_16x16x32_bf16 v[110:113], v[6:9], v[22:25], 0
	v_lshl_add_u64 v[58:59], v[58:59], 0, s[28:29]
	s_cmp_lt_i32 s16, 48
	s_nop 5
	v_max_i32_e32 v110, 0, v110
	v_max_i32_e32 v105, 0, v113
	v_max_i32_e32 v106, 0, v112
	v_max_i32_e32 v109, 0, v111
	v_mul_f32_e32 v114, v2, v110
	s_waitcnt vmcnt(10)
	v_mfma_f32_16x16x32_bf16 v[110:113], v[6:9], v[18:21], 0
	v_fmac_f32_e32 v114, v3, v109
	v_fmac_f32_e32 v114, v4, v106
	v_fmac_f32_e32 v114, v5, v105
	s_nop 4
	v_max_i32_e32 v110, 0, v110
	v_max_i32_e32 v105, 0, v113
	v_max_i32_e32 v106, 0, v112
	v_max_i32_e32 v109, 0, v111
	v_mul_f32_e32 v115, v2, v110
	s_waitcnt vmcnt(9)
	v_mfma_f32_16x16x32_bf16 v[110:113], v[6:9], v[14:17], 0
	v_fmac_f32_e32 v115, v3, v109
	v_fmac_f32_e32 v115, v4, v106
	v_fmac_f32_e32 v115, v5, v105
	s_nop 4
	v_max_i32_e32 v110, 0, v110
	v_max_i32_e32 v105, 0, v113
	v_max_i32_e32 v106, 0, v112
	v_max_i32_e32 v109, 0, v111
	v_mul_f32_e32 v116, v2, v110
	s_waitcnt vmcnt(8)
	v_mfma_f32_16x16x32_bf16 v[110:113], v[6:9], v[10:13], 0
	v_fmac_f32_e32 v116, v3, v109
	v_fmac_f32_e32 v116, v4, v106
	v_fmac_f32_e32 v116, v5, v105
	s_nop 1
	v_permlane32_swap_b32_e32 v114, v116
	s_nop 1
	v_max_i32_e32 v110, 0, v110
	v_max_i32_e32 v109, 0, v111
	v_mul_f32_e32 v110, v2, v110
	v_max_i32_e32 v106, 0, v112
	v_fmac_f32_e32 v110, v3, v109
	v_max_i32_e32 v105, 0, v113
	v_fmac_f32_e32 v110, v4, v106
	v_fmac_f32_e32 v110, v5, v105
	v_add_f32_e32 v105, v114, v116
	s_nop 0
	v_permlane32_swap_b32_e32 v115, v110
	v_add_f32_e32 v106, v115, v110
	s_nop 1
	v_permlane16_swap_b32_e32 v105, v106
	s_nop 0
	v_add_co_u32_e32 v10, vcc, 0x2000, v58
	s_nop 1
	v_addc_co_u32_e32 v11, vcc, 0, v59, vcc
	global_load_dwordx4 v[22:25], v[10:11], off
	global_load_dwordx4 v[18:21], v[10:11], off offset:1024
	global_load_dwordx4 v[14:17], v[10:11], off offset:2048
	s_nop 0
	global_load_dwordx4 v[10:13], v[10:11], off offset:3072
; __device__ __forceinline__ SwapPair swap32p(float x, float y) { unsigned a = __builtin_bit_cast(unsigned, x), b = __builtin_bit_cast(unsigned, y); asm volatile("" : "+v"(a), "+v"(b)); auto r = __builtin_amdgcn_permlane32_swap(a, b, false, false); return SwapPair{r[0], r[1]}; }
; __device__ __forceinline__ SwapPair swap16p(float x, float y) { unsigned a = __builtin_bit_cast(unsigned, x), b = __builtin_bit_cast(unsigned, y); asm volatile("" : "+v"(a), "+v"(b)); auto r = __builtin_amdgcn_permlane16_swap(a, b, false, false); return SwapPair{r[0], r[1]}; }
; #define MFMA16(a, b, c) __builtin_amdgcn_mfma_f32_16x16x32_bf16((a), (b), (c), 0, 0, 0)
; __device__ __forceinline__ void dsa_token(Frame& F, int b, int t, const bf16* QI, const bf16* KI, const float* WI, const bf16* CKVN, const bf16* QLAT, bf16* OLAT) {
;     ...
;         for (int g4 = 0; g4 < 16; ++g4) {
;             if (4 * g4 <= cmax) {
; #pragma unroll
;                 for (int c = 4 * g4; c < 4 * g4 + 4; ++c) {
;                     asm volatile("" : "+v"(kp));
;                     if (c + 2 < 64) { if (c + 2 <= cmax4) DSA_KLOAD(c + 2, 2); }
;                     float v[4];
; #pragma unroll
;                     for (int tau = 0; tau < 4; ++tau) {
;                         const f32x4 d = MFMA16(qa, kbuf[c % 3][tau], ((f32x4){0.f, 0.f, 0.f, 0.f}));
;                         typedef int i32x4_ __attribute__((ext_vector_type(4)));
;                         const f32x4 rl = __builtin_bit_cast(f32x4, __builtin_elementwise_max(__builtin_bit_cast(i32x4_, d), ((i32x4_){0, 0, 0, 0})));
;                         v[tau] = fmaf(w4.w, rl[3], fmaf(w4.z, rl[2], fmaf(w4.y, rl[1], w4.x * rl[0])));
;                     }
;                     const SwapPair r0 = swap32p(v[0], v[2]), r1 = swap32p(v[1], v[3]);
;                     const float a0 = __builtin_bit_cast(float, r0.a) + __builtin_bit_cast(float, r0.b), a1 = __builtin_bit_cast(float, r1.a) + __builtin_bit_cast(float, r1.b);
;                     const SwapPair r2 = swap16p(a0, a1);
;                     const float keep = __builtin_bit_cast(float, r2.a) + __builtin_bit_cast(float, r2.b);
;                     const bool cand = 64 * c + lane <= t;
;                     sc[c] = cand ? keep : -INFINITY; vmax = fmaxf(vmax, sc[c]); vmin = fminf(vmin, cand ? keep : INFINITY);
;                     kp += 64 * 32;
;                 }
;             }
;         }
.LBB0_1069:
	s_waitcnt vmcnt(11)
	v_mfma_f32_16x16x32_bf16 v[110:113], v[6:9], v[42:45], 0
	v_lshl_add_u64 v[58:59], v[58:59], 0, s[28:29]
	s_cmp_lt_i32 s16, 49
	s_nop 5
	v_max_i32_e32 v110, 0, v110
	v_max_i32_e32 v111, 0, v111
	v_mul_f32_e32 v114, v2, v110
	v_max_i32_e32 v112, 0, v112
	v_fmac_f32_e32 v114, v3, v111
	v_max_i32_e32 v109, 0, v113
	v_fmac_f32_e32 v114, v4, v112
	s_waitcnt vmcnt(10)
	v_mfma_f32_16x16x32_bf16 v[110:113], v[6:9], v[46:49], 0
	v_fmac_f32_e32 v114, v5, v109
	s_nop 6
	v_max_i32_e32 v110, 0, v110
	v_max_i32_e32 v111, 0, v111
	v_mul_f32_e32 v115, v2, v110
	v_max_i32_e32 v112, 0, v112
	v_fmac_f32_e32 v115, v3, v111
	v_max_i32_e32 v109, 0, v113
	v_fmac_f32_e32 v115, v4, v112
	s_waitcnt vmcnt(9)
	v_mfma_f32_16x16x32_bf16 v[110:113], v[6:9], v[50:53], 0
	v_fmac_f32_e32 v115, v5, v109
	s_nop 6
	v_max_i32_e32 v110, 0, v110
	v_max_i32_e32 v111, 0, v111
	v_mul_f32_e32 v116, v2, v110
	v_max_i32_e32 v112, 0, v112
	v_fmac_f32_e32 v116, v3, v111
	v_max_i32_e32 v109, 0, v113
	v_fmac_f32_e32 v116, v4, v112
	s_waitcnt vmcnt(8)
	v_mfma_f32_16x16x32_bf16 v[110:113], v[6:9], v[54:57], 0
	v_fmac_f32_e32 v116, v5, v109
	s_nop 1
	v_permlane32_swap_b32_e32 v114, v116
	s_nop 3
	v_max_i32_e32 v110, 0, v110
	v_max_i32_e32 v111, 0, v111
	v_mul_f32_e32 v110, v2, v110
	v_max_i32_e32 v112, 0, v112
	v_fmac_f32_e32 v110, v3, v111
	v_max_i32_e32 v109, 0, v113
	v_fmac_f32_e32 v110, v4, v112
	v_fmac_f32_e32 v110, v5, v109
	v_add_f32_e32 v109, v114, v116
	s_nop 0
	v_permlane32_swap_b32_e32 v115, v110
	v_add_f32_e32 v110, v115, v110
	s_nop 1
	v_permlane16_swap_b32_e32 v109, v110
	s_nop 0
	v_add_co_u32_e32 v54, vcc, 0x2000, v58
	s_nop 1
	v_addc_co_u32_e32 v55, vcc, 0, v59, vcc
	global_load_dwordx4 v[42:45], v[54:55], off
	global_load_dwordx4 v[46:49], v[54:55], off offset:1024
	global_load_dwordx4 v[50:53], v[54:55], off offset:2048
	s_nop 0
	global_load_dwordx4 v[54:57], v[54:55], off offset:3072
.LBB0_1071:
	v_add_f32_e32 v104, v103, v104
	v_cmp_lt_i32_e32 vcc, s2, v251
	v_add_f32_e32 v106, v105, v106
	v_lshl_add_u64 v[58:59], v[58:59], 0, s[28:29]
	v_cndmask_b32_e32 v103, v104, v206, vcc
	v_cndmask_b32_e32 v104, v104, v207, vcc
	v_cmp_lt_i32_e32 vcc, s2, v252
	s_nop 1
	v_cndmask_b32_e32 v105, v106, v206, vcc
	v_cndmask_b32_e32 v106, v106, v207, vcc
	v_min3_f32 v112, v108, v104, v106
	v_add_f32_e32 v106, v109, v110
	v_cmp_lt_i32_e32 vcc, s2, v204
	v_max3_f32 v111, v107, v103, v105
	s_nop 0
	v_cndmask_b32_e32 v104, v106, v206, vcc
	v_cndmask_b32_e32 v110, v106, v207, vcc
	s_waitcnt vmcnt(11)
	v_mfma_f32_16x16x32_bf16 v[106:109], v[6:9], v[26:29], 0
	v_cmp_lt_i32_e32 vcc, s2, v168
	s_nop 6
	v_max_i32_e32 v106, 0, v106
	v_max_i32_e32 v107, 0, v107
	v_mul_f32_e32 v113, v2, v106
	v_max_i32_e32 v108, 0, v108
	v_fmac_f32_e32 v113, v3, v107
	v_max_i32_e32 v109, 0, v109
	v_fmac_f32_e32 v113, v4, v108
	v_fmac_f32_e32 v113, v5, v109
	s_waitcnt vmcnt(10)
	v_mfma_f32_16x16x32_bf16 v[106:109], v[6:9], v[30:33], 0
	s_nop 7
	v_max_i32_e32 v106, 0, v106
	v_max_i32_e32 v107, 0, v107
	v_mul_f32_e32 v114, v2, v106
	v_max_i32_e32 v108, 0, v108
	v_fmac_f32_e32 v114, v3, v107
	v_max_i32_e32 v109, 0, v109
	v_fmac_f32_e32 v114, v4, v108
	v_fmac_f32_e32 v114, v5, v109
	s_waitcnt vmcnt(9)
	v_mfma_f32_16x16x32_bf16 v[106:109], v[6:9], v[34:37], 0
	s_nop 7
	v_max_i32_e32 v106, 0, v106
	v_max_i32_e32 v107, 0, v107
	v_mul_f32_e32 v115, v2, v106
	v_max_i32_e32 v108, 0, v108
	v_fmac_f32_e32 v115, v3, v107
	v_max_i32_e32 v109, 0, v109
	v_fmac_f32_e32 v115, v4, v108
	v_fmac_f32_e32 v115, v5, v109
	s_waitcnt vmcnt(8)
	v_mfma_f32_16x16x32_bf16 v[106:109], v[6:9], v[38:41], 0
	s_nop 0
	v_permlane32_swap_b32_e32 v113, v115
	s_nop 5
	v_max_i32_e32 v106, 0, v106
	v_max_i32_e32 v107, 0, v107
	v_mul_f32_e32 v106, v2, v106
	v_max_i32_e32 v108, 0, v108
	v_fmac_f32_e32 v106, v3, v107
	v_max_i32_e32 v109, 0, v109
	v_fmac_f32_e32 v106, v4, v108
	v_fmac_f32_e32 v106, v5, v109
	v_add_f32_e32 v107, v113, v115
	s_nop 0
	v_permlane32_swap_b32_e32 v114, v106
	v_add_f32_e32 v106, v114, v106
	s_nop 1
	v_permlane16_swap_b32_e32 v107, v106
	v_add_f32_e32 v108, v107, v106
	v_cndmask_b32_e32 v106, v108, v206, vcc
	v_cndmask_b32_e32 v108, v108, v207, vcc
	v_max3_f32 v107, v111, v104, v106
	v_min3_f32 v108, v112, v110, v108
	s_branch .LBB0_1073

; __device__ __forceinline__ SwapPair swap32p(float x, float y) { unsigned a = __builtin_bit_cast(unsigned, x), b = __builtin_bit_cast(unsigned, y); asm volatile("" : "+v"(a), "+v"(b)); auto r = __builtin_amdgcn_permlane32_swap(a, b, false, false); return SwapPair{r[0], r[1]}; }
; __device__ __forceinline__ SwapPair swap16p(float x, float y) { unsigned a = __builtin_bit_cast(unsigned, x), b = __builtin_bit_cast(unsigned, y); asm volatile("" : "+v"(a), "+v"(b)); auto r = __builtin_amdgcn_permlane16_swap(a, b, false, false); return SwapPair{r[0], r[1]}; }
; #define MFMA16(a, b, c) __builtin_amdgcn_mfma_f32_16x16x32_bf16((a), (b), (c), 0, 0, 0)
; __device__ __forceinline__ void dsa_token(Frame& F, int b, int t, const bf16* QI, const bf16* KI, const float* WI, const bf16* CKVN, const bf16* QLAT, bf16* OLAT) {
;     ...
;         for (int g4 = 0; g4 < 16; ++g4) {
;             if (4 * g4 <= cmax) {
; #pragma unroll
;                 for (int c = 4 * g4; c < 4 * g4 + 4; ++c) {
;                     asm volatile("" : "+v"(kp));
;                     if (c + 2 < 64) { if (c + 2 <= cmax4) DSA_KLOAD(c + 2, 2); }
;                     float v[4];
; #pragma unroll
;                     for (int tau = 0; tau < 4; ++tau) {
;                         const f32x4 d = MFMA16(qa, kbuf[c % 3][tau], ((f32x4){0.f, 0.f, 0.f, 0.f}));
;                         typedef int i32x4_ __attribute__((ext_vector_type(4)));
;                         const f32x4 rl = __builtin_bit_cast(f32x4, __builtin_elementwise_max(__builtin_bit_cast(i32x4_, d), ((i32x4_){0, 0, 0, 0})));
;                         v[tau] = fmaf(w4.w, rl[3], fmaf(w4.z, rl[2], fmaf(w4.y, rl[1], w4.x * rl[0])));
;                     }
;                     const SwapPair r0 = swap32p(v[0], v[2]), r1 = swap32p(v[1], v[3]);
;                     const float a0 = __builtin_bit_cast(float, r0.a) + __builtin_bit_cast(float, r0.b), a1 = __builtin_bit_cast(float, r1.a) + __builtin_bit_cast(float, r1.b);
;                     const SwapPair r2 = swap16p(a0, a1);
;                     const float keep = __builtin_bit_cast(float, r2.a) + __builtin_bit_cast(float, r2.b);
;                     const bool cand = 64 * c + lane <= t;
;                     sc[c] = cand ? keep : -INFINITY; vmax = fmaxf(vmax, sc[c]); vmin = fminf(vmin, cand ? keep : INFINITY);
;                     kp += 64 * 32;
;                 }
;             }
;         }
.LBB0_1073:
	s_cmp_gt_i32 s18, 47
	s_cselect_b64 s[92:93], -1, 0
	s_cmp_lt_i32 s18, 48
	v_mov_b32_e32 v112, 0xff800000
	s_cbranch_scc1 .LBB0_1083
	s_cmp_lt_i32 s16, 50
	s_nop 0
	s_nop 0
	v_add_co_u32_e32 v38, vcc, 0x2000, v58
	s_nop 1
	v_addc_co_u32_e32 v39, vcc, 0, v59, vcc
	global_load_dwordx4 v[26:29], v[38:39], off
	global_load_dwordx4 v[30:33], v[38:39], off offset:1024
	global_load_dwordx4 v[34:37], v[38:39], off offset:2048
	s_nop 0
	global_load_dwordx4 v[38:41], v[38:39], off offset:3072
.LBB0_1076:
	s_waitcnt vmcnt(11)
	v_mfma_f32_16x16x32_bf16 v[110:113], v[6:9], v[22:25], 0
	v_lshl_add_u64 v[58:59], v[58:59], 0, s[28:29]
	s_cmp_lt_i32 s16, 51
	s_nop 5
	v_max_i32_e32 v110, 0, v110
	v_max_i32_e32 v111, 0, v111
	v_mul_f32_e32 v114, v2, v110
	v_max_i32_e32 v112, 0, v112
	v_fmac_f32_e32 v114, v3, v111
	v_max_i32_e32 v109, 0, v113
	v_fmac_f32_e32 v114, v4, v112
	s_waitcnt vmcnt(10)
	v_mfma_f32_16x16x32_bf16 v[110:113], v[6:9], v[18:21], 0
	v_fmac_f32_e32 v114, v5, v109
	s_nop 6
	v_max_i32_e32 v110, 0, v110
	v_max_i32_e32 v111, 0, v111
	v_mul_f32_e32 v115, v2, v110
	v_max_i32_e32 v112, 0, v112
	v_fmac_f32_e32 v115, v3, v111
	v_max_i32_e32 v109, 0, v113
	v_fmac_f32_e32 v115, v4, v112
	s_waitcnt vmcnt(9)
	v_mfma_f32_16x16x32_bf16 v[110:113], v[6:9], v[14:17], 0
	v_fmac_f32_e32 v115, v5, v109
	s_nop 6
	v_max_i32_e32 v110, 0, v110
	v_max_i32_e32 v111, 0, v111
	v_mul_f32_e32 v116, v2, v110
	v_max_i32_e32 v112, 0, v112
	v_fmac_f32_e32 v116, v3, v111
	v_max_i32_e32 v109, 0, v113
	v_fmac_f32_e32 v116, v4, v112
	s_waitcnt vmcnt(8)
	v_mfma_f32_16x16x32_bf16 v[110:113], v[6:9], v[10:13], 0
	v_fmac_f32_e32 v116, v5, v109
	s_nop 1
	v_permlane32_swap_b32_e32 v114, v116
	s_nop 3
	v_max_i32_e32 v110, 0, v110
	v_max_i32_e32 v111, 0, v111
	v_mul_f32_e32 v110, v2, v110
	v_max_i32_e32 v112, 0, v112
	v_fmac_f32_e32 v110, v3, v111
	v_max_i32_e32 v109, 0, v113
	v_fmac_f32_e32 v110, v4, v112
	v_fmac_f32_e32 v110, v5, v109
	v_add_f32_e32 v109, v114, v116
	s_nop 0
	v_permlane32_swap_b32_e32 v115, v110
	v_add_f32_e32 v110, v115, v110
	s_nop 1
	v_permlane16_swap_b32_e32 v109, v110
	s_nop 0
	v_add_co_u32_e32 v10, vcc, 0x2000, v58
	s_nop 1
	v_addc_co_u32_e32 v11, vcc, 0, v59, vcc
	global_load_dwordx4 v[22:25], v[10:11], off
	global_load_dwordx4 v[18:21], v[10:11], off offset:1024
	global_load_dwordx4 v[14:17], v[10:11], off offset:2048
	s_nop 0
	global_load_dwordx4 v[10:13], v[10:11], off offset:3072
.LBB0_1078:
	s_waitcnt vmcnt(11)
	v_mfma_f32_16x16x32_bf16 v[112:115], v[6:9], v[42:45], 0
	v_lshl_add_u64 v[58:59], v[58:59], 0, s[28:29]
	s_cmp_lt_i32 s16, 52
	s_nop 5
	v_max_i32_e32 v112, 0, v112
	v_max_i32_e32 v113, 0, v113
	v_mul_f32_e32 v116, v2, v112
	v_max_i32_e32 v114, 0, v114
	v_fmac_f32_e32 v116, v3, v113
	v_max_i32_e32 v111, 0, v115
	v_fmac_f32_e32 v116, v4, v114
	s_waitcnt vmcnt(10)
	v_mfma_f32_16x16x32_bf16 v[112:115], v[6:9], v[46:49], 0
	v_fmac_f32_e32 v116, v5, v111
	s_nop 6
	v_max_i32_e32 v112, 0, v112
	v_max_i32_e32 v113, 0, v113
	v_mul_f32_e32 v117, v2, v112
	v_max_i32_e32 v114, 0, v114
	v_fmac_f32_e32 v117, v3, v113
	v_max_i32_e32 v111, 0, v115
	v_fmac_f32_e32 v117, v4, v114
	s_waitcnt vmcnt(9)
	v_mfma_f32_16x16x32_bf16 v[112:115], v[6:9], v[50:53], 0
	v_fmac_f32_e32 v117, v5, v111
	s_nop 6
	v_max_i32_e32 v112, 0, v112
	v_max_i32_e32 v113, 0, v113
	v_mul_f32_e32 v118, v2, v112
	v_max_i32_e32 v114, 0, v114
	v_fmac_f32_e32 v118, v3, v113
	v_max_i32_e32 v111, 0, v115
	v_fmac_f32_e32 v118, v4, v114
	s_waitcnt vmcnt(8)
	v_mfma_f32_16x16x32_bf16 v[112:115], v[6:9], v[54:57], 0
	v_fmac_f32_e32 v118, v5, v111
	s_nop 1
	v_permlane32_swap_b32_e32 v116, v118
	s_nop 3
	v_max_i32_e32 v112, 0, v112
	v_max_i32_e32 v111, 0, v115
	v_max_i32_e32 v113, 0, v113
	v_mul_f32_e32 v115, v2, v112
	v_max_i32_e32 v114, 0, v114
	v_fmac_f32_e32 v115, v3, v113
	v_fmac_f32_e32 v115, v4, v114
	v_fmac_f32_e32 v115, v5, v111
	v_add_f32_e32 v112, v116, v118
	s_nop 0
	v_permlane32_swap_b32_e32 v117, v115
	v_add_f32_e32 v113, v117, v115
	s_nop 1
	v_permlane16_swap_b32_e32 v112, v113
	s_nop 0
	v_add_co_u32_e32 v54, vcc, 0x2000, v58
	s_nop 1
	v_addc_co_u32_e32 v55, vcc, 0, v59, vcc
	global_load_dwordx4 v[42:45], v[54:55], off
	global_load_dwordx4 v[46:49], v[54:55], off offset:1024
	global_load_dwordx4 v[50:53], v[54:55], off offset:2048
	s_nop 0
	global_load_dwordx4 v[54:57], v[54:55], off offset:3072
; __device__ __forceinline__ SwapPair swap32p(float x, float y) { unsigned a = __builtin_bit_cast(unsigned, x), b = __builtin_bit_cast(unsigned, y); asm volatile("" : "+v"(a), "+v"(b)); auto r = __builtin_amdgcn_permlane32_swap(a, b, false, false); return SwapPair{r[0], r[1]}; }
; __device__ __forceinline__ SwapPair swap16p(float x, float y) { unsigned a = __builtin_bit_cast(unsigned, x), b = __builtin_bit_cast(unsigned, y); asm volatile("" : "+v"(a), "+v"(b)); auto r = __builtin_amdgcn_permlane16_swap(a, b, false, false); return SwapPair{r[0], r[1]}; }
; #define MFMA16(a, b, c) __builtin_amdgcn_mfma_f32_16x16x32_bf16((a), (b), (c), 0, 0, 0)
; __device__ __forceinline__ void dsa_token(Frame& F, int b, int t, const bf16* QI, const bf16* KI, const float* WI, const bf16* CKVN, const bf16* QLAT, bf16* OLAT) {
;     ...
;         for (int g4 = 0; g4 < 16; ++g4) {
;             if (4 * g4 <= cmax) {
; #pragma unroll
;                 for (int c = 4 * g4; c < 4 * g4 + 4; ++c) {
;                     asm volatile("" : "+v"(kp));
;                     if (c + 2 < 64) { if (c + 2 <= cmax4) DSA_KLOAD(c + 2, 2); }
;                     float v[4];
; #pragma unroll
;                     for (int tau = 0; tau < 4; ++tau) {
;                         const f32x4 d = MFMA16(qa, kbuf[c % 3][tau], ((f32x4){0.f, 0.f, 0.f, 0.f}));
;                         typedef int i32x4_ __attribute__((ext_vector_type(4)));
;                         const f32x4 rl = __builtin_bit_cast(f32x4, __builtin_elementwise_max(__builtin_bit_cast(i32x4_, d), ((i32x4_){0, 0, 0, 0})));
;                         v[tau] = fmaf(w4.w, rl[3], fmaf(w4.z, rl[2], fmaf(w4.y, rl[1], w4.x * rl[0])));
;                     }
;                     const SwapPair r0 = swap32p(v[0], v[2]), r1 = swap32p(v[1], v[3]);
;                     const float a0 = __builtin_bit_cast(float, r0.a) + __builtin_bit_cast(float, r0.b), a1 = __builtin_bit_cast(float, r1.a) + __builtin_bit_cast(float, r1.b);
;                     const SwapPair r2 = swap16p(a0, a1);
;                     const float keep = __builtin_bit_cast(float, r2.a) + __builtin_bit_cast(float, r2.b);
;                     const bool cand = 64 * c + lane <= t;
;                     sc[c] = cand ? keep : -INFINITY; vmax = fmaxf(vmax, sc[c]); vmin = fminf(vmin, cand ? keep : INFINITY);
;                     kp += 64 * 32;
;                 }
;             }
;         }
.LBB0_1080:
	s_waitcnt vmcnt(11)
	v_mfma_f32_16x16x32_bf16 v[114:117], v[6:9], v[26:29], 0
	v_lshl_add_u64 v[58:59], v[58:59], 0, s[28:29]
	s_cmp_lt_i32 s16, 53
	s_nop 5
	v_max_i32_e32 v114, 0, v114
	v_max_i32_e32 v115, 0, v115
	v_mul_f32_e32 v118, v2, v114
	v_max_i32_e32 v116, 0, v116
	v_fmac_f32_e32 v118, v3, v115
	v_max_i32_e32 v111, 0, v117
	v_fmac_f32_e32 v118, v4, v116
	s_waitcnt vmcnt(10)
	v_mfma_f32_16x16x32_bf16 v[114:117], v[6:9], v[30:33], 0
	v_fmac_f32_e32 v118, v5, v111
	s_nop 6
	v_max_i32_e32 v114, 0, v114
	v_max_i32_e32 v115, 0, v115
	v_mul_f32_e32 v119, v2, v114
	v_max_i32_e32 v116, 0, v116
	v_fmac_f32_e32 v119, v3, v115
	v_max_i32_e32 v111, 0, v117
	v_fmac_f32_e32 v119, v4, v116
	s_waitcnt vmcnt(9)
	v_mfma_f32_16x16x32_bf16 v[114:117], v[6:9], v[34:37], 0
	v_fmac_f32_e32 v119, v5, v111
	s_nop 6
	v_max_i32_e32 v114, 0, v114
	v_max_i32_e32 v115, 0, v115
	v_mul_f32_e32 v120, v2, v114
	v_max_i32_e32 v116, 0, v116
	v_fmac_f32_e32 v120, v3, v115
	v_max_i32_e32 v111, 0, v117
	v_fmac_f32_e32 v120, v4, v116
	s_waitcnt vmcnt(8)
	v_mfma_f32_16x16x32_bf16 v[114:117], v[6:9], v[38:41], 0
	v_fmac_f32_e32 v120, v5, v111
	s_nop 1
	v_permlane32_swap_b32_e32 v118, v120
	s_nop 3
	v_max_i32_e32 v114, 0, v114
	v_max_i32_e32 v111, 0, v117
	v_max_i32_e32 v115, 0, v115
	v_mul_f32_e32 v117, v2, v114
	v_max_i32_e32 v116, 0, v116
	v_fmac_f32_e32 v117, v3, v115
	v_fmac_f32_e32 v117, v4, v116
	v_fmac_f32_e32 v117, v5, v111
	v_add_f32_e32 v114, v118, v120
	s_nop 0
	v_permlane32_swap_b32_e32 v119, v117
	v_add_f32_e32 v115, v119, v117
	s_nop 1
	v_permlane16_swap_b32_e32 v114, v115
	s_nop 0
	v_add_co_u32_e32 v38, vcc, 0x2000, v58
	s_nop 1
	v_addc_co_u32_e32 v39, vcc, 0, v59, vcc
	global_load_dwordx4 v[26:29], v[38:39], off
	global_load_dwordx4 v[30:33], v[38:39], off offset:1024
	global_load_dwordx4 v[34:37], v[38:39], off offset:2048
	s_nop 0
	global_load_dwordx4 v[38:41], v[38:39], off offset:3072
.LBB0_1082:
	v_add_f32_e32 v109, v109, v110
	v_cmp_lt_i32_e32 vcc, s2, v169
	v_add_f32_e32 v112, v112, v113
	v_lshl_add_u64 v[58:59], v[58:59], 0, s[28:29]
	v_cndmask_b32_e32 v111, v109, v206, vcc
	v_cndmask_b32_e32 v109, v109, v207, vcc
	v_cmp_lt_i32_e32 vcc, s2, v170
	s_nop 1
	v_cndmask_b32_e32 v110, v112, v206, vcc
	v_cndmask_b32_e32 v112, v112, v207, vcc
	v_min3_f32 v108, v108, v109, v112
	v_add_f32_e32 v112, v114, v115
	v_cmp_lt_i32_e32 vcc, s2, v171
	v_max3_f32 v107, v107, v111, v110
	s_nop 0
	v_cndmask_b32_e32 v109, v112, v206, vcc
	v_cndmask_b32_e32 v116, v112, v207, vcc
	s_waitcnt vmcnt(11)
	v_mfma_f32_16x16x32_bf16 v[112:115], v[6:9], v[22:25], 0
	v_cmp_lt_i32_e32 vcc, s2, v211
	s_nop 6
	v_max_i32_e32 v112, 0, v112
	v_max_i32_e32 v113, 0, v113
	v_mul_f32_e32 v117, v2, v112
	v_max_i32_e32 v114, 0, v114
	v_fmac_f32_e32 v117, v3, v113
	v_max_i32_e32 v115, 0, v115
	v_fmac_f32_e32 v117, v4, v114
	v_fmac_f32_e32 v117, v5, v115
	s_waitcnt vmcnt(10)
	v_mfma_f32_16x16x32_bf16 v[112:115], v[6:9], v[18:21], 0
	s_nop 7
	v_max_i32_e32 v112, 0, v112
	v_max_i32_e32 v113, 0, v113
	v_mul_f32_e32 v118, v2, v112
	v_max_i32_e32 v114, 0, v114
	v_fmac_f32_e32 v118, v3, v113
	v_max_i32_e32 v115, 0, v115
	v_fmac_f32_e32 v118, v4, v114
	v_fmac_f32_e32 v118, v5, v115
	s_waitcnt vmcnt(9)
	v_mfma_f32_16x16x32_bf16 v[112:115], v[6:9], v[14:17], 0
	s_nop 7
	v_max_i32_e32 v112, 0, v112
	v_max_i32_e32 v113, 0, v113
	v_mul_f32_e32 v119, v2, v112
	v_max_i32_e32 v114, 0, v114
	v_fmac_f32_e32 v119, v3, v113
	v_max_i32_e32 v115, 0, v115
	v_fmac_f32_e32 v119, v4, v114
	v_fmac_f32_e32 v119, v5, v115
	s_waitcnt vmcnt(8)
	v_mfma_f32_16x16x32_bf16 v[112:115], v[6:9], v[10:13], 0
	s_nop 0
	v_permlane32_swap_b32_e32 v117, v119
	s_nop 5
	v_max_i32_e32 v112, 0, v112
	v_max_i32_e32 v113, 0, v113
	v_mul_f32_e32 v112, v2, v112
	v_max_i32_e32 v114, 0, v114
	v_fmac_f32_e32 v112, v3, v113
	v_max_i32_e32 v115, 0, v115
	v_fmac_f32_e32 v112, v4, v114
	v_fmac_f32_e32 v112, v5, v115
	v_add_f32_e32 v113, v117, v119
	s_nop 0
	v_permlane32_swap_b32_e32 v118, v112
	v_add_f32_e32 v112, v118, v112
	s_nop 1
	v_permlane16_swap_b32_e32 v113, v112
	v_add_f32_e32 v113, v113, v112
	v_cndmask_b32_e32 v112, v113, v206, vcc
	v_cndmask_b32_e32 v113, v113, v207, vcc
	v_max3_f32 v107, v107, v109, v112
	v_min3_f32 v108, v108, v116, v113
	s_branch .LBB0_1084

; __device__ __forceinline__ SwapPair swap32p(float x, float y) { unsigned a = __builtin_bit_cast(unsigned, x), b = __builtin_bit_cast(unsigned, y); asm volatile("" : "+v"(a), "+v"(b)); auto r = __builtin_amdgcn_permlane32_swap(a, b, false, false); return SwapPair{r[0], r[1]}; }
; __device__ __forceinline__ SwapPair swap16p(float x, float y) { unsigned a = __builtin_bit_cast(unsigned, x), b = __builtin_bit_cast(unsigned, y); asm volatile("" : "+v"(a), "+v"(b)); auto r = __builtin_amdgcn_permlane16_swap(a, b, false, false); return SwapPair{r[0], r[1]}; }
; #define MFMA16(a, b, c) __builtin_amdgcn_mfma_f32_16x16x32_bf16((a), (b), (c), 0, 0, 0)
; __device__ __forceinline__ void dsa_token(Frame& F, int b, int t, const bf16* QI, const bf16* KI, const float* WI, const bf16* CKVN, const bf16* QLAT, bf16* OLAT) {
;     ...
;         for (int g4 = 0; g4 < 16; ++g4) {
;             if (4 * g4 <= cmax) {
; #pragma unroll
;                 for (int c = 4 * g4; c < 4 * g4 + 4; ++c) {
;                     asm volatile("" : "+v"(kp));
;                     if (c + 2 < 64) { if (c + 2 <= cmax4) DSA_KLOAD(c + 2, 2); }
;                     float v[4];
; #pragma unroll
;                     for (int tau = 0; tau < 4; ++tau) {
;                         const f32x4 d = MFMA16(qa, kbuf[c % 3][tau], ((f32x4){0.f, 0.f, 0.f, 0.f}));
;                         typedef int i32x4_ __attribute__((ext_vector_type(4)));
;                         const f32x4 rl = __builtin_bit_cast(f32x4, __builtin_elementwise_max(__builtin_bit_cast(i32x4_, d), ((i32x4_){0, 0, 0, 0})));
;                         v[tau] = fmaf(w4.w, rl[3], fmaf(w4.z, rl[2], fmaf(w4.y, rl[1], w4.x * rl[0])));
;                     }
;                     const SwapPair r0 = swap32p(v[0], v[2]), r1 = swap32p(v[1], v[3]);
;                     const float a0 = __builtin_bit_cast(float, r0.a) + __builtin_bit_cast(float, r0.b), a1 = __builtin_bit_cast(float, r1.a) + __builtin_bit_cast(float, r1.b);
;                     const SwapPair r2 = swap16p(a0, a1);
;                     const float keep = __builtin_bit_cast(float, r2.a) + __builtin_bit_cast(float, r2.b);
;                     const bool cand = 64 * c + lane <= t;
;                     sc[c] = cand ? keep : -INFINITY; vmax = fmaxf(vmax, sc[c]); vmin = fminf(vmin, cand ? keep : INFINITY);
;                     kp += 64 * 32;
;                 }
;             }
;         }
.LBB0_1084:
	s_cmp_gt_i32 s18, 51
	s_cselect_b64 s[66:67], -1, 0
	s_cmp_lt_i32 s18, 52
	v_mov_b32_e32 v116, 0xff800000
	s_cbranch_scc1 .LBB0_1094
	s_cmp_lt_i32 s16, 54
	s_nop 0
	s_nop 0
	v_add_co_u32_e32 v10, vcc, 0x2000, v58
	s_nop 1
	v_addc_co_u32_e32 v11, vcc, 0, v59, vcc
	global_load_dwordx4 v[22:25], v[10:11], off
	global_load_dwordx4 v[18:21], v[10:11], off offset:1024
	global_load_dwordx4 v[14:17], v[10:11], off offset:2048
	s_nop 0
	global_load_dwordx4 v[10:13], v[10:11], off offset:3072
.LBB0_1087:
	s_waitcnt vmcnt(11)
	v_mfma_f32_16x16x32_bf16 v[114:117], v[6:9], v[42:45], 0
	v_lshl_add_u64 v[58:59], v[58:59], 0, s[28:29]
	s_cmp_lt_i32 s16, 55
	s_nop 5
	v_max_i32_e32 v114, 0, v114
	v_max_i32_e32 v115, 0, v115
	v_mul_f32_e32 v118, v2, v114
	v_max_i32_e32 v116, 0, v116
	v_fmac_f32_e32 v118, v3, v115
	v_max_i32_e32 v113, 0, v117
	v_fmac_f32_e32 v118, v4, v116
	s_waitcnt vmcnt(10)
	v_mfma_f32_16x16x32_bf16 v[114:117], v[6:9], v[46:49], 0
	v_fmac_f32_e32 v118, v5, v113
	s_nop 6
	v_max_i32_e32 v114, 0, v114
	v_max_i32_e32 v115, 0, v115
	v_mul_f32_e32 v119, v2, v114
	v_max_i32_e32 v116, 0, v116
	v_fmac_f32_e32 v119, v3, v115
	v_max_i32_e32 v113, 0, v117
	v_fmac_f32_e32 v119, v4, v116
	s_waitcnt vmcnt(9)
	v_mfma_f32_16x16x32_bf16 v[114:117], v[6:9], v[50:53], 0
	v_fmac_f32_e32 v119, v5, v113
	s_nop 6
	v_max_i32_e32 v114, 0, v114
	v_max_i32_e32 v115, 0, v115
	v_mul_f32_e32 v120, v2, v114
	v_max_i32_e32 v116, 0, v116
	v_fmac_f32_e32 v120, v3, v115
	v_max_i32_e32 v113, 0, v117
	v_fmac_f32_e32 v120, v4, v116
	s_waitcnt vmcnt(8)
	v_mfma_f32_16x16x32_bf16 v[114:117], v[6:9], v[54:57], 0
	v_fmac_f32_e32 v120, v5, v113
	s_nop 1
	v_permlane32_swap_b32_e32 v118, v120
	s_nop 3
	v_max_i32_e32 v114, 0, v114
	v_max_i32_e32 v115, 0, v115
	v_mul_f32_e32 v114, v2, v114
	v_max_i32_e32 v116, 0, v116
	v_fmac_f32_e32 v114, v3, v115
	v_max_i32_e32 v113, 0, v117
	v_fmac_f32_e32 v114, v4, v116
	v_fmac_f32_e32 v114, v5, v113
	v_add_f32_e32 v113, v118, v120
	s_nop 0
	v_permlane32_swap_b32_e32 v119, v114
	v_add_f32_e32 v114, v119, v114
	s_nop 1
	v_permlane16_swap_b32_e32 v113, v114
	s_nop 0
	v_add_co_u32_e32 v54, vcc, 0x2000, v58
	s_nop 1
	v_addc_co_u32_e32 v55, vcc, 0, v59, vcc
	global_load_dwordx4 v[42:45], v[54:55], off
	global_load_dwordx4 v[46:49], v[54:55], off offset:1024
	global_load_dwordx4 v[50:53], v[54:55], off offset:2048
	s_nop 0
	global_load_dwordx4 v[54:57], v[54:55], off offset:3072
.LBB0_1089:
	s_waitcnt vmcnt(11)
	v_mfma_f32_16x16x32_bf16 v[116:119], v[6:9], v[26:29], 0
	v_lshl_add_u64 v[58:59], v[58:59], 0, s[28:29]
	s_cmp_lt_i32 s16, 56
	s_nop 5
	v_max_i32_e32 v116, 0, v116
	v_max_i32_e32 v117, 0, v117
	v_mul_f32_e32 v120, v2, v116
	v_max_i32_e32 v118, 0, v118
	v_fmac_f32_e32 v120, v3, v117
	v_max_i32_e32 v115, 0, v119
	v_fmac_f32_e32 v120, v4, v118
	s_waitcnt vmcnt(10)
	v_mfma_f32_16x16x32_bf16 v[116:119], v[6:9], v[30:33], 0
	v_fmac_f32_e32 v120, v5, v115
	s_nop 6
	v_max_i32_e32 v116, 0, v116
	v_max_i32_e32 v117, 0, v117
	v_mul_f32_e32 v121, v2, v116
	v_max_i32_e32 v118, 0, v118
	v_fmac_f32_e32 v121, v3, v117
	v_max_i32_e32 v115, 0, v119
	v_fmac_f32_e32 v121, v4, v118
	s_waitcnt vmcnt(9)
	v_mfma_f32_16x16x32_bf16 v[116:119], v[6:9], v[34:37], 0
	v_fmac_f32_e32 v121, v5, v115
	s_nop 6
	v_max_i32_e32 v116, 0, v116
	v_max_i32_e32 v117, 0, v117
	v_mul_f32_e32 v122, v2, v116
	v_max_i32_e32 v118, 0, v118
	v_fmac_f32_e32 v122, v3, v117
	v_max_i32_e32 v115, 0, v119
	v_fmac_f32_e32 v122, v4, v118
	s_waitcnt vmcnt(8)
	v_mfma_f32_16x16x32_bf16 v[116:119], v[6:9], v[38:41], 0
	v_fmac_f32_e32 v122, v5, v115
	s_nop 1
	v_permlane32_swap_b32_e32 v120, v122
	s_nop 3
	v_max_i32_e32 v116, 0, v116
	v_max_i32_e32 v115, 0, v119
	v_max_i32_e32 v117, 0, v117
	v_mul_f32_e32 v119, v2, v116
	v_max_i32_e32 v118, 0, v118
	v_fmac_f32_e32 v119, v3, v117
	v_fmac_f32_e32 v119, v4, v118
	v_fmac_f32_e32 v119, v5, v115
	v_add_f32_e32 v116, v120, v122
	s_nop 0
	v_permlane32_swap_b32_e32 v121, v119
	v_add_f32_e32 v117, v121, v119
	s_nop 1
	v_permlane16_swap_b32_e32 v116, v117
	s_nop 0
	v_add_co_u32_e32 v38, vcc, 0x2000, v58
	s_nop 1
	v_addc_co_u32_e32 v39, vcc, 0, v59, vcc
	global_load_dwordx4 v[26:29], v[38:39], off
	global_load_dwordx4 v[30:33], v[38:39], off offset:1024
	global_load_dwordx4 v[34:37], v[38:39], off offset:2048
	s_nop 0
	global_load_dwordx4 v[38:41], v[38:39], off offset:3072
; __device__ __forceinline__ SwapPair swap32p(float x, float y) { unsigned a = __builtin_bit_cast(unsigned, x), b = __builtin_bit_cast(unsigned, y); asm volatile("" : "+v"(a), "+v"(b)); auto r = __builtin_amdgcn_permlane32_swap(a, b, false, false); return SwapPair{r[0], r[1]}; }
; __device__ __forceinline__ SwapPair swap16p(float x, float y) { unsigned a = __builtin_bit_cast(unsigned, x), b = __builtin_bit_cast(unsigned, y); asm volatile("" : "+v"(a), "+v"(b)); auto r = __builtin_amdgcn_permlane16_swap(a, b, false, false); return SwapPair{r[0], r[1]}; }
; #define MFMA16(a, b, c) __builtin_amdgcn_mfma_f32_16x16x32_bf16((a), (b), (c), 0, 0, 0)
; __device__ __forceinline__ void dsa_token(Frame& F, int b, int t, const bf16* QI, const bf16* KI, const float* WI, const bf16* CKVN, const bf16* QLAT, bf16* OLAT) {
;     ...
;         for (int g4 = 0; g4 < 16; ++g4) {
;             if (4 * g4 <= cmax) {
; #pragma unroll
;                 for (int c = 4 * g4; c < 4 * g4 + 4; ++c) {
;                     asm volatile("" : "+v"(kp));
;                     if (c + 2 < 64) { if (c + 2 <= cmax4) DSA_KLOAD(c + 2, 2); }
;                     float v[4];
; #pragma unroll
;                     for (int tau = 0; tau < 4; ++tau) {
;                         const f32x4 d = MFMA16(qa, kbuf[c % 3][tau], ((f32x4){0.f, 0.f, 0.f, 0.f}));
;                         typedef int i32x4_ __attribute__((ext_vector_type(4)));
;                         const f32x4 rl = __builtin_bit_cast(f32x4, __builtin_elementwise_max(__builtin_bit_cast(i32x4_, d), ((i32x4_){0, 0, 0, 0})));
;                         v[tau] = fmaf(w4.w, rl[3], fmaf(w4.z, rl[2], fmaf(w4.y, rl[1], w4.x * rl[0])));
;                     }
;                     const SwapPair r0 = swap32p(v[0], v[2]), r1 = swap32p(v[1], v[3]);
;                     const float a0 = __builtin_bit_cast(float, r0.a) + __builtin_bit_cast(float, r0.b), a1 = __builtin_bit_cast(float, r1.a) + __builtin_bit_cast(float, r1.b);
;                     const SwapPair r2 = swap16p(a0, a1);
;                     const float keep = __builtin_bit_cast(float, r2.a) + __builtin_bit_cast(float, r2.b);
;                     const bool cand = 64 * c + lane <= t;
;                     sc[c] = cand ? keep : -INFINITY; vmax = fmaxf(vmax, sc[c]); vmin = fminf(vmin, cand ? keep : INFINITY);
;                     kp += 64 * 32;
;                 }
;             }
;         }
.LBB0_1091:
	s_waitcnt vmcnt(11)
	v_mfma_f32_16x16x32_bf16 v[118:121], v[6:9], v[22:25], 0
	v_lshl_add_u64 v[58:59], v[58:59], 0, s[28:29]
	s_cmp_lt_i32 s16, 57
	s_nop 5
	v_max_i32_e32 v118, 0, v118
	v_max_i32_e32 v119, 0, v119
	v_mul_f32_e32 v122, v2, v118
	v_max_i32_e32 v120, 0, v120
	v_fmac_f32_e32 v122, v3, v119
	v_max_i32_e32 v115, 0, v121
	v_fmac_f32_e32 v122, v4, v120
	s_waitcnt vmcnt(10)
	v_mfma_f32_16x16x32_bf16 v[118:121], v[6:9], v[18:21], 0
	v_fmac_f32_e32 v122, v5, v115
	s_nop 6
	v_max_i32_e32 v118, 0, v118
	v_max_i32_e32 v119, 0, v119
	v_mul_f32_e32 v123, v2, v118
	v_max_i32_e32 v120, 0, v120
	v_fmac_f32_e32 v123, v3, v119
	v_max_i32_e32 v115, 0, v121
	v_fmac_f32_e32 v123, v4, v120
	s_waitcnt vmcnt(9)
	v_mfma_f32_16x16x32_bf16 v[118:121], v[6:9], v[14:17], 0
	v_fmac_f32_e32 v123, v5, v115
	s_nop 6
	v_max_i32_e32 v118, 0, v118
	v_max_i32_e32 v119, 0, v119
	v_mul_f32_e32 v124, v2, v118
	v_max_i32_e32 v120, 0, v120
	v_fmac_f32_e32 v124, v3, v119
	v_max_i32_e32 v115, 0, v121
	v_fmac_f32_e32 v124, v4, v120
	s_waitcnt vmcnt(8)
	v_mfma_f32_16x16x32_bf16 v[118:121], v[6:9], v[10:13], 0
	v_fmac_f32_e32 v124, v5, v115
	s_nop 1
	v_permlane32_swap_b32_e32 v122, v124
	s_nop 3
	v_max_i32_e32 v118, 0, v118
	v_max_i32_e32 v115, 0, v121
	v_max_i32_e32 v119, 0, v119
	v_mul_f32_e32 v121, v2, v118
	v_max_i32_e32 v120, 0, v120
	v_fmac_f32_e32 v121, v3, v119
	v_fmac_f32_e32 v121, v4, v120
	v_fmac_f32_e32 v121, v5, v115
	v_add_f32_e32 v118, v122, v124
	s_nop 0
	v_permlane32_swap_b32_e32 v123, v121
	v_add_f32_e32 v119, v123, v121
	s_nop 1
	v_permlane16_swap_b32_e32 v118, v119
	s_nop 0
	v_add_co_u32_e32 v10, vcc, 0x2000, v58
	s_nop 1
	v_addc_co_u32_e32 v11, vcc, 0, v59, vcc
	global_load_dwordx4 v[22:25], v[10:11], off
	global_load_dwordx4 v[18:21], v[10:11], off offset:1024
	global_load_dwordx4 v[14:17], v[10:11], off offset:2048
	s_nop 0
	global_load_dwordx4 v[10:13], v[10:11], off offset:3072
.LBB0_1093:
	v_add_f32_e32 v113, v113, v114
	v_cmp_lt_i32_e32 vcc, s2, v212
	v_add_f32_e32 v116, v116, v117
	v_lshl_add_u64 v[58:59], v[58:59], 0, s[28:29]
	v_cndmask_b32_e32 v115, v113, v206, vcc
	v_cndmask_b32_e32 v113, v113, v207, vcc
	v_cmp_lt_i32_e32 vcc, s2, v213
	s_nop 1
	v_cndmask_b32_e32 v114, v116, v206, vcc
	v_cndmask_b32_e32 v116, v116, v207, vcc
	v_min3_f32 v108, v108, v113, v116
	v_add_f32_e32 v116, v118, v119
	v_cmp_lt_i32_e32 vcc, s2, v214
	v_max3_f32 v107, v107, v115, v114
	s_nop 0
	v_cndmask_b32_e32 v113, v116, v206, vcc
	v_cndmask_b32_e32 v120, v116, v207, vcc
	s_waitcnt vmcnt(11)
	v_mfma_f32_16x16x32_bf16 v[116:119], v[6:9], v[42:45], 0
	v_cmp_lt_i32_e32 vcc, s2, v215
	s_nop 6
	v_max_i32_e32 v116, 0, v116
	v_max_i32_e32 v117, 0, v117
	v_mul_f32_e32 v121, v2, v116
	v_max_i32_e32 v118, 0, v118
	v_fmac_f32_e32 v121, v3, v117
	v_max_i32_e32 v119, 0, v119
	v_fmac_f32_e32 v121, v4, v118
	v_fmac_f32_e32 v121, v5, v119
	s_waitcnt vmcnt(10)
	v_mfma_f32_16x16x32_bf16 v[116:119], v[6:9], v[46:49], 0
	s_nop 7
	v_max_i32_e32 v116, 0, v116
	v_max_i32_e32 v117, 0, v117
	v_mul_f32_e32 v122, v2, v116
	v_max_i32_e32 v118, 0, v118
	v_fmac_f32_e32 v122, v3, v117
	v_max_i32_e32 v119, 0, v119
	v_fmac_f32_e32 v122, v4, v118
	v_fmac_f32_e32 v122, v5, v119
	s_waitcnt vmcnt(9)
	v_mfma_f32_16x16x32_bf16 v[116:119], v[6:9], v[50:53], 0
	s_nop 7
	v_max_i32_e32 v116, 0, v116
	v_max_i32_e32 v117, 0, v117
	v_mul_f32_e32 v123, v2, v116
	v_max_i32_e32 v118, 0, v118
	v_fmac_f32_e32 v123, v3, v117
	v_max_i32_e32 v119, 0, v119
	v_fmac_f32_e32 v123, v4, v118
	v_fmac_f32_e32 v123, v5, v119
	s_waitcnt vmcnt(8)
	v_mfma_f32_16x16x32_bf16 v[116:119], v[6:9], v[54:57], 0
	s_nop 0
	v_permlane32_swap_b32_e32 v121, v123
	s_nop 5
	v_max_i32_e32 v116, 0, v116
	v_max_i32_e32 v117, 0, v117
	v_mul_f32_e32 v116, v2, v116
	v_max_i32_e32 v118, 0, v118
	v_fmac_f32_e32 v116, v3, v117
	v_max_i32_e32 v119, 0, v119
	v_fmac_f32_e32 v116, v4, v118
	v_fmac_f32_e32 v116, v5, v119
	v_add_f32_e32 v117, v121, v123
	s_nop 0
	v_permlane32_swap_b32_e32 v122, v116
	v_add_f32_e32 v116, v122, v116
	s_nop 1
	v_permlane16_swap_b32_e32 v117, v116
	v_add_f32_e32 v117, v117, v116
	v_cndmask_b32_e32 v116, v117, v206, vcc
	v_cndmask_b32_e32 v117, v117, v207, vcc
	v_max3_f32 v107, v107, v113, v116
	v_min3_f32 v108, v108, v120, v117
	s_branch .LBB0_1095

; __device__ __forceinline__ SwapPair swap32p(float x, float y) { unsigned a = __builtin_bit_cast(unsigned, x), b = __builtin_bit_cast(unsigned, y); asm volatile("" : "+v"(a), "+v"(b)); auto r = __builtin_amdgcn_permlane32_swap(a, b, false, false); return SwapPair{r[0], r[1]}; }
; __device__ __forceinline__ SwapPair swap16p(float x, float y) { unsigned a = __builtin_bit_cast(unsigned, x), b = __builtin_bit_cast(unsigned, y); asm volatile("" : "+v"(a), "+v"(b)); auto r = __builtin_amdgcn_permlane16_swap(a, b, false, false); return SwapPair{r[0], r[1]}; }
; #define MFMA16(a, b, c) __builtin_amdgcn_mfma_f32_16x16x32_bf16((a), (b), (c), 0, 0, 0)
; __device__ __forceinline__ void dsa_token(Frame& F, int b, int t, const bf16* QI, const bf16* KI, const float* WI, const bf16* CKVN, const bf16* QLAT, bf16* OLAT) {
;     ...
;         for (int g4 = 0; g4 < 16; ++g4) {
;             if (4 * g4 <= cmax) {
; #pragma unroll
;                 for (int c = 4 * g4; c < 4 * g4 + 4; ++c) {
;                     asm volatile("" : "+v"(kp));
;                     if (c + 2 < 64) { if (c + 2 <= cmax4) DSA_KLOAD(c + 2, 2); }
;                     float v[4];
; #pragma unroll
;                     for (int tau = 0; tau < 4; ++tau) {
;                         const f32x4 d = MFMA16(qa, kbuf[c % 3][tau], ((f32x4){0.f, 0.f, 0.f, 0.f}));
;                         typedef int i32x4_ __attribute__((ext_vector_type(4)));
;                         const f32x4 rl = __builtin_bit_cast(f32x4, __builtin_elementwise_max(__builtin_bit_cast(i32x4_, d), ((i32x4_){0, 0, 0, 0})));
;                         v[tau] = fmaf(w4.w, rl[3], fmaf(w4.z, rl[2], fmaf(w4.y, rl[1], w4.x * rl[0])));
;                     }
;                     const SwapPair r0 = swap32p(v[0], v[2]), r1 = swap32p(v[1], v[3]);
;                     const float a0 = __builtin_bit_cast(float, r0.a) + __builtin_bit_cast(float, r0.b), a1 = __builtin_bit_cast(float, r1.a) + __builtin_bit_cast(float, r1.b);
;                     const SwapPair r2 = swap16p(a0, a1);
;                     const float keep = __builtin_bit_cast(float, r2.a) + __builtin_bit_cast(float, r2.b);
;                     const bool cand = 64 * c + lane <= t;
;                     sc[c] = cand ? keep : -INFINITY; vmax = fmaxf(vmax, sc[c]); vmin = fminf(vmin, cand ? keep : INFINITY);
;                     kp += 64 * 32;
;                 }
;             }
;         }
.LBB0_1095:
	s_cmp_gt_i32 s18, 55
	s_cselect_b64 s[36:37], -1, 0
	s_cmp_lt_i32 s18, 56
	v_mov_b32_e32 v120, 0xff800000
	s_cbranch_scc1 .LBB0_1105
	s_cmp_lt_i32 s16, 58
	s_nop 0
	s_nop 0
	v_add_co_u32_e32 v54, vcc, 0x2000, v58
	s_nop 1
	v_addc_co_u32_e32 v55, vcc, 0, v59, vcc
	global_load_dwordx4 v[42:45], v[54:55], off
	global_load_dwordx4 v[46:49], v[54:55], off offset:1024
	global_load_dwordx4 v[50:53], v[54:55], off offset:2048
	s_nop 0
	global_load_dwordx4 v[54:57], v[54:55], off offset:3072
.LBB0_1098:
	s_waitcnt vmcnt(11)
	v_mfma_f32_16x16x32_bf16 v[118:121], v[6:9], v[26:29], 0
	v_lshl_add_u64 v[58:59], v[58:59], 0, s[28:29]
	s_cmp_lt_i32 s16, 59
	s_nop 5
	v_max_i32_e32 v118, 0, v118
	v_max_i32_e32 v119, 0, v119
	v_mul_f32_e32 v122, v2, v118
	v_max_i32_e32 v120, 0, v120
	v_fmac_f32_e32 v122, v3, v119
	v_max_i32_e32 v117, 0, v121
	v_fmac_f32_e32 v122, v4, v120
	s_waitcnt vmcnt(10)
	v_mfma_f32_16x16x32_bf16 v[118:121], v[6:9], v[30:33], 0
	v_fmac_f32_e32 v122, v5, v117
	s_nop 6
	v_max_i32_e32 v118, 0, v118
	v_max_i32_e32 v119, 0, v119
	v_mul_f32_e32 v123, v2, v118
	v_max_i32_e32 v120, 0, v120
	v_fmac_f32_e32 v123, v3, v119
	v_max_i32_e32 v117, 0, v121
	v_fmac_f32_e32 v123, v4, v120
	s_waitcnt vmcnt(9)
	v_mfma_f32_16x16x32_bf16 v[118:121], v[6:9], v[34:37], 0
	v_fmac_f32_e32 v123, v5, v117
	s_nop 6
	v_max_i32_e32 v118, 0, v118
	v_max_i32_e32 v119, 0, v119
	v_mul_f32_e32 v124, v2, v118
	v_max_i32_e32 v120, 0, v120
	v_fmac_f32_e32 v124, v3, v119
	v_max_i32_e32 v117, 0, v121
	v_fmac_f32_e32 v124, v4, v120
	s_waitcnt vmcnt(8)
	v_mfma_f32_16x16x32_bf16 v[118:121], v[6:9], v[38:41], 0
	v_fmac_f32_e32 v124, v5, v117
	s_nop 1
	v_permlane32_swap_b32_e32 v122, v124
	s_nop 3
	v_max_i32_e32 v118, 0, v118
	v_max_i32_e32 v119, 0, v119
	v_mul_f32_e32 v118, v2, v118
	v_max_i32_e32 v120, 0, v120
	v_fmac_f32_e32 v118, v3, v119
	v_max_i32_e32 v117, 0, v121
	v_fmac_f32_e32 v118, v4, v120
	v_fmac_f32_e32 v118, v5, v117
	v_add_f32_e32 v117, v122, v124
	s_nop 0
	v_permlane32_swap_b32_e32 v123, v118
	v_add_f32_e32 v118, v123, v118
	s_nop 1
	v_permlane16_swap_b32_e32 v117, v118
	s_nop 0
	v_add_co_u32_e32 v38, vcc, 0x2000, v58
	s_nop 1
	v_addc_co_u32_e32 v39, vcc, 0, v59, vcc
	global_load_dwordx4 v[26:29], v[38:39], off
	global_load_dwordx4 v[30:33], v[38:39], off offset:1024
	global_load_dwordx4 v[34:37], v[38:39], off offset:2048
	s_nop 0
	global_load_dwordx4 v[38:41], v[38:39], off offset:3072
.LBB0_1100:
	s_waitcnt vmcnt(11)
	v_mfma_f32_16x16x32_bf16 v[120:123], v[6:9], v[22:25], 0
	v_lshl_add_u64 v[58:59], v[58:59], 0, s[28:29]
	s_cmp_lt_i32 s16, 60
	s_nop 5
	v_max_i32_e32 v120, 0, v120
	v_max_i32_e32 v121, 0, v121
	v_mul_f32_e32 v124, v2, v120
	v_max_i32_e32 v122, 0, v122
	v_fmac_f32_e32 v124, v3, v121
	v_max_i32_e32 v119, 0, v123
	v_fmac_f32_e32 v124, v4, v122
	s_waitcnt vmcnt(10)
	v_mfma_f32_16x16x32_bf16 v[120:123], v[6:9], v[18:21], 0
	v_fmac_f32_e32 v124, v5, v119
	s_nop 6
	v_max_i32_e32 v120, 0, v120
	v_max_i32_e32 v121, 0, v121
	v_mul_f32_e32 v125, v2, v120
	v_max_i32_e32 v122, 0, v122
	v_fmac_f32_e32 v125, v3, v121
	v_max_i32_e32 v119, 0, v123
	v_fmac_f32_e32 v125, v4, v122
	s_waitcnt vmcnt(9)
	v_mfma_f32_16x16x32_bf16 v[120:123], v[6:9], v[14:17], 0
	v_fmac_f32_e32 v125, v5, v119
	s_nop 6
	v_max_i32_e32 v120, 0, v120
	v_max_i32_e32 v121, 0, v121
	v_mul_f32_e32 v126, v2, v120
	v_max_i32_e32 v122, 0, v122
	v_fmac_f32_e32 v126, v3, v121
	v_max_i32_e32 v119, 0, v123
	v_fmac_f32_e32 v126, v4, v122
	s_waitcnt vmcnt(8)
	v_mfma_f32_16x16x32_bf16 v[120:123], v[6:9], v[10:13], 0
	v_fmac_f32_e32 v126, v5, v119
	s_nop 1
	v_permlane32_swap_b32_e32 v124, v126
	s_nop 3
	v_max_i32_e32 v120, 0, v120
	v_max_i32_e32 v119, 0, v123
	v_max_i32_e32 v121, 0, v121
	v_mul_f32_e32 v123, v2, v120
	v_max_i32_e32 v122, 0, v122
	v_fmac_f32_e32 v123, v3, v121
	v_fmac_f32_e32 v123, v4, v122
	v_fmac_f32_e32 v123, v5, v119
	v_add_f32_e32 v120, v124, v126
	s_nop 0
	v_permlane32_swap_b32_e32 v125, v123
	v_add_f32_e32 v121, v125, v123
	s_nop 1
	v_permlane16_swap_b32_e32 v120, v121
	s_nop 0
	v_add_co_u32_e32 v10, vcc, 0x2000, v58
	s_nop 1
	v_addc_co_u32_e32 v11, vcc, 0, v59, vcc
	global_load_dwordx4 v[22:25], v[10:11], off
	global_load_dwordx4 v[18:21], v[10:11], off offset:1024
	global_load_dwordx4 v[14:17], v[10:11], off offset:2048
	s_nop 0
	global_load_dwordx4 v[10:13], v[10:11], off offset:3072
; __device__ __forceinline__ SwapPair swap32p(float x, float y) { unsigned a = __builtin_bit_cast(unsigned, x), b = __builtin_bit_cast(unsigned, y); asm volatile("" : "+v"(a), "+v"(b)); auto r = __builtin_amdgcn_permlane32_swap(a, b, false, false); return SwapPair{r[0], r[1]}; }
; __device__ __forceinline__ SwapPair swap16p(float x, float y) { unsigned a = __builtin_bit_cast(unsigned, x), b = __builtin_bit_cast(unsigned, y); asm volatile("" : "+v"(a), "+v"(b)); auto r = __builtin_amdgcn_permlane16_swap(a, b, false, false); return SwapPair{r[0], r[1]}; }
; #define MFMA16(a, b, c) __builtin_amdgcn_mfma_f32_16x16x32_bf16((a), (b), (c), 0, 0, 0)
; __device__ __forceinline__ void dsa_token(Frame& F, int b, int t, const bf16* QI, const bf16* KI, const float* WI, const bf16* CKVN, const bf16* QLAT, bf16* OLAT) {
;     ...
;         for (int g4 = 0; g4 < 16; ++g4) {
;             if (4 * g4 <= cmax) {
; #pragma unroll
;                 for (int c = 4 * g4; c < 4 * g4 + 4; ++c) {
;                     asm volatile("" : "+v"(kp));
;                     if (c + 2 < 64) { if (c + 2 <= cmax4) DSA_KLOAD(c + 2, 2); }
;                     float v[4];
; #pragma unroll
;                     for (int tau = 0; tau < 4; ++tau) {
;                         const f32x4 d = MFMA16(qa, kbuf[c % 3][tau], ((f32x4){0.f, 0.f, 0.f, 0.f}));
;                         typedef int i32x4_ __attribute__((ext_vector_type(4)));
;                         const f32x4 rl = __builtin_bit_cast(f32x4, __builtin_elementwise_max(__builtin_bit_cast(i32x4_, d), ((i32x4_){0, 0, 0, 0})));
;                         v[tau] = fmaf(w4.w, rl[3], fmaf(w4.z, rl[2], fmaf(w4.y, rl[1], w4.x * rl[0])));
;                     }
;                     const SwapPair r0 = swap32p(v[0], v[2]), r1 = swap32p(v[1], v[3]);
;                     const float a0 = __builtin_bit_cast(float, r0.a) + __builtin_bit_cast(float, r0.b), a1 = __builtin_bit_cast(float, r1.a) + __builtin_bit_cast(float, r1.b);
;                     const SwapPair r2 = swap16p(a0, a1);
;                     const float keep = __builtin_bit_cast(float, r2.a) + __builtin_bit_cast(float, r2.b);
;                     const bool cand = 64 * c + lane <= t;
;                     sc[c] = cand ? keep : -INFINITY; vmax = fmaxf(vmax, sc[c]); vmin = fminf(vmin, cand ? keep : INFINITY);
;                     kp += 64 * 32;
;                 }
;             }
;         }
.LBB0_1102:
	s_waitcnt vmcnt(11)
	v_mfma_f32_16x16x32_bf16 v[122:125], v[6:9], v[42:45], 0
	v_lshl_add_u64 v[58:59], v[58:59], 0, s[28:29]
	s_cmp_lt_i32 s16, 61
	s_nop 5
	v_max_i32_e32 v122, 0, v122
	v_max_i32_e32 v123, 0, v123
	v_mul_f32_e32 v126, v2, v122
	v_max_i32_e32 v124, 0, v124
	v_fmac_f32_e32 v126, v3, v123
	v_max_i32_e32 v119, 0, v125
	v_fmac_f32_e32 v126, v4, v124
	s_waitcnt vmcnt(10)
	v_mfma_f32_16x16x32_bf16 v[122:125], v[6:9], v[46:49], 0
	v_fmac_f32_e32 v126, v5, v119
	s_nop 6
	v_max_i32_e32 v122, 0, v122
	v_max_i32_e32 v123, 0, v123
	v_mul_f32_e32 v127, v2, v122
	v_max_i32_e32 v124, 0, v124
	v_fmac_f32_e32 v127, v3, v123
	v_max_i32_e32 v119, 0, v125
	v_fmac_f32_e32 v127, v4, v124
	s_waitcnt vmcnt(9)
	v_mfma_f32_16x16x32_bf16 v[122:125], v[6:9], v[50:53], 0
	v_fmac_f32_e32 v127, v5, v119
	s_nop 6
	v_max_i32_e32 v122, 0, v122
	v_max_i32_e32 v123, 0, v123
	v_mul_f32_e32 v128, v2, v122
	v_max_i32_e32 v124, 0, v124
	v_fmac_f32_e32 v128, v3, v123
	v_max_i32_e32 v119, 0, v125
	v_fmac_f32_e32 v128, v4, v124
	s_waitcnt vmcnt(8)
	v_mfma_f32_16x16x32_bf16 v[122:125], v[6:9], v[54:57], 0
	v_fmac_f32_e32 v128, v5, v119
	s_nop 1
	v_permlane32_swap_b32_e32 v126, v128
	s_nop 3
	v_max_i32_e32 v122, 0, v122
	v_max_i32_e32 v119, 0, v125
	v_max_i32_e32 v123, 0, v123
	v_mul_f32_e32 v125, v2, v122
	v_max_i32_e32 v124, 0, v124
	v_fmac_f32_e32 v125, v3, v123
	v_fmac_f32_e32 v125, v4, v124
	v_fmac_f32_e32 v125, v5, v119
	v_add_f32_e32 v122, v126, v128
	s_nop 0
	v_permlane32_swap_b32_e32 v127, v125
	v_add_f32_e32 v123, v127, v125
	s_nop 1
	v_permlane16_swap_b32_e32 v122, v123
	s_nop 0
	v_add_co_u32_e32 v54, vcc, 0x2000, v58
	s_nop 1
	v_addc_co_u32_e32 v55, vcc, 0, v59, vcc
	global_load_dwordx4 v[42:45], v[54:55], off
	global_load_dwordx4 v[46:49], v[54:55], off offset:1024
	global_load_dwordx4 v[50:53], v[54:55], off offset:2048
	s_nop 0
	global_load_dwordx4 v[54:57], v[54:55], off offset:3072
.LBB0_1104:
	v_add_f32_e32 v117, v117, v118
	v_cmp_lt_i32_e32 vcc, s2, v216
	v_add_f32_e32 v120, v120, v121
	v_lshl_add_u64 v[58:59], v[58:59], 0, s[28:29]
	v_cndmask_b32_e32 v119, v117, v206, vcc
	v_cndmask_b32_e32 v117, v117, v207, vcc
	v_cmp_lt_i32_e32 vcc, s2, v217
	s_nop 1
	v_cndmask_b32_e32 v118, v120, v206, vcc
	v_cndmask_b32_e32 v120, v120, v207, vcc
	v_min3_f32 v108, v108, v117, v120
	v_add_f32_e32 v120, v122, v123
	v_cmp_lt_i32_e32 vcc, s2, v218
	v_max3_f32 v107, v107, v119, v118
	s_nop 0
	v_cndmask_b32_e32 v117, v120, v206, vcc
	v_cndmask_b32_e32 v124, v120, v207, vcc
	s_waitcnt vmcnt(11)
	v_mfma_f32_16x16x32_bf16 v[120:123], v[6:9], v[26:29], 0
	v_cmp_lt_i32_e32 vcc, s2, v219
	s_nop 6
	v_max_i32_e32 v120, 0, v120
	v_max_i32_e32 v121, 0, v121
	v_mul_f32_e32 v125, v2, v120
	v_max_i32_e32 v122, 0, v122
	v_fmac_f32_e32 v125, v3, v121
	v_max_i32_e32 v123, 0, v123
	v_fmac_f32_e32 v125, v4, v122
	v_fmac_f32_e32 v125, v5, v123
	s_waitcnt vmcnt(10)
	v_mfma_f32_16x16x32_bf16 v[120:123], v[6:9], v[30:33], 0
	s_nop 7
	v_max_i32_e32 v120, 0, v120
	v_max_i32_e32 v121, 0, v121
	v_mul_f32_e32 v126, v2, v120
	v_max_i32_e32 v122, 0, v122
	v_fmac_f32_e32 v126, v3, v121
	v_max_i32_e32 v123, 0, v123
	v_fmac_f32_e32 v126, v4, v122
	v_fmac_f32_e32 v126, v5, v123
	s_waitcnt vmcnt(9)
	v_mfma_f32_16x16x32_bf16 v[120:123], v[6:9], v[34:37], 0
	s_nop 7
	v_max_i32_e32 v120, 0, v120
	v_max_i32_e32 v121, 0, v121
	v_mul_f32_e32 v127, v2, v120
	v_max_i32_e32 v122, 0, v122
	v_fmac_f32_e32 v127, v3, v121
	v_max_i32_e32 v123, 0, v123
	v_fmac_f32_e32 v127, v4, v122
	v_fmac_f32_e32 v127, v5, v123
	s_waitcnt vmcnt(8)
	v_mfma_f32_16x16x32_bf16 v[120:123], v[6:9], v[38:41], 0
	s_nop 0
	v_permlane32_swap_b32_e32 v125, v127
	s_nop 5
	v_max_i32_e32 v120, 0, v120
	v_max_i32_e32 v121, 0, v121
	v_mul_f32_e32 v120, v2, v120
	v_max_i32_e32 v122, 0, v122
	v_fmac_f32_e32 v120, v3, v121
	v_max_i32_e32 v123, 0, v123
	v_fmac_f32_e32 v120, v4, v122
	v_fmac_f32_e32 v120, v5, v123
	v_add_f32_e32 v121, v125, v127
	s_nop 0
	v_permlane32_swap_b32_e32 v126, v120
	v_add_f32_e32 v120, v126, v120
	s_nop 1
	v_permlane16_swap_b32_e32 v121, v120
	v_add_f32_e32 v121, v121, v120
	v_cndmask_b32_e32 v120, v121, v206, vcc
	v_cndmask_b32_e32 v121, v121, v207, vcc
	v_max3_f32 v107, v107, v117, v120
	v_min3_f32 v108, v108, v124, v121
	s_branch .LBB0_1106

; __device__ __forceinline__ SwapPair swap32p(float x, float y) { unsigned a = __builtin_bit_cast(unsigned, x), b = __builtin_bit_cast(unsigned, y); asm volatile("" : "+v"(a), "+v"(b)); auto r = __builtin_amdgcn_permlane32_swap(a, b, false, false); return SwapPair{r[0], r[1]}; }
; __device__ __forceinline__ SwapPair swap16p(float x, float y) { unsigned a = __builtin_bit_cast(unsigned, x), b = __builtin_bit_cast(unsigned, y); asm volatile("" : "+v"(a), "+v"(b)); auto r = __builtin_amdgcn_permlane16_swap(a, b, false, false); return SwapPair{r[0], r[1]}; }
; #define MFMA16(a, b, c) __builtin_amdgcn_mfma_f32_16x16x32_bf16((a), (b), (c), 0, 0, 0)
; __device__ __forceinline__ void dsa_token(Frame& F, int b, int t, const bf16* QI, const bf16* KI, const float* WI, const bf16* CKVN, const bf16* QLAT, bf16* OLAT) {
;     ...
;         for (int g4 = 0; g4 < 16; ++g4) {
;             if (4 * g4 <= cmax) {
; #pragma unroll
;                 for (int c = 4 * g4; c < 4 * g4 + 4; ++c) {
;                     asm volatile("" : "+v"(kp));
;                     if (c + 2 < 64) { if (c + 2 <= cmax4) DSA_KLOAD(c + 2, 2); }
;                     float v[4];
; #pragma unroll
;                     for (int tau = 0; tau < 4; ++tau) {
;                         const f32x4 d = MFMA16(qa, kbuf[c % 3][tau], ((f32x4){0.f, 0.f, 0.f, 0.f}));
;                         typedef int i32x4_ __attribute__((ext_vector_type(4)));
;                         const f32x4 rl = __builtin_bit_cast(f32x4, __builtin_elementwise_max(__builtin_bit_cast(i32x4_, d), ((i32x4_){0, 0, 0, 0})));
;                         v[tau] = fmaf(w4.w, rl[3], fmaf(w4.z, rl[2], fmaf(w4.y, rl[1], w4.x * rl[0])));
;                     }
;                     const SwapPair r0 = swap32p(v[0], v[2]), r1 = swap32p(v[1], v[3]);
;                     const float a0 = __builtin_bit_cast(float, r0.a) + __builtin_bit_cast(float, r0.b), a1 = __builtin_bit_cast(float, r1.a) + __builtin_bit_cast(float, r1.b);
;                     const SwapPair r2 = swap16p(a0, a1);
;                     const float keep = __builtin_bit_cast(float, r2.a) + __builtin_bit_cast(float, r2.b);
;                     const bool cand = 64 * c + lane <= t;
;                     sc[c] = cand ? keep : -INFINITY; vmax = fmaxf(vmax, sc[c]); vmin = fminf(vmin, cand ? keep : INFINITY);
;                     kp += 64 * 32;
;                 }
;             }
;         }
.LBB0_1106:
	s_cmp_gt_i32 s18, 59
	s_cselect_b64 s[0:1], -1, 0
	s_cmp_lt_i32 s18, 60
	v_mov_b32_e32 v122, 0xff800000
	s_cbranch_scc1 .LBB0_1112
	s_cmp_lt_i32 s16, 62
	s_nop 0
	s_nop 0
	v_add_co_u32_e32 v38, vcc, 0x2000, v58
	s_nop 1
	v_addc_co_u32_e32 v39, vcc, 0, v59, vcc
	global_load_dwordx4 v[26:29], v[38:39], off
	global_load_dwordx4 v[30:33], v[38:39], off offset:1024
	global_load_dwordx4 v[34:37], v[38:39], off offset:2048
	s_nop 0
	global_load_dwordx4 v[38:41], v[38:39], off offset:3072
.LBB0_1109:
	s_waitcnt vmcnt(11)
	v_mfma_f32_16x16x32_bf16 v[122:125], v[6:9], v[22:25], 0
	v_lshl_add_u64 v[58:59], v[58:59], 0, s[28:29]
	s_cmp_lt_i32 s16, 63
	s_nop 5
	v_max_i32_e32 v122, 0, v122
	v_max_i32_e32 v123, 0, v123
	v_mul_f32_e32 v126, v2, v122
	v_max_i32_e32 v124, 0, v124
	v_fmac_f32_e32 v126, v3, v123
	v_max_i32_e32 v121, 0, v125
	v_fmac_f32_e32 v126, v4, v124
	s_waitcnt vmcnt(10)
	v_mfma_f32_16x16x32_bf16 v[122:125], v[6:9], v[18:21], 0
	v_fmac_f32_e32 v126, v5, v121
	s_nop 6
	v_max_i32_e32 v122, 0, v122
	v_max_i32_e32 v123, 0, v123
	v_mul_f32_e32 v127, v2, v122
	v_max_i32_e32 v124, 0, v124
	v_fmac_f32_e32 v127, v3, v123
	v_max_i32_e32 v121, 0, v125
	v_fmac_f32_e32 v127, v4, v124
	s_waitcnt vmcnt(9)
	v_mfma_f32_16x16x32_bf16 v[122:125], v[6:9], v[14:17], 0
	v_fmac_f32_e32 v127, v5, v121
	s_nop 6
	v_max_i32_e32 v122, 0, v122
	v_max_i32_e32 v123, 0, v123
	v_mul_f32_e32 v128, v2, v122
	v_max_i32_e32 v124, 0, v124
	v_fmac_f32_e32 v128, v3, v123
	v_max_i32_e32 v121, 0, v125
	v_fmac_f32_e32 v128, v4, v124
	s_waitcnt vmcnt(8)
	v_mfma_f32_16x16x32_bf16 v[122:125], v[6:9], v[10:13], 0
	v_fmac_f32_e32 v128, v5, v121
	s_nop 1
	v_permlane32_swap_b32_e32 v126, v128
	s_nop 3
	v_max_i32_e32 v122, 0, v122
	v_max_i32_e32 v123, 0, v123
	v_mul_f32_e32 v122, v2, v122
	v_max_i32_e32 v124, 0, v124
	v_fmac_f32_e32 v122, v3, v123
	v_max_i32_e32 v121, 0, v125
	v_fmac_f32_e32 v122, v4, v124
	v_fmac_f32_e32 v122, v5, v121
	v_add_f32_e32 v121, v126, v128
	s_nop 0
	v_permlane32_swap_b32_e32 v127, v122
	v_add_f32_e32 v122, v127, v122
	s_nop 1
	v_permlane16_swap_b32_e32 v121, v122
	s_nop 0
	v_add_co_u32_e32 v10, vcc, 0x2000, v58
	s_nop 1
	v_addc_co_u32_e32 v11, vcc, 0, v59, vcc
	global_load_dwordx4 v[22:25], v[10:11], off
	global_load_dwordx4 v[18:21], v[10:11], off offset:1024
	global_load_dwordx4 v[14:17], v[10:11], off offset:2048
	s_nop 0
	global_load_dwordx4 v[10:13], v[10:11], off offset:3072
; __device__ __forceinline__ SwapPair swap32p(float x, float y) { unsigned a = __builtin_bit_cast(unsigned, x), b = __builtin_bit_cast(unsigned, y); asm volatile("" : "+v"(a), "+v"(b)); auto r = __builtin_amdgcn_permlane32_swap(a, b, false, false); return SwapPair{r[0], r[1]}; }
; __device__ __forceinline__ SwapPair swap16p(float x, float y) { unsigned a = __builtin_bit_cast(unsigned, x), b = __builtin_bit_cast(unsigned, y); asm volatile("" : "+v"(a), "+v"(b)); auto r = __builtin_amdgcn_permlane16_swap(a, b, false, false); return SwapPair{r[0], r[1]}; }
; __device__ __forceinline__ void dsa_token(Frame& F, int b, int t, const bf16* QI, const bf16* KI, const float* WI, const bf16* CKVN, const bf16* QLAT, bf16* OLAT) {
;     ...
;         for (int g4 = 0; g4 < 16; ++g4) {
;             if (4 * g4 <= cmax) {
; #pragma unroll
;                 for (int c = 4 * g4; c < 4 * g4 + 4; ++c) {
;                     asm volatile("" : "+v"(kp));
;                     if (c + 2 < 64) { if (c + 2 <= cmax4) DSA_KLOAD(c + 2, 2); }
;                     float v[4];
; #pragma unroll
;                     for (int tau = 0; tau < 4; ++tau) {
;                         const f32x4 d = MFMA16(qa, kbuf[c % 3][tau], ((f32x4){0.f, 0.f, 0.f, 0.f}));
;                         typedef int i32x4_ __attribute__((ext_vector_type(4)));
;                         const f32x4 rl = __builtin_bit_cast(f32x4, __builtin_elementwise_max(__builtin_bit_cast(i32x4_, d), ((i32x4_){0, 0, 0, 0})));
;                         v[tau] = fmaf(w4.w, rl[3], fmaf(w4.z, rl[2], fmaf(w4.y, rl[1], w4.x * rl[0])));
;                     }
;                     const SwapPair r0 = swap32p(v[0], v[2]), r1 = swap32p(v[1], v[3]);
;                     const float a0 = __builtin_bit_cast(float, r0.a) + __builtin_bit_cast(float, r0.b), a1 = __builtin_bit_cast(float, r1.a) + __builtin_bit_cast(float, r1.b);
;                     const SwapPair r2 = swap16p(a0, a1);
;                     const float keep = __builtin_bit_cast(float, r2.a) + __builtin_bit_cast(float, r2.b);
;                     const bool cand = 64 * c + lane <= t;
;                     sc[c] = cand ? keep : -INFINITY; vmax = fmaxf(vmax, sc[c]); vmin = fminf(vmin, cand ? keep : INFINITY);
;                     kp += 64 * 32;
;                 }
;             }
;         }
;     ...
;         if (t < 256) {
.LBB0_1111:
	s_waitcnt vmcnt(11)
	v_mfma_f32_16x16x32_bf16 v[42:45], v[6:9], v[42:45], 0
	v_add_f32_e32 v122, v121, v122
	v_cmp_lt_i32_e32 vcc, s2, v220
	s_waitcnt vmcnt(7)
	v_mfma_f32_16x16x32_bf16 v[26:29], v[6:9], v[26:29], 0
	s_nop 0
	v_cndmask_b32_e32 v121, v122, v206, vcc
	s_nop 2
	v_max_i32_e32 v42, 0, v42
	v_max_i32_e32 v43, 0, v43
	v_mul_f32_e32 v123, v2, v42
	v_max_i32_e32 v44, 0, v44
	v_fmac_f32_e32 v123, v3, v43
	v_max_i32_e32 v45, 0, v45
	v_fmac_f32_e32 v123, v4, v44
	v_fmac_f32_e32 v123, v5, v45
	s_nop 0
	v_mfma_f32_16x16x32_bf16 v[42:45], v[6:9], v[46:49], 0
	v_max_i32_e32 v26, 0, v26
	v_max_i32_e32 v27, 0, v27
	v_max_i32_e32 v28, 0, v28
	v_max_i32_e32 v29, 0, v29
	s_waitcnt vmcnt(3)
	v_mfma_f32_16x16x32_bf16 v[22:25], v[6:9], v[22:25], 0
	s_nop 2
	v_max_i32_e32 v42, 0, v42
	v_max_i32_e32 v43, 0, v43
	v_mul_f32_e32 v46, v2, v42
	v_max_i32_e32 v44, 0, v44
	v_fmac_f32_e32 v46, v3, v43
	v_max_i32_e32 v45, 0, v45
	v_fmac_f32_e32 v46, v4, v44
	v_fmac_f32_e32 v46, v5, v45
	s_nop 0
	v_mfma_f32_16x16x32_bf16 v[42:45], v[6:9], v[50:53], 0
	v_max_i32_e32 v22, 0, v22
	v_max_i32_e32 v23, 0, v23
	v_mul_f32_e32 v22, v2, v22
	s_waitcnt vmcnt(2)
	v_mfma_f32_16x16x32_bf16 v[18:21], v[6:9], v[18:21], 0
	v_max_i32_e32 v24, 0, v24
	s_nop 2
	v_max_i32_e32 v42, 0, v42
	v_max_i32_e32 v43, 0, v43
	v_mul_f32_e32 v47, v2, v42
	v_max_i32_e32 v44, 0, v44
	v_fmac_f32_e32 v47, v3, v43
	v_max_i32_e32 v45, 0, v45
	v_fmac_f32_e32 v47, v4, v44
	v_fmac_f32_e32 v47, v5, v45
	s_nop 0
	v_mfma_f32_16x16x32_bf16 v[42:45], v[6:9], v[54:57], 0
	v_max_i32_e32 v18, 0, v18
	v_permlane32_swap_b32_e32 v123, v47
	s_waitcnt vmcnt(1)
	v_mfma_f32_16x16x32_bf16 v[14:17], v[6:9], v[14:17], 0
	s_nop 4
	v_max_i32_e32 v42, 0, v42
	v_max_i32_e32 v43, 0, v43
	v_mul_f32_e32 v42, v2, v42
	v_max_i32_e32 v44, 0, v44
	v_fmac_f32_e32 v42, v3, v43
	v_max_i32_e32 v45, 0, v45
	v_fmac_f32_e32 v42, v4, v44
	v_fmac_f32_e32 v42, v5, v45
	v_max_i32_e32 v14, 0, v14
	s_nop 0
	v_permlane32_swap_b32_e32 v46, v42
	v_add_f32_e32 v42, v46, v42
	v_mul_f32_e32 v46, v2, v26
	v_fmac_f32_e32 v46, v3, v27
	v_fmac_f32_e32 v46, v4, v28
	v_fmac_f32_e32 v46, v5, v29
	v_mfma_f32_16x16x32_bf16 v[26:29], v[6:9], v[30:33], 0
	v_add_f32_e32 v43, v123, v47
	v_lshl_add_u64 v[44:45], v[58:59], 0, s[28:29]
	v_max_i32_e32 v19, 0, v19
	v_mul_f32_e32 v18, v2, v18
	v_max_i32_e32 v15, 0, v15
	s_nop 2
	v_max_i32_e32 v26, 0, v26
	v_max_i32_e32 v27, 0, v27
	v_mul_f32_e32 v30, v2, v26
	v_max_i32_e32 v28, 0, v28
	v_fmac_f32_e32 v30, v3, v27
	v_max_i32_e32 v29, 0, v29
	v_fmac_f32_e32 v30, v4, v28
	v_fmac_f32_e32 v30, v5, v29
	v_mfma_f32_16x16x32_bf16 v[26:29], v[6:9], v[34:37], 0
	v_mul_f32_e32 v14, v2, v14
	v_fmac_f32_e32 v22, v3, v23
	v_max_i32_e32 v20, 0, v20
	s_nop 4
	v_max_i32_e32 v26, 0, v26
	v_max_i32_e32 v27, 0, v27
	v_mul_f32_e32 v31, v2, v26
	v_max_i32_e32 v28, 0, v28
	v_fmac_f32_e32 v31, v3, v27
	v_max_i32_e32 v29, 0, v29
	v_fmac_f32_e32 v31, v4, v28
	v_fmac_f32_e32 v31, v5, v29
	v_mfma_f32_16x16x32_bf16 v[26:29], v[6:9], v[38:41], 0
	v_fmac_f32_e32 v18, v3, v19
	v_max_i32_e32 v16, 0, v16
	s_waitcnt vmcnt(0)
	v_mfma_f32_16x16x32_bf16 v[6:9], v[6:9], v[10:13], 0
	v_fmac_f32_e32 v14, v3, v15
	s_nop 3
	v_max_i32_e32 v26, 0, v26
	v_max_i32_e32 v27, 0, v27
	v_mul_f32_e32 v26, v2, v26
	v_max_i32_e32 v28, 0, v28
	v_fmac_f32_e32 v26, v3, v27
	v_max_i32_e32 v29, 0, v29
	v_fmac_f32_e32 v26, v4, v28
	v_max_i32_e32 v6, 0, v6
	v_fmac_f32_e32 v26, v5, v29
	v_max_i32_e32 v7, 0, v7
	v_mul_f32_e32 v2, v2, v6
	v_max_i32_e32 v8, 0, v8
	v_fmac_f32_e32 v2, v3, v7
	v_permlane32_swap_b32_e32 v46, v31
	v_permlane32_swap_b32_e32 v30, v26
	v_max_i32_e32 v25, 0, v25
	v_fmac_f32_e32 v22, v4, v24
	v_max_i32_e32 v21, 0, v21
	v_fmac_f32_e32 v18, v4, v20
	v_max_i32_e32 v17, 0, v17
	v_fmac_f32_e32 v14, v4, v16
	v_max_i32_e32 v9, 0, v9
	v_fmac_f32_e32 v2, v4, v8
	v_permlane16_swap_b32_e32 v43, v42
	v_add_f32_e32 v27, v46, v31
	v_add_f32_e32 v29, v30, v26
	v_lshl_add_u64 v[30:31], v[44:45], 0, s[28:29]
	v_fmac_f32_e32 v22, v5, v25
	v_fmac_f32_e32 v18, v5, v21
	v_fmac_f32_e32 v14, v5, v17
	v_fmac_f32_e32 v2, v5, v9
	v_cndmask_b32_e32 v122, v122, v207, vcc
	v_add_f32_e32 v43, v43, v42
	v_cmp_lt_i32_e32 vcc, s2, v221
	s_nop 0
	v_permlane32_swap_b32_e32 v22, v14
	v_cndmask_b32_e32 v26, v43, v207, vcc
	v_permlane32_swap_b32_e32 v18, v2
	v_min3_f32 v30, v108, v122, v26
	v_add_f32_e32 v26, v22, v14
	v_add_f32_e32 v28, v18, v2
	v_permlane16_swap_b32_e32 v27, v29
	s_nop 0
	v_permlane16_swap_b32_e32 v26, v28
	v_cndmask_b32_e32 v42, v43, v206, vcc
	v_pk_add_f32 v[4:5], v[26:27], v[28:29]
	v_cmp_lt_i32_e32 vcc, s2, v195
	v_max3_f32 v31, v107, v121, v42
	s_nop 0
	v_cndmask_b32_e32 v3, v5, v207, vcc
	v_cndmask_b32_e32 v122, v5, v206, vcc
	v_cmp_lt_i32_e32 vcc, s2, v194
	s_nop 1
	v_cndmask_b32_e32 v2, v4, v206, vcc
	v_cndmask_b32_e32 v4, v4, v207, vcc
	v_max3_f32 v107, v31, v122, v2
	v_min3_f32 v108, v30, v3, v4
	s_waitcnt vmcnt(0)
	s_cmpk_lt_i32 s2, 0x100
	s_mov_b64 s[16:17], -1
	s_cbranch_scc0 .LBB0_1113
	s_branch .LBB0_1447
.LBB0_1112:
	s_waitcnt vmcnt(0)
	s_nop 0
	v_mov_b32_e32 v2, 0xff800000
	s_nop 0
	v_mov_b32_e32 v42, 0xff800000
	v_mov_b32_e32 v121, 0xff800000
	s_cmpk_lt_i32 s2, 0x100
	s_mov_b64 s[16:17], -1
	s_cbranch_scc1 .LBB0_1447
